# attention V-fragment LDS prefetch distance 4 -> 6 MFMAs
# speedup vs baseline: 1.1121x; 1.0023x over previous
.LBB0_417:
	s_ashr_i32 s40, s77, 8
	s_ashr_i32 s41, s40, 31
	s_and_b32 s49, s77, 7
	s_lshl_b32 s1, s77, 5
	s_and_b32 s34, s1, 0x1f00
	s_lshl_b32 s2, s40, 3
	s_or_b32 s2, s2, s49
	s_mul_i32 s3, s2, 0x300000
	s_mul_i32 s1, s34, 0x180
	s_add_u32 s12, s68, s3
	s_addc_u32 s13, s69, 0
	s_add_u32 s12, s12, s1
	s_addc_u32 s13, s13, 0
	s_add_u32 s42, s70, s3
	s_addc_u32 s43, s71, 0
	s_lshl_b32 s1, s40, 25
	s_lshl_b32 s3, s49, 9
	s_add_i32 s1, s1, s3
	s_add_i32 s1, s1, 0x24000100
	s_add_u32 s46, s38, s1
	s_addc_u32 s47, s39, 0
	s_lshr_b32 s15, s85, 6
	s_lshl_b32 s52, s15, 5
	s_lshl_b32 s1, s15, 8
	s_add_i32 s44, s1, 0x1e000
	s_mul_i32 s60, s15, 0xc00
	s_lshl_b32 s61, s15, 11
	v_mbcnt_lo_u32_b32 v176, -1, 0
	v_mbcnt_hi_u32_b32 v200, -1, v176
	v_and_b32_e32 v196, 31, v200
	v_lshrrev_b32_e32 v198, 5, v200
	v_or_b32_e32 v187, s52, v196
	v_mul_u32_u24_e32 v187, 0x180, v187
	v_lshl_add_u32 v187, v198, 4, v187
	global_load_dwordx4 v[96:99], v187, s[12:13] offset:0
	global_load_dwordx4 v[100:103], v187, s[12:13] offset:32
	global_load_dwordx4 v[104:107], v187, s[12:13] offset:64
	global_load_dwordx4 v[108:111], v187, s[12:13] offset:96
	global_load_dwordx4 v[112:115], v187, s[12:13] offset:128
	global_load_dwordx4 v[116:119], v187, s[12:13] offset:160
	global_load_dwordx4 v[120:123], v187, s[12:13] offset:192
	global_load_dwordx4 v[124:127], v187, s[12:13] offset:224
	global_load_dwordx4 v[128:131], v187, s[12:13] offset:256
	global_load_dwordx4 v[132:135], v187, s[12:13] offset:288
	global_load_dwordx4 v[136:139], v187, s[12:13] offset:320
	global_load_dwordx4 v[140:143], v187, s[12:13] offset:352
	s_mul_i32 s1, s15, 3
	s_add_i32 s1, s1, 0
	s_lshl_b32 s1, s1, 6
	v_add_u32_e32 v247, s1, v200
	v_mul_u32_u24_e32 v248, 0xaab, v247
	v_lshrrev_b32_e32 v248, 16, v248
	v_mul_u32_u24_e32 v249, 24, v248
	v_sub_u32_e32 v247, v247, v249
	v_bfe_u32 v249, v248, 1, 3
	v_xor_b32_e32 v247, v247, v249
	v_mul_u32_u24_e32 v248, 0x180, v248
	v_lshl_add_u32 v182, v247, 4, v248
	s_mul_i32 s1, s15, 3
	s_add_i32 s1, s1, 1
	s_lshl_b32 s1, s1, 6
	v_add_u32_e32 v247, s1, v200
	v_mul_u32_u24_e32 v248, 0xaab, v247
	v_lshrrev_b32_e32 v248, 16, v248
	v_mul_u32_u24_e32 v249, 24, v248
	v_sub_u32_e32 v247, v247, v249
	v_bfe_u32 v249, v248, 1, 3
	v_xor_b32_e32 v247, v247, v249
	v_mul_u32_u24_e32 v248, 0x180, v248
	v_lshl_add_u32 v183, v247, 4, v248
	s_mul_i32 s1, s15, 3
	s_add_i32 s1, s1, 2
	s_lshl_b32 s1, s1, 6
	v_add_u32_e32 v247, s1, v200
	v_mul_u32_u24_e32 v248, 0xaab, v247
	v_lshrrev_b32_e32 v248, 16, v248
	v_mul_u32_u24_e32 v249, 24, v248
	v_sub_u32_e32 v247, v247, v249
	v_bfe_u32 v249, v248, 1, 3
	v_xor_b32_e32 v247, v247, v249
	v_mul_u32_u24_e32 v248, 0x180, v248
	v_lshl_add_u32 v184, v247, 4, v248
	s_lshl_b32 s1, s15, 1
	s_add_i32 s1, s1, 0
	s_lshl_b32 s1, s1, 6
	v_add_u32_e32 v247, s1, v200
	v_lshrrev_b32_e32 v248, 7, v247
	v_lshlrev_b32_e32 v248, 3, v248
	v_bfe_u32 v249, v247, 2, 3
	v_or_b32_e32 v248, v248, v249
	v_bfe_u32 v249, v247, 5, 2
	v_and_b32_e32 v247, 3, v247
	v_lshlrev_b32_e32 v247, 4, v247
	v_lshl_add_u32 v247, v249, 6, v247
	v_lshl_add_u32 v185, v248, 12, v247
	s_lshl_b32 s1, s15, 1
	s_add_i32 s1, s1, 1
	s_lshl_b32 s1, s1, 6
	v_add_u32_e32 v247, s1, v200
	v_lshrrev_b32_e32 v248, 7, v247
	v_lshlrev_b32_e32 v248, 3, v248
	v_bfe_u32 v249, v247, 2, 3
	v_or_b32_e32 v248, v248, v249
	v_bfe_u32 v249, v247, 5, 2
	v_and_b32_e32 v247, 3, v247
	v_lshlrev_b32_e32 v247, 4, v247
	v_lshl_add_u32 v247, v249, 6, v247
	v_lshl_add_u32 v186, v248, 12, v247
	v_bfe_u32 v247, v196, 1, 3
	v_mul_u32_u24_e32 v248, 0x180, v196
	v_add_u32_e32 v248, 0xc000, v248
	v_or_b32_e32 v249, 0, v198
	v_xor_b32_e32 v249, v249, v247
	v_lshl_add_u32 v240, v249, 4, v248
	v_or_b32_e32 v249, 2, v198
	v_xor_b32_e32 v249, v249, v247
	v_lshl_add_u32 v241, v249, 4, v248
	v_or_b32_e32 v249, 4, v198
	v_xor_b32_e32 v249, v249, v247
	v_lshl_add_u32 v242, v249, 4, v248
	v_or_b32_e32 v249, 6, v198
	v_xor_b32_e32 v249, v249, v247
	v_lshl_add_u32 v243, v249, 4, v248
	v_and_b32_e32 v247, 3, v200
	v_lshlrev_b32_e32 v244, 3, v247
	v_bfe_u32 v247, v200, 2, 2
	v_lshl_or_b32 v244, v247, 6, v244
	v_bfe_u32 v247, v200, 4, 1
	v_lshl_or_b32 v244, v247, 5, v244
	v_lshl_or_b32 v244, v198, 8, v244
	v_mov_b32_e32 v0, 0
	v_mov_b32_e32 v1, 0
	v_mov_b32_e32 v2, 0
	v_mov_b32_e32 v3, 0
	v_mov_b32_e32 v4, 0
	v_mov_b32_e32 v5, 0
	v_mov_b32_e32 v6, 0
	v_mov_b32_e32 v7, 0
	v_mov_b32_e32 v8, 0
	v_mov_b32_e32 v9, 0
	v_mov_b32_e32 v10, 0
	v_mov_b32_e32 v11, 0
	v_mov_b32_e32 v12, 0
	v_mov_b32_e32 v13, 0
	v_mov_b32_e32 v14, 0
	v_mov_b32_e32 v15, 0
	v_mov_b32_e32 v16, 0
	v_mov_b32_e32 v17, 0
	v_mov_b32_e32 v18, 0
	v_mov_b32_e32 v19, 0
	v_mov_b32_e32 v20, 0
	v_mov_b32_e32 v21, 0
	v_mov_b32_e32 v22, 0
	v_mov_b32_e32 v23, 0
	v_mov_b32_e32 v24, 0
	v_mov_b32_e32 v25, 0
	v_mov_b32_e32 v26, 0
	v_mov_b32_e32 v27, 0
	v_mov_b32_e32 v28, 0
	v_mov_b32_e32 v29, 0
	v_mov_b32_e32 v30, 0
	v_mov_b32_e32 v31, 0
	v_mov_b32_e32 v32, 0
	v_mov_b32_e32 v33, 0
	v_mov_b32_e32 v34, 0
	v_mov_b32_e32 v35, 0
	v_mov_b32_e32 v36, 0
	v_mov_b32_e32 v37, 0
	v_mov_b32_e32 v38, 0
	v_mov_b32_e32 v39, 0
	v_mov_b32_e32 v40, 0
	v_mov_b32_e32 v41, 0
	v_mov_b32_e32 v42, 0
	v_mov_b32_e32 v43, 0
	v_mov_b32_e32 v44, 0
	v_mov_b32_e32 v45, 0
	v_mov_b32_e32 v46, 0
	v_mov_b32_e32 v47, 0
	v_mov_b32_e32 v48, 0
	v_mov_b32_e32 v49, 0
	v_mov_b32_e32 v50, 0
	v_mov_b32_e32 v51, 0
	v_mov_b32_e32 v52, 0
	v_mov_b32_e32 v53, 0
	v_mov_b32_e32 v54, 0
	v_mov_b32_e32 v55, 0
	v_mov_b32_e32 v56, 0
	v_mov_b32_e32 v57, 0
	v_mov_b32_e32 v58, 0
	v_mov_b32_e32 v59, 0
	v_mov_b32_e32 v60, 0
	v_mov_b32_e32 v61, 0
	v_mov_b32_e32 v62, 0
	v_mov_b32_e32 v63, 0
	v_mov_b32_e32 v245, 0
	v_mov_b32_e32 v246, 0
	s_add_i32 m0, s60, 0xc000
	s_nop 0
	global_load_lds_dwordx4 v182, s[42:43]
	s_add_i32 m0, s60, 0xc400
	s_nop 0
	global_load_lds_dwordx4 v183, s[42:43]
	s_add_i32 m0, s60, 0xc800
	s_nop 0
	global_load_lds_dwordx4 v184, s[42:43]
	s_add_u32 s42, s42, 0x6000
	s_addc_u32 s43, s43, 0
	s_add_i32 m0, s60, 0x12000
	s_nop 0
	global_load_lds_dwordx4 v182, s[42:43]
	s_add_i32 m0, s60, 0x12400
	s_nop 0
	global_load_lds_dwordx4 v183, s[42:43]
	s_add_i32 m0, s60, 0x12800
	s_nop 0
	global_load_lds_dwordx4 v184, s[42:43]
	s_add_u32 s42, s42, 0x6000
	s_addc_u32 s43, s43, 0
	s_add_i32 m0, s60, 0x18000
	s_nop 0
	global_load_lds_dwordx4 v182, s[42:43]
	s_add_i32 m0, s60, 0x18400
	s_nop 0
	global_load_lds_dwordx4 v183, s[42:43]
	s_add_i32 m0, s60, 0x18800
	s_nop 0
	global_load_lds_dwordx4 v184, s[42:43]
	s_add_u32 s42, s42, 0x6000
	s_addc_u32 s43, s43, 0
	s_add_i32 m0, s61, 0x0
	s_nop 0
	global_load_lds_dwordx4 v185, s[46:47]
	s_add_i32 m0, s61, 0x400
	s_nop 0
	global_load_lds_dwordx4 v186, s[46:47]
	s_add_u32 s46, s46, 0x40000
	s_addc_u32 s47, s47, 0
	s_waitcnt vmcnt(5)
	s_barrier
	ds_read_b128 v[144:147], v240 offset:0
	ds_read_b128 v[148:151], v240 offset:12288
	ds_read_b128 v[152:155], v241 offset:0
	ds_read_b128 v[156:159], v241 offset:12288
	ds_read_b128 v[160:163], v242 offset:0
	ds_read_b128 v[164:167], v242 offset:12288
	ds_read_b128 v[168:171], v243 offset:0
	s_waitcnt lgkmcnt(6)
	v_mfma_f32_32x32x16_bf16 v[208:223], v[144:147], v[96:99], 0
	s_add_i32 m0, s60, 0x21010
	s_nop 0
	global_load_lds_dwordx4 v182, s[42:43]
	ds_read_b128 v[172:175], v243 offset:12288
	s_waitcnt lgkmcnt(6)
	v_mfma_f32_32x32x16_bf16 v[224:239], v[148:151], v[96:99], 0
	s_add_i32 m0, s60, 0x21410
	s_nop 0
	global_load_lds_dwordx4 v183, s[42:43]
	ds_read_b128 v[144:147], v240 offset:128
	s_waitcnt lgkmcnt(6)
	v_mfma_f32_32x32x16_bf16 v[208:223], v[152:155], v[100:103], v[208:223]
	s_add_i32 m0, s60, 0x21810
	s_nop 0
	global_load_lds_dwordx4 v184, s[42:43]
	ds_read_b128 v[148:151], v240 offset:12416
	s_waitcnt lgkmcnt(6)
	v_mfma_f32_32x32x16_bf16 v[224:239], v[156:159], v[100:103], v[224:239]
	s_add_i32 m0, s61, 0x4000
	s_nop 0
	global_load_lds_dwordx4 v185, s[46:47]
	ds_read_b128 v[152:155], v241 offset:128
	s_waitcnt lgkmcnt(6)
	v_mfma_f32_32x32x16_bf16 v[208:223], v[160:163], v[104:107], v[208:223]
	s_add_i32 m0, s61, 0x4400
	s_nop 0
	global_load_lds_dwordx4 v186, s[46:47]
	ds_read_b128 v[156:159], v241 offset:12416
	s_waitcnt lgkmcnt(6)
	v_mfma_f32_32x32x16_bf16 v[224:239], v[164:167], v[104:107], v[224:239]
	s_add_u32 s42, s42, 0x6000
	s_addc_u32 s43, s43, 0
	ds_read_b128 v[160:163], v242 offset:128
	s_waitcnt lgkmcnt(6)
	v_mfma_f32_32x32x16_bf16 v[208:223], v[168:171], v[108:111], v[208:223]
	s_add_u32 s46, s46, 0x40000
	s_addc_u32 s47, s47, 0
	ds_read_b128 v[164:167], v242 offset:12416
	s_waitcnt lgkmcnt(6)
	v_mfma_f32_32x32x16_bf16 v[224:239], v[172:175], v[108:111], v[224:239]
	ds_read_b128 v[168:171], v243 offset:128
	s_waitcnt lgkmcnt(6)
	v_mfma_f32_32x32x16_bf16 v[208:223], v[144:147], v[112:115], v[208:223]
	ds_read_b128 v[172:175], v243 offset:12416
	s_waitcnt lgkmcnt(6)
	v_mfma_f32_32x32x16_bf16 v[224:239], v[148:151], v[112:115], v[224:239]
	ds_read_b128 v[144:147], v240 offset:256
	s_waitcnt lgkmcnt(6)
	v_mfma_f32_32x32x16_bf16 v[208:223], v[152:155], v[116:119], v[208:223]
	ds_read_b128 v[148:151], v240 offset:12544
	s_waitcnt lgkmcnt(6)
	v_mfma_f32_32x32x16_bf16 v[224:239], v[156:159], v[116:119], v[224:239]
	ds_read_b128 v[152:155], v241 offset:256
	s_waitcnt lgkmcnt(6)
	v_mfma_f32_32x32x16_bf16 v[208:223], v[160:163], v[120:123], v[208:223]
	ds_read_b128 v[156:159], v241 offset:12544
	s_waitcnt lgkmcnt(6)
	v_mfma_f32_32x32x16_bf16 v[224:239], v[164:167], v[120:123], v[224:239]
	ds_read_b128 v[160:163], v242 offset:256
	s_waitcnt lgkmcnt(6)
	v_mfma_f32_32x32x16_bf16 v[208:223], v[168:171], v[124:127], v[208:223]
	ds_read_b128 v[164:167], v242 offset:12544
	s_waitcnt lgkmcnt(6)
	v_mfma_f32_32x32x16_bf16 v[224:239], v[172:175], v[124:127], v[224:239]
	ds_read_b128 v[168:171], v243 offset:256
	s_waitcnt lgkmcnt(6)
	v_mfma_f32_32x32x16_bf16 v[208:223], v[144:147], v[128:131], v[208:223]
	ds_read_b128 v[172:175], v243 offset:12544
	s_waitcnt lgkmcnt(6)
	v_mfma_f32_32x32x16_bf16 v[224:239], v[148:151], v[128:131], v[224:239]
	v_add_u32_e32 v240, 0x6000, v240
	s_waitcnt lgkmcnt(5)
	v_mfma_f32_32x32x16_bf16 v[208:223], v[152:155], v[132:135], v[208:223]
	v_add_u32_e32 v241, 0x6000, v241
	s_waitcnt lgkmcnt(4)
	v_mfma_f32_32x32x16_bf16 v[224:239], v[156:159], v[132:135], v[224:239]
	v_add_u32_e32 v242, 0x6000, v242
	s_waitcnt lgkmcnt(3)
	v_mfma_f32_32x32x16_bf16 v[208:223], v[160:163], v[136:139], v[208:223]
	v_add_u32_e32 v243, 0x6000, v243
	s_waitcnt lgkmcnt(2)
	v_mfma_f32_32x32x16_bf16 v[224:239], v[164:167], v[136:139], v[224:239]
	s_waitcnt lgkmcnt(1)
	v_mfma_f32_32x32x16_bf16 v[208:223], v[168:171], v[140:143], v[208:223]
	s_waitcnt lgkmcnt(0)
	v_mfma_f32_32x32x16_bf16 v[224:239], v[172:175], v[140:143], v[224:239]
	s_nop 7
	s_nop 7
	v_exp_f32_e32 v208, v208
	v_exp_f32_e32 v209, v209
	v_exp_f32_e32 v210, v210
	v_exp_f32_e32 v211, v211
	v_exp_f32_e32 v212, v212
	v_exp_f32_e32 v213, v213
	v_exp_f32_e32 v214, v214
	v_exp_f32_e32 v215, v215
	v_exp_f32_e32 v216, v216
	v_exp_f32_e32 v217, v217
	v_exp_f32_e32 v218, v218
	v_exp_f32_e32 v219, v219
	v_exp_f32_e32 v220, v220
	v_exp_f32_e32 v221, v221
	v_exp_f32_e32 v222, v222
	v_exp_f32_e32 v223, v223
	s_mov_b32 s78, 10
	s_waitcnt vmcnt(5)
	s_barrier
	ds_read_b128 v[144:147], v240 offset:0
	ds_read_b128 v[148:151], v240 offset:12288
	ds_read_b128 v[152:155], v241 offset:0
	ds_read_b128 v[156:159], v241 offset:12288
	ds_read_b128 v[160:163], v242 offset:0
	ds_read_b128 v[164:167], v242 offset:12288
	v_exp_f32_e32 v224, v224
	v_add_f32_e32 v245, v208, v245
	v_exp_f32_e32 v225, v225
	v_add_f32_e32 v246, v209, v246
	v_exp_f32_e32 v226, v226
	v_add_f32_e32 v245, v210, v245
	v_exp_f32_e32 v227, v227
	v_add_f32_e32 v246, v211, v246
	ds_read_b128 v[168:171], v243 offset:0
	s_waitcnt lgkmcnt(6)
	v_mfma_f32_32x32x16_bf16 v[64:79], v[144:147], v[96:99], 0
	v_exp_f32_e32 v228, v228
	v_add_f32_e32 v245, v212, v245
	v_exp_f32_e32 v229, v229
	ds_read_b128 v[172:175], v243 offset:12288
	s_waitcnt lgkmcnt(6)
	v_mfma_f32_32x32x16_bf16 v[80:95], v[148:151], v[96:99], 0
	v_add_f32_e32 v246, v213, v246
	v_exp_f32_e32 v230, v230
	v_add_f32_e32 v245, v214, v245
	ds_read_b128 v[144:147], v240 offset:128
	s_waitcnt lgkmcnt(6)
	v_mfma_f32_32x32x16_bf16 v[64:79], v[152:155], v[100:103], v[64:79]
	v_exp_f32_e32 v231, v231
	s_add_i32 m0, s60, 0xc000
	s_nop 0
	global_load_lds_dwordx4 v182, s[42:43]
	v_add_f32_e32 v246, v215, v246
	ds_read_b128 v[148:151], v240 offset:12416
	s_waitcnt lgkmcnt(6)
	v_mfma_f32_32x32x16_bf16 v[80:95], v[156:159], v[100:103], v[80:95]
	v_exp_f32_e32 v232, v232
	v_add_f32_e32 v245, v216, v245
	v_exp_f32_e32 v233, v233
	ds_read_b128 v[152:155], v241 offset:128
	s_waitcnt lgkmcnt(6)
	v_mfma_f32_32x32x16_bf16 v[64:79], v[160:163], v[104:107], v[64:79]
	v_add_f32_e32 v246, v217, v246
	v_exp_f32_e32 v234, v234
	v_add_f32_e32 v245, v218, v245
	ds_read_b128 v[156:159], v241 offset:12416
	s_waitcnt lgkmcnt(6)
	v_mfma_f32_32x32x16_bf16 v[80:95], v[164:167], v[104:107], v[80:95]
	s_add_i32 m0, s60, 0xc400
	s_nop 0
	global_load_lds_dwordx4 v183, s[42:43]
	v_exp_f32_e32 v235, v235
	v_add_f32_e32 v246, v219, v246
	ds_read_b128 v[160:163], v242 offset:128
	s_waitcnt lgkmcnt(6)
	v_mfma_f32_32x32x16_bf16 v[64:79], v[168:171], v[108:111], v[64:79]
	v_exp_f32_e32 v236, v236
	v_add_f32_e32 v245, v220, v245
	v_exp_f32_e32 v237, v237
	ds_read_b128 v[164:167], v242 offset:12416
	s_waitcnt lgkmcnt(6)
	v_mfma_f32_32x32x16_bf16 v[80:95], v[172:175], v[108:111], v[80:95]
	v_add_f32_e32 v246, v221, v246
	v_exp_f32_e32 v238, v238
	s_add_i32 m0, s60, 0xc800
	s_nop 0
	global_load_lds_dwordx4 v184, s[42:43]
	ds_read_b128 v[168:171], v243 offset:128
	s_waitcnt lgkmcnt(6)
	v_mfma_f32_32x32x16_bf16 v[64:79], v[144:147], v[112:115], v[64:79]
	v_add_f32_e32 v245, v222, v245
	v_exp_f32_e32 v239, v239
	v_add_f32_e32 v246, v223, v246
	ds_read_b128 v[172:175], v243 offset:12416
	s_waitcnt lgkmcnt(6)
	v_mfma_f32_32x32x16_bf16 v[80:95], v[148:151], v[112:115], v[80:95]
	v_add_f32_e32 v245, v224, v245
	v_add_f32_e32 v246, v225, v246
	v_add_f32_e32 v245, v226, v245
	ds_read_b128 v[144:147], v240 offset:256
	s_waitcnt lgkmcnt(6)
	v_mfma_f32_32x32x16_bf16 v[64:79], v[152:155], v[116:119], v[64:79]
	v_add_f32_e32 v246, v227, v246
	s_add_i32 m0, s61, 0x8000
	s_nop 0
	global_load_lds_dwordx4 v185, s[46:47]
	v_add_f32_e32 v245, v228, v245
	ds_read_b128 v[148:151], v240 offset:12544
	s_waitcnt lgkmcnt(6)
	v_mfma_f32_32x32x16_bf16 v[80:95], v[156:159], v[116:119], v[80:95]
	v_add_f32_e32 v246, v229, v246
	v_add_f32_e32 v245, v230, v245
	v_add_f32_e32 v246, v231, v246
	ds_read_b128 v[152:155], v241 offset:256
	s_waitcnt lgkmcnt(6)
	v_mfma_f32_32x32x16_bf16 v[64:79], v[160:163], v[120:123], v[64:79]
	v_add_f32_e32 v245, v232, v245
	v_add_f32_e32 v246, v233, v246
	v_add_f32_e32 v245, v234, v245
	ds_read_b128 v[156:159], v241 offset:12544
	s_waitcnt lgkmcnt(6)
	v_mfma_f32_32x32x16_bf16 v[80:95], v[164:167], v[120:123], v[80:95]
	s_add_i32 m0, s61, 0x8400
	s_nop 0
	global_load_lds_dwordx4 v186, s[46:47]
	v_add_f32_e32 v246, v235, v246
	v_add_f32_e32 v245, v236, v245
	ds_read_b128 v[160:163], v242 offset:256
	s_waitcnt lgkmcnt(6)
	v_mfma_f32_32x32x16_bf16 v[64:79], v[168:171], v[124:127], v[64:79]
	v_add_f32_e32 v246, v237, v246
	v_add_f32_e32 v245, v238, v245
	v_add_f32_e32 v246, v239, v246
	ds_read_b128 v[164:167], v242 offset:12544
	s_waitcnt lgkmcnt(6)
	v_mfma_f32_32x32x16_bf16 v[80:95], v[172:175], v[124:127], v[80:95]
	v_cvt_pk_bf16_f32 v208, v208, v209
	v_cvt_pk_bf16_f32 v209, v210, v211
	ds_read_b128 v[168:171], v243 offset:256
	s_waitcnt lgkmcnt(6)
	v_mfma_f32_32x32x16_bf16 v[64:79], v[144:147], v[128:131], v[64:79]
	s_add_u32 s42, s42, 0x6000
	s_addc_u32 s43, s43, 0
	v_cvt_pk_bf16_f32 v210, v212, v213
	ds_read_b128 v[172:175], v243 offset:12544
	s_waitcnt lgkmcnt(6)
	v_mfma_f32_32x32x16_bf16 v[80:95], v[148:151], v[128:131], v[80:95]
	v_cvt_pk_bf16_f32 v211, v214, v215
	v_cvt_pk_bf16_f32 v212, v216, v217
	v_add_u32_e32 v240, 0x6000, v240
	ds_read_b64_tr_b16 v[144:145], v244 offset:0
	ds_read_b64_tr_b16 v[146:147], v244 offset:2048
	s_waitcnt lgkmcnt(7)
	v_mfma_f32_32x32x16_bf16 v[64:79], v[152:155], v[132:135], v[64:79]
	v_cvt_pk_bf16_f32 v213, v218, v219
	v_cvt_pk_bf16_f32 v214, v220, v221
	v_add_u32_e32 v241, 0x6000, v241
	ds_read_b64_tr_b16 v[148:149], v244 offset:4096
	ds_read_b64_tr_b16 v[150:151], v244 offset:6144
	s_waitcnt lgkmcnt(8)
	v_mfma_f32_32x32x16_bf16 v[80:95], v[156:159], v[132:135], v[80:95]
	v_cvt_pk_bf16_f32 v215, v222, v223
	v_cvt_pk_bf16_f32 v224, v224, v225
	v_add_u32_e32 v242, 0x6000, v242
	ds_read_b64_tr_b16 v[152:153], v244 offset:8192
	ds_read_b64_tr_b16 v[154:155], v244 offset:10240
	s_waitcnt lgkmcnt(9)
	v_mfma_f32_32x32x16_bf16 v[64:79], v[160:163], v[136:139], v[64:79]
	s_add_u32 s46, s46, 0x40000
	s_addc_u32 s47, s47, 0
	v_cvt_pk_bf16_f32 v225, v226, v227
	v_add_u32_e32 v243, 0x6000, v243
	ds_read_b64_tr_b16 v[156:157], v244 offset:12288
	ds_read_b64_tr_b16 v[158:159], v244 offset:14336
	s_waitcnt lgkmcnt(10)
	v_mfma_f32_32x32x16_bf16 v[80:95], v[164:167], v[136:139], v[80:95]
	v_cvt_pk_bf16_f32 v226, v228, v229
	v_cvt_pk_bf16_f32 v227, v230, v231
	ds_read_b64_tr_b16 v[160:161], v244 offset:512
	ds_read_b64_tr_b16 v[162:163], v244 offset:2560
	s_waitcnt lgkmcnt(11)
	v_mfma_f32_32x32x16_bf16 v[64:79], v[168:171], v[140:143], v[64:79]
	v_cvt_pk_bf16_f32 v228, v232, v233
	v_cvt_pk_bf16_f32 v229, v234, v235
	ds_read_b64_tr_b16 v[164:165], v244 offset:4608
	ds_read_b64_tr_b16 v[166:167], v244 offset:6656
	s_waitcnt lgkmcnt(12)
	v_mfma_f32_32x32x16_bf16 v[80:95], v[172:175], v[140:143], v[80:95]
	v_cvt_pk_bf16_f32 v230, v236, v237
	v_cvt_pk_bf16_f32 v231, v238, v239
	ds_read_b64_tr_b16 v[168:169], v244 offset:8704
	ds_read_b64_tr_b16 v[170:171], v244 offset:10752
	s_waitcnt lgkmcnt(12)
	v_mfma_f32_32x32x16_bf16 v[48:63], v[208:211], v[144:147], v[48:63]
	ds_read_b64_tr_b16 v[172:173], v244 offset:12800
	ds_read_b64_tr_b16 v[174:175], v244 offset:14848
	s_waitcnt lgkmcnt(12)
	v_mfma_f32_32x32x16_bf16 v[48:63], v[212:215], v[148:151], v[48:63]
	ds_read_b64_tr_b16 v[144:145], v244 offset:1024
	ds_read_b64_tr_b16 v[146:147], v244 offset:3072
	s_waitcnt lgkmcnt(12)
	v_mfma_f32_32x32x16_bf16 v[48:63], v[224:227], v[152:155], v[48:63]
	v_exp_f32_e32 v64, v64
	v_exp_f32_e32 v65, v65
	ds_read_b64_tr_b16 v[148:149], v244 offset:5120
	ds_read_b64_tr_b16 v[150:151], v244 offset:7168
	s_waitcnt lgkmcnt(12)
	v_mfma_f32_32x32x16_bf16 v[48:63], v[228:231], v[156:159], v[48:63]
	v_exp_f32_e32 v66, v66
	v_exp_f32_e32 v67, v67
	ds_read_b64_tr_b16 v[152:153], v244 offset:9216
	ds_read_b64_tr_b16 v[154:155], v244 offset:11264
	s_waitcnt lgkmcnt(12)
	v_mfma_f32_32x32x16_bf16 v[32:47], v[208:211], v[160:163], v[32:47]
	v_exp_f32_e32 v68, v68
	ds_read_b64_tr_b16 v[156:157], v244 offset:13312
	ds_read_b64_tr_b16 v[158:159], v244 offset:15360
	s_waitcnt lgkmcnt(12)
	v_mfma_f32_32x32x16_bf16 v[32:47], v[212:215], v[164:167], v[32:47]
	v_exp_f32_e32 v69, v69
	ds_read_b64_tr_b16 v[160:161], v244 offset:1536
	ds_read_b64_tr_b16 v[162:163], v244 offset:3584
	s_waitcnt lgkmcnt(12)
	v_mfma_f32_32x32x16_bf16 v[32:47], v[224:227], v[168:171], v[32:47]
	v_exp_f32_e32 v70, v70
	ds_read_b64_tr_b16 v[164:165], v244 offset:5632
	ds_read_b64_tr_b16 v[166:167], v244 offset:7680
	s_waitcnt lgkmcnt(12)
	v_mfma_f32_32x32x16_bf16 v[32:47], v[228:231], v[172:175], v[32:47]
	v_exp_f32_e32 v71, v71
	ds_read_b64_tr_b16 v[168:169], v244 offset:9728
	ds_read_b64_tr_b16 v[170:171], v244 offset:11776
	s_waitcnt lgkmcnt(12)
	v_mfma_f32_32x32x16_bf16 v[16:31], v[208:211], v[144:147], v[16:31]
	v_exp_f32_e32 v72, v72
	ds_read_b64_tr_b16 v[172:173], v244 offset:13824
	ds_read_b64_tr_b16 v[174:175], v244 offset:15872
	s_waitcnt lgkmcnt(12)
	v_mfma_f32_32x32x16_bf16 v[16:31], v[212:215], v[148:151], v[16:31]
	v_exp_f32_e32 v73, v73
	v_add_u32_e32 v244, 0x4000, v244
	ds_read_b128 v[144:147], v240 offset:0
	s_waitcnt lgkmcnt(11)
	v_mfma_f32_32x32x16_bf16 v[16:31], v[224:227], v[152:155], v[16:31]
	v_exp_f32_e32 v74, v74
	ds_read_b128 v[148:151], v240 offset:12288
	s_waitcnt lgkmcnt(10)
	v_mfma_f32_32x32x16_bf16 v[16:31], v[228:231], v[156:159], v[16:31]
	v_exp_f32_e32 v75, v75
	ds_read_b128 v[152:155], v241 offset:0
	s_waitcnt lgkmcnt(9)
	v_mfma_f32_32x32x16_bf16 v[0:15], v[208:211], v[160:163], v[0:15]
	v_exp_f32_e32 v76, v76
	ds_read_b128 v[156:159], v241 offset:12288
	s_waitcnt lgkmcnt(8)
	v_mfma_f32_32x32x16_bf16 v[0:15], v[212:215], v[164:167], v[0:15]
	v_exp_f32_e32 v77, v77
	ds_read_b128 v[160:163], v242 offset:0
	s_waitcnt lgkmcnt(7)
	v_mfma_f32_32x32x16_bf16 v[0:15], v[224:227], v[168:171], v[0:15]
	v_exp_f32_e32 v78, v78
	ds_read_b128 v[164:167], v242 offset:12288
	s_waitcnt lgkmcnt(6)
	v_mfma_f32_32x32x16_bf16 v[0:15], v[228:231], v[172:175], v[0:15]
	v_exp_f32_e32 v79, v79
.Lattn_loop:
	s_waitcnt vmcnt(5)
	s_barrier
	ds_read_b128 v[168:171], v243 offset:0
	s_waitcnt lgkmcnt(6)
	v_mfma_f32_32x32x16_bf16 v[208:223], v[144:147], v[96:99], 0
	v_exp_f32_e32 v80, v80
	v_add_f32_e32 v245, v64, v245
	v_exp_f32_e32 v81, v81
	ds_read_b128 v[172:175], v243 offset:12288
	s_waitcnt lgkmcnt(6)
	v_mfma_f32_32x32x16_bf16 v[224:239], v[148:151], v[96:99], 0
	v_add_f32_e32 v246, v65, v246
	v_exp_f32_e32 v82, v82
	v_add_f32_e32 v245, v66, v245
	ds_read_b128 v[144:147], v240 offset:128
	s_waitcnt lgkmcnt(6)
	v_mfma_f32_32x32x16_bf16 v[208:223], v[152:155], v[100:103], v[208:223]
	v_exp_f32_e32 v83, v83
	v_add_f32_e32 v246, v67, v246
	s_add_i32 m0, s60, 0x12000
	s_nop 0
	global_load_lds_dwordx4 v182, s[42:43]
	ds_read_b128 v[148:151], v240 offset:12416
	s_waitcnt lgkmcnt(6)
	v_mfma_f32_32x32x16_bf16 v[224:239], v[156:159], v[100:103], v[224:239]
	v_exp_f32_e32 v84, v84
	v_add_f32_e32 v245, v68, v245
	v_exp_f32_e32 v85, v85
	ds_read_b128 v[152:155], v241 offset:128
	s_waitcnt lgkmcnt(6)
	v_mfma_f32_32x32x16_bf16 v[208:223], v[160:163], v[104:107], v[208:223]
	v_add_f32_e32 v246, v69, v246
	v_exp_f32_e32 v86, v86
	v_add_f32_e32 v245, v70, v245
	ds_read_b128 v[156:159], v241 offset:12416
	s_waitcnt lgkmcnt(6)
	v_mfma_f32_32x32x16_bf16 v[224:239], v[164:167], v[104:107], v[224:239]
	v_exp_f32_e32 v87, v87
	v_add_f32_e32 v246, v71, v246
	s_add_i32 m0, s60, 0x12400
	s_nop 0
	global_load_lds_dwordx4 v183, s[42:43]
	ds_read_b128 v[160:163], v242 offset:128
	s_waitcnt lgkmcnt(6)
	v_mfma_f32_32x32x16_bf16 v[208:223], v[168:171], v[108:111], v[208:223]
	v_exp_f32_e32 v88, v88
	v_add_f32_e32 v245, v72, v245
	v_exp_f32_e32 v89, v89
	ds_read_b128 v[164:167], v242 offset:12416
	s_waitcnt lgkmcnt(6)
	v_mfma_f32_32x32x16_bf16 v[224:239], v[172:175], v[108:111], v[224:239]
	v_add_f32_e32 v246, v73, v246
	v_exp_f32_e32 v90, v90
	v_add_f32_e32 v245, v74, v245
	ds_read_b128 v[168:171], v243 offset:128
	s_waitcnt lgkmcnt(6)
	v_mfma_f32_32x32x16_bf16 v[208:223], v[144:147], v[112:115], v[208:223]
	v_exp_f32_e32 v91, v91
	v_add_f32_e32 v246, v75, v246
	s_add_i32 m0, s60, 0x12800
	s_nop 0
	global_load_lds_dwordx4 v184, s[42:43]
	ds_read_b128 v[172:175], v243 offset:12416
	s_waitcnt lgkmcnt(6)
	v_mfma_f32_32x32x16_bf16 v[224:239], v[148:151], v[112:115], v[224:239]
	v_exp_f32_e32 v92, v92
	v_add_f32_e32 v245, v76, v245
	v_exp_f32_e32 v93, v93
	ds_read_b128 v[144:147], v240 offset:256
	s_waitcnt lgkmcnt(6)
	v_mfma_f32_32x32x16_bf16 v[208:223], v[152:155], v[116:119], v[208:223]
	v_add_f32_e32 v246, v77, v246
	v_exp_f32_e32 v94, v94
	v_add_f32_e32 v245, v78, v245
	ds_read_b128 v[148:151], v240 offset:12544
	s_waitcnt lgkmcnt(6)
	v_mfma_f32_32x32x16_bf16 v[224:239], v[156:159], v[116:119], v[224:239]
	v_exp_f32_e32 v95, v95
	v_add_f32_e32 v246, v79, v246
	s_add_i32 m0, s61, 0x0
	s_nop 0
	global_load_lds_dwordx4 v185, s[46:47]
	ds_read_b128 v[152:155], v241 offset:256
	s_waitcnt lgkmcnt(6)
	v_mfma_f32_32x32x16_bf16 v[208:223], v[160:163], v[120:123], v[208:223]
	v_add_f32_e32 v245, v80, v245
	v_add_f32_e32 v246, v81, v246
	v_add_f32_e32 v245, v82, v245
	ds_read_b128 v[156:159], v241 offset:12544
	s_waitcnt lgkmcnt(6)
	v_mfma_f32_32x32x16_bf16 v[224:239], v[164:167], v[120:123], v[224:239]
	v_add_f32_e32 v246, v83, v246
	v_add_f32_e32 v245, v84, v245
	v_add_f32_e32 v246, v85, v246
	ds_read_b128 v[160:163], v242 offset:256
	s_waitcnt lgkmcnt(6)
	v_mfma_f32_32x32x16_bf16 v[208:223], v[168:171], v[124:127], v[208:223]
	v_add_f32_e32 v245, v86, v245
	v_add_f32_e32 v246, v87, v246
	s_add_i32 m0, s61, 0x400
	s_nop 0
	global_load_lds_dwordx4 v186, s[46:47]
	ds_read_b128 v[164:167], v242 offset:12544
	s_waitcnt lgkmcnt(6)
	v_mfma_f32_32x32x16_bf16 v[224:239], v[172:175], v[124:127], v[224:239]
	v_add_f32_e32 v245, v88, v245
	v_add_f32_e32 v246, v89, v246
	v_add_f32_e32 v245, v90, v245
	ds_read_b128 v[168:171], v243 offset:256
	s_waitcnt lgkmcnt(6)
	v_mfma_f32_32x32x16_bf16 v[208:223], v[144:147], v[128:131], v[208:223]
	v_add_f32_e32 v246, v91, v246
	v_add_f32_e32 v245, v92, v245
	v_add_f32_e32 v246, v93, v246
	ds_read_b128 v[172:175], v243 offset:12544
	s_waitcnt lgkmcnt(6)
	v_mfma_f32_32x32x16_bf16 v[224:239], v[148:151], v[128:131], v[224:239]
	v_add_f32_e32 v245, v94, v245
	v_add_f32_e32 v246, v95, v246
	s_add_u32 s42, s42, 0x6000
	s_addc_u32 s43, s43, 0
	v_add_u32_e32 v240, 0x9010, v240
	ds_read_b64_tr_b16 v[144:145], v244 offset:0
	ds_read_b64_tr_b16 v[146:147], v244 offset:2048
	s_waitcnt lgkmcnt(7)
	v_mfma_f32_32x32x16_bf16 v[208:223], v[152:155], v[132:135], v[208:223]
	v_cvt_pk_bf16_f32 v64, v64, v65
	v_cvt_pk_bf16_f32 v65, v66, v67
	v_cvt_pk_bf16_f32 v66, v68, v69
	v_add_u32_e32 v241, 0x9010, v241
	ds_read_b64_tr_b16 v[148:149], v244 offset:4096
	ds_read_b64_tr_b16 v[150:151], v244 offset:6144
	s_waitcnt lgkmcnt(8)
	v_mfma_f32_32x32x16_bf16 v[224:239], v[156:159], v[132:135], v[224:239]
	v_cvt_pk_bf16_f32 v67, v70, v71
	v_cvt_pk_bf16_f32 v68, v72, v73
	v_cvt_pk_bf16_f32 v69, v74, v75
	v_add_u32_e32 v242, 0x9010, v242
	ds_read_b64_tr_b16 v[152:153], v244 offset:8192
	ds_read_b64_tr_b16 v[154:155], v244 offset:10240
	s_waitcnt lgkmcnt(9)
	v_mfma_f32_32x32x16_bf16 v[208:223], v[160:163], v[136:139], v[208:223]
	v_cvt_pk_bf16_f32 v70, v76, v77
	v_cvt_pk_bf16_f32 v71, v78, v79
	s_add_u32 s46, s46, 0x40000
	s_addc_u32 s47, s47, 0
	v_add_u32_e32 v243, 0x9010, v243
	ds_read_b64_tr_b16 v[156:157], v244 offset:12288
	ds_read_b64_tr_b16 v[158:159], v244 offset:14336
	s_waitcnt lgkmcnt(10)
	v_mfma_f32_32x32x16_bf16 v[224:239], v[164:167], v[136:139], v[224:239]
	v_cvt_pk_bf16_f32 v80, v80, v81
	v_cvt_pk_bf16_f32 v81, v82, v83
	v_cvt_pk_bf16_f32 v82, v84, v85
	ds_read_b64_tr_b16 v[160:161], v244 offset:512
	ds_read_b64_tr_b16 v[162:163], v244 offset:2560
	s_waitcnt lgkmcnt(11)
	v_mfma_f32_32x32x16_bf16 v[208:223], v[168:171], v[140:143], v[208:223]
	v_cvt_pk_bf16_f32 v83, v86, v87
	v_cvt_pk_bf16_f32 v84, v88, v89
	v_cvt_pk_bf16_f32 v85, v90, v91
	ds_read_b64_tr_b16 v[164:165], v244 offset:4608
	ds_read_b64_tr_b16 v[166:167], v244 offset:6656
	s_waitcnt lgkmcnt(12)
	v_mfma_f32_32x32x16_bf16 v[224:239], v[172:175], v[140:143], v[224:239]
	v_cvt_pk_bf16_f32 v86, v92, v93
	v_cvt_pk_bf16_f32 v87, v94, v95
	ds_read_b64_tr_b16 v[168:169], v244 offset:8704
	ds_read_b64_tr_b16 v[170:171], v244 offset:10752
	s_waitcnt lgkmcnt(12)
	v_mfma_f32_32x32x16_bf16 v[48:63], v[64:67], v[144:147], v[48:63]
	ds_read_b64_tr_b16 v[172:173], v244 offset:12800
	ds_read_b64_tr_b16 v[174:175], v244 offset:14848
	s_waitcnt lgkmcnt(12)
	v_mfma_f32_32x32x16_bf16 v[48:63], v[68:71], v[148:151], v[48:63]
	ds_read_b64_tr_b16 v[144:145], v244 offset:1024
	ds_read_b64_tr_b16 v[146:147], v244 offset:3072
	s_waitcnt lgkmcnt(12)
	v_mfma_f32_32x32x16_bf16 v[48:63], v[80:83], v[152:155], v[48:63]
	v_exp_f32_e32 v208, v208
	v_exp_f32_e32 v209, v209
	ds_read_b64_tr_b16 v[148:149], v244 offset:5120
	ds_read_b64_tr_b16 v[150:151], v244 offset:7168
	s_waitcnt lgkmcnt(12)
	v_mfma_f32_32x32x16_bf16 v[48:63], v[84:87], v[156:159], v[48:63]
	v_exp_f32_e32 v210, v210
	v_exp_f32_e32 v211, v211
	ds_read_b64_tr_b16 v[152:153], v244 offset:9216
	ds_read_b64_tr_b16 v[154:155], v244 offset:11264
	s_waitcnt lgkmcnt(12)
	v_mfma_f32_32x32x16_bf16 v[32:47], v[64:67], v[160:163], v[32:47]
	v_exp_f32_e32 v212, v212
	ds_read_b64_tr_b16 v[156:157], v244 offset:13312
	ds_read_b64_tr_b16 v[158:159], v244 offset:15360
	s_waitcnt lgkmcnt(12)
	v_mfma_f32_32x32x16_bf16 v[32:47], v[68:71], v[164:167], v[32:47]
	v_exp_f32_e32 v213, v213
	ds_read_b64_tr_b16 v[160:161], v244 offset:1536
	ds_read_b64_tr_b16 v[162:163], v244 offset:3584
	s_waitcnt lgkmcnt(12)
	v_mfma_f32_32x32x16_bf16 v[32:47], v[80:83], v[168:171], v[32:47]
	v_exp_f32_e32 v214, v214
	ds_read_b64_tr_b16 v[164:165], v244 offset:5632
	ds_read_b64_tr_b16 v[166:167], v244 offset:7680
	s_waitcnt lgkmcnt(12)
	v_mfma_f32_32x32x16_bf16 v[32:47], v[84:87], v[172:175], v[32:47]
	v_exp_f32_e32 v215, v215
	ds_read_b64_tr_b16 v[168:169], v244 offset:9728
	ds_read_b64_tr_b16 v[170:171], v244 offset:11776
	s_waitcnt lgkmcnt(12)
	v_mfma_f32_32x32x16_bf16 v[16:31], v[64:67], v[144:147], v[16:31]
	v_exp_f32_e32 v216, v216
	ds_read_b64_tr_b16 v[172:173], v244 offset:13824
	ds_read_b64_tr_b16 v[174:175], v244 offset:15872
	s_waitcnt lgkmcnt(12)
	v_mfma_f32_32x32x16_bf16 v[16:31], v[68:71], v[148:151], v[16:31]
	v_exp_f32_e32 v217, v217
	v_add_u32_e32 v244, 0x4000, v244
	ds_read_b128 v[144:147], v240 offset:0
	s_waitcnt lgkmcnt(11)
	v_mfma_f32_32x32x16_bf16 v[16:31], v[80:83], v[152:155], v[16:31]
	v_exp_f32_e32 v218, v218
	ds_read_b128 v[148:151], v240 offset:12288
	s_waitcnt lgkmcnt(10)
	v_mfma_f32_32x32x16_bf16 v[16:31], v[84:87], v[156:159], v[16:31]
	v_exp_f32_e32 v219, v219
	ds_read_b128 v[152:155], v241 offset:0
	s_waitcnt lgkmcnt(9)
	v_mfma_f32_32x32x16_bf16 v[0:15], v[64:67], v[160:163], v[0:15]
	v_exp_f32_e32 v220, v220
	ds_read_b128 v[156:159], v241 offset:12288
	s_waitcnt lgkmcnt(8)
	v_mfma_f32_32x32x16_bf16 v[0:15], v[68:71], v[164:167], v[0:15]
	v_exp_f32_e32 v221, v221
	ds_read_b128 v[160:163], v242 offset:0
	s_waitcnt lgkmcnt(7)
	v_mfma_f32_32x32x16_bf16 v[0:15], v[80:83], v[168:171], v[0:15]
	v_exp_f32_e32 v222, v222
	ds_read_b128 v[164:167], v242 offset:12288
	s_waitcnt lgkmcnt(6)
	v_mfma_f32_32x32x16_bf16 v[0:15], v[84:87], v[172:175], v[0:15]
	v_exp_f32_e32 v223, v223
	s_waitcnt vmcnt(5)
	s_barrier
	ds_read_b128 v[168:171], v243 offset:0
	s_waitcnt lgkmcnt(6)
	v_mfma_f32_32x32x16_bf16 v[64:79], v[144:147], v[96:99], 0
	v_exp_f32_e32 v224, v224
	v_add_f32_e32 v245, v208, v245
	v_exp_f32_e32 v225, v225
	ds_read_b128 v[172:175], v243 offset:12288
	s_waitcnt lgkmcnt(6)
	v_mfma_f32_32x32x16_bf16 v[80:95], v[148:151], v[96:99], 0
	v_add_f32_e32 v246, v209, v246
	v_exp_f32_e32 v226, v226
	v_add_f32_e32 v245, v210, v245
	ds_read_b128 v[144:147], v240 offset:128
	s_waitcnt lgkmcnt(6)
	v_mfma_f32_32x32x16_bf16 v[64:79], v[152:155], v[100:103], v[64:79]
	v_exp_f32_e32 v227, v227
	v_add_f32_e32 v246, v211, v246
	s_add_i32 m0, s60, 0x18000
	s_nop 0
	global_load_lds_dwordx4 v182, s[42:43]
	ds_read_b128 v[148:151], v240 offset:12416
	s_waitcnt lgkmcnt(6)
	v_mfma_f32_32x32x16_bf16 v[80:95], v[156:159], v[100:103], v[80:95]
	v_exp_f32_e32 v228, v228
	v_add_f32_e32 v245, v212, v245
	v_exp_f32_e32 v229, v229
	ds_read_b128 v[152:155], v241 offset:128
	s_waitcnt lgkmcnt(6)
	v_mfma_f32_32x32x16_bf16 v[64:79], v[160:163], v[104:107], v[64:79]
	v_add_f32_e32 v246, v213, v246
	v_exp_f32_e32 v230, v230
	v_add_f32_e32 v245, v214, v245
	ds_read_b128 v[156:159], v241 offset:12416
	s_waitcnt lgkmcnt(6)
	v_mfma_f32_32x32x16_bf16 v[80:95], v[164:167], v[104:107], v[80:95]
	v_exp_f32_e32 v231, v231
	v_add_f32_e32 v246, v215, v246
	s_add_i32 m0, s60, 0x18400
	s_nop 0
	global_load_lds_dwordx4 v183, s[42:43]
	ds_read_b128 v[160:163], v242 offset:128
	s_waitcnt lgkmcnt(6)
	v_mfma_f32_32x32x16_bf16 v[64:79], v[168:171], v[108:111], v[64:79]
	v_exp_f32_e32 v232, v232
	v_add_f32_e32 v245, v216, v245
	v_exp_f32_e32 v233, v233
	ds_read_b128 v[164:167], v242 offset:12416
	s_waitcnt lgkmcnt(6)
	v_mfma_f32_32x32x16_bf16 v[80:95], v[172:175], v[108:111], v[80:95]
	v_add_f32_e32 v246, v217, v246
	v_exp_f32_e32 v234, v234
	v_add_f32_e32 v245, v218, v245
	ds_read_b128 v[168:171], v243 offset:128
	s_waitcnt lgkmcnt(6)
	v_mfma_f32_32x32x16_bf16 v[64:79], v[144:147], v[112:115], v[64:79]
	v_exp_f32_e32 v235, v235
	v_add_f32_e32 v246, v219, v246
	s_add_i32 m0, s60, 0x18800
	s_nop 0
	global_load_lds_dwordx4 v184, s[42:43]
	ds_read_b128 v[172:175], v243 offset:12416
	s_waitcnt lgkmcnt(6)
	v_mfma_f32_32x32x16_bf16 v[80:95], v[148:151], v[112:115], v[80:95]
	v_exp_f32_e32 v236, v236
	v_add_f32_e32 v245, v220, v245
	v_exp_f32_e32 v237, v237
	ds_read_b128 v[144:147], v240 offset:256
	s_waitcnt lgkmcnt(6)
	v_mfma_f32_32x32x16_bf16 v[64:79], v[152:155], v[116:119], v[64:79]
	v_add_f32_e32 v246, v221, v246
	v_exp_f32_e32 v238, v238
	v_add_f32_e32 v245, v222, v245
	ds_read_b128 v[148:151], v240 offset:12544
	s_waitcnt lgkmcnt(6)
	v_mfma_f32_32x32x16_bf16 v[80:95], v[156:159], v[116:119], v[80:95]
	v_exp_f32_e32 v239, v239
	v_add_f32_e32 v246, v223, v246
	s_add_i32 m0, s61, 0x4000
	s_nop 0
	global_load_lds_dwordx4 v185, s[46:47]
	ds_read_b128 v[152:155], v241 offset:256
	s_waitcnt lgkmcnt(6)
	v_mfma_f32_32x32x16_bf16 v[64:79], v[160:163], v[120:123], v[64:79]
	v_add_f32_e32 v245, v224, v245
	v_add_f32_e32 v246, v225, v246
	v_add_f32_e32 v245, v226, v245
	ds_read_b128 v[156:159], v241 offset:12544
	s_waitcnt lgkmcnt(6)
	v_mfma_f32_32x32x16_bf16 v[80:95], v[164:167], v[120:123], v[80:95]
	v_add_f32_e32 v246, v227, v246
	v_add_f32_e32 v245, v228, v245
	v_add_f32_e32 v246, v229, v246
	ds_read_b128 v[160:163], v242 offset:256
	s_waitcnt lgkmcnt(6)
	v_mfma_f32_32x32x16_bf16 v[64:79], v[168:171], v[124:127], v[64:79]
	v_add_f32_e32 v245, v230, v245
	v_add_f32_e32 v246, v231, v246
	s_add_i32 m0, s61, 0x4400
	s_nop 0
	global_load_lds_dwordx4 v186, s[46:47]
	ds_read_b128 v[164:167], v242 offset:12544
	s_waitcnt lgkmcnt(6)
	v_mfma_f32_32x32x16_bf16 v[80:95], v[172:175], v[124:127], v[80:95]
	v_add_f32_e32 v245, v232, v245
	v_add_f32_e32 v246, v233, v246
	v_add_f32_e32 v245, v234, v245
	ds_read_b128 v[168:171], v243 offset:256
	s_waitcnt lgkmcnt(6)
	v_mfma_f32_32x32x16_bf16 v[64:79], v[144:147], v[128:131], v[64:79]
	v_add_f32_e32 v246, v235, v246
	v_add_f32_e32 v245, v236, v245
	v_add_f32_e32 v246, v237, v246
	ds_read_b128 v[172:175], v243 offset:12544
	s_waitcnt lgkmcnt(6)
	v_mfma_f32_32x32x16_bf16 v[80:95], v[148:151], v[128:131], v[80:95]
	v_add_f32_e32 v245, v238, v245
	v_add_f32_e32 v246, v239, v246
	s_add_u32 s42, s42, 0x6000
	s_addc_u32 s43, s43, 0
	v_add_u32_e32 v240, 0xfffeaff0, v240
	ds_read_b64_tr_b16 v[144:145], v244 offset:0
	ds_read_b64_tr_b16 v[146:147], v244 offset:2048
	s_waitcnt lgkmcnt(7)
	v_mfma_f32_32x32x16_bf16 v[64:79], v[152:155], v[132:135], v[64:79]
	v_cvt_pk_bf16_f32 v208, v208, v209
	v_cvt_pk_bf16_f32 v209, v210, v211
	v_cvt_pk_bf16_f32 v210, v212, v213
	v_add_u32_e32 v241, 0xfffeaff0, v241
	ds_read_b64_tr_b16 v[148:149], v244 offset:4096
	ds_read_b64_tr_b16 v[150:151], v244 offset:6144
	s_waitcnt lgkmcnt(8)
	v_mfma_f32_32x32x16_bf16 v[80:95], v[156:159], v[132:135], v[80:95]
	v_cvt_pk_bf16_f32 v211, v214, v215
	v_cvt_pk_bf16_f32 v212, v216, v217
	v_cvt_pk_bf16_f32 v213, v218, v219
	v_add_u32_e32 v242, 0xfffeaff0, v242
	ds_read_b64_tr_b16 v[152:153], v244 offset:8192
	ds_read_b64_tr_b16 v[154:155], v244 offset:10240
	s_waitcnt lgkmcnt(9)
	v_mfma_f32_32x32x16_bf16 v[64:79], v[160:163], v[136:139], v[64:79]
	v_cvt_pk_bf16_f32 v214, v220, v221
	v_cvt_pk_bf16_f32 v215, v222, v223
	s_add_u32 s46, s46, 0x40000
	s_addc_u32 s47, s47, 0
	v_add_u32_e32 v243, 0xfffeaff0, v243
	ds_read_b64_tr_b16 v[156:157], v244 offset:12288
	ds_read_b64_tr_b16 v[158:159], v244 offset:14336
	s_waitcnt lgkmcnt(10)
	v_mfma_f32_32x32x16_bf16 v[80:95], v[164:167], v[136:139], v[80:95]
	v_cvt_pk_bf16_f32 v224, v224, v225
	v_cvt_pk_bf16_f32 v225, v226, v227
	v_cvt_pk_bf16_f32 v226, v228, v229
	ds_read_b64_tr_b16 v[160:161], v244 offset:512
	ds_read_b64_tr_b16 v[162:163], v244 offset:2560
	s_waitcnt lgkmcnt(11)
	v_mfma_f32_32x32x16_bf16 v[64:79], v[168:171], v[140:143], v[64:79]
	v_cvt_pk_bf16_f32 v227, v230, v231
	v_cvt_pk_bf16_f32 v228, v232, v233
	v_cvt_pk_bf16_f32 v229, v234, v235
	ds_read_b64_tr_b16 v[164:165], v244 offset:4608
	ds_read_b64_tr_b16 v[166:167], v244 offset:6656
	s_waitcnt lgkmcnt(12)
	v_mfma_f32_32x32x16_bf16 v[80:95], v[172:175], v[140:143], v[80:95]
	v_cvt_pk_bf16_f32 v230, v236, v237
	v_cvt_pk_bf16_f32 v231, v238, v239
	ds_read_b64_tr_b16 v[168:169], v244 offset:8704
	ds_read_b64_tr_b16 v[170:171], v244 offset:10752
	s_waitcnt lgkmcnt(12)
	v_mfma_f32_32x32x16_bf16 v[48:63], v[208:211], v[144:147], v[48:63]
	ds_read_b64_tr_b16 v[172:173], v244 offset:12800
	ds_read_b64_tr_b16 v[174:175], v244 offset:14848
	s_waitcnt lgkmcnt(12)
	v_mfma_f32_32x32x16_bf16 v[48:63], v[212:215], v[148:151], v[48:63]
	ds_read_b64_tr_b16 v[144:145], v244 offset:1024
	ds_read_b64_tr_b16 v[146:147], v244 offset:3072
	s_waitcnt lgkmcnt(12)
	v_mfma_f32_32x32x16_bf16 v[48:63], v[224:227], v[152:155], v[48:63]
	v_exp_f32_e32 v64, v64
	v_exp_f32_e32 v65, v65
	ds_read_b64_tr_b16 v[148:149], v244 offset:5120
	ds_read_b64_tr_b16 v[150:151], v244 offset:7168
	s_waitcnt lgkmcnt(12)
	v_mfma_f32_32x32x16_bf16 v[48:63], v[228:231], v[156:159], v[48:63]
	v_exp_f32_e32 v66, v66
	v_exp_f32_e32 v67, v67
	ds_read_b64_tr_b16 v[152:153], v244 offset:9216
	ds_read_b64_tr_b16 v[154:155], v244 offset:11264
	s_waitcnt lgkmcnt(12)
	v_mfma_f32_32x32x16_bf16 v[32:47], v[208:211], v[160:163], v[32:47]
	v_exp_f32_e32 v68, v68
	ds_read_b64_tr_b16 v[156:157], v244 offset:13312
	ds_read_b64_tr_b16 v[158:159], v244 offset:15360
	s_waitcnt lgkmcnt(12)
	v_mfma_f32_32x32x16_bf16 v[32:47], v[212:215], v[164:167], v[32:47]
	v_exp_f32_e32 v69, v69
	ds_read_b64_tr_b16 v[160:161], v244 offset:1536
	ds_read_b64_tr_b16 v[162:163], v244 offset:3584
	s_waitcnt lgkmcnt(12)
	v_mfma_f32_32x32x16_bf16 v[32:47], v[224:227], v[168:171], v[32:47]
	v_exp_f32_e32 v70, v70
	ds_read_b64_tr_b16 v[164:165], v244 offset:5632
	ds_read_b64_tr_b16 v[166:167], v244 offset:7680
	s_waitcnt lgkmcnt(12)
	v_mfma_f32_32x32x16_bf16 v[32:47], v[228:231], v[172:175], v[32:47]
	v_exp_f32_e32 v71, v71
	ds_read_b64_tr_b16 v[168:169], v244 offset:9728
	ds_read_b64_tr_b16 v[170:171], v244 offset:11776
	s_waitcnt lgkmcnt(12)
	v_mfma_f32_32x32x16_bf16 v[16:31], v[208:211], v[144:147], v[16:31]
	v_exp_f32_e32 v72, v72
	ds_read_b64_tr_b16 v[172:173], v244 offset:13824
	ds_read_b64_tr_b16 v[174:175], v244 offset:15872
	s_waitcnt lgkmcnt(12)
	v_mfma_f32_32x32x16_bf16 v[16:31], v[212:215], v[148:151], v[16:31]
	v_exp_f32_e32 v73, v73
	v_add_u32_e32 v244, 0xffff8000, v244
	ds_read_b128 v[144:147], v240 offset:0
	s_waitcnt lgkmcnt(11)
	v_mfma_f32_32x32x16_bf16 v[16:31], v[224:227], v[152:155], v[16:31]
	v_exp_f32_e32 v74, v74
	ds_read_b128 v[148:151], v240 offset:12288
	s_waitcnt lgkmcnt(10)
	v_mfma_f32_32x32x16_bf16 v[16:31], v[228:231], v[156:159], v[16:31]
	v_exp_f32_e32 v75, v75
	ds_read_b128 v[152:155], v241 offset:0
	s_waitcnt lgkmcnt(9)
	v_mfma_f32_32x32x16_bf16 v[0:15], v[208:211], v[160:163], v[0:15]
	v_exp_f32_e32 v76, v76
	ds_read_b128 v[156:159], v241 offset:12288
	s_waitcnt lgkmcnt(8)
	v_mfma_f32_32x32x16_bf16 v[0:15], v[212:215], v[164:167], v[0:15]
	v_exp_f32_e32 v77, v77
	ds_read_b128 v[160:163], v242 offset:0
	s_waitcnt lgkmcnt(7)
	v_mfma_f32_32x32x16_bf16 v[0:15], v[224:227], v[168:171], v[0:15]
	v_exp_f32_e32 v78, v78
	ds_read_b128 v[164:167], v242 offset:12288
	s_waitcnt lgkmcnt(6)
	v_mfma_f32_32x32x16_bf16 v[0:15], v[228:231], v[172:175], v[0:15]
	v_exp_f32_e32 v79, v79
	s_waitcnt vmcnt(5)
	s_barrier
	ds_read_b128 v[168:171], v243 offset:0
	s_waitcnt lgkmcnt(6)
	v_mfma_f32_32x32x16_bf16 v[208:223], v[144:147], v[96:99], 0
	v_exp_f32_e32 v80, v80
	v_add_f32_e32 v245, v64, v245
	v_exp_f32_e32 v81, v81
	ds_read_b128 v[172:175], v243 offset:12288
	s_waitcnt lgkmcnt(6)
	v_mfma_f32_32x32x16_bf16 v[224:239], v[148:151], v[96:99], 0
	v_add_f32_e32 v246, v65, v246
	v_exp_f32_e32 v82, v82
	v_add_f32_e32 v245, v66, v245
	ds_read_b128 v[144:147], v240 offset:128
	s_waitcnt lgkmcnt(6)
	v_mfma_f32_32x32x16_bf16 v[208:223], v[152:155], v[100:103], v[208:223]
	v_exp_f32_e32 v83, v83
	v_add_f32_e32 v246, v67, v246
	s_add_i32 m0, s60, 0x21010
	s_nop 0
	global_load_lds_dwordx4 v182, s[42:43]
	ds_read_b128 v[148:151], v240 offset:12416
	s_waitcnt lgkmcnt(6)
	v_mfma_f32_32x32x16_bf16 v[224:239], v[156:159], v[100:103], v[224:239]
	v_exp_f32_e32 v84, v84
	v_add_f32_e32 v245, v68, v245
	v_exp_f32_e32 v85, v85
	ds_read_b128 v[152:155], v241 offset:128
	s_waitcnt lgkmcnt(6)
	v_mfma_f32_32x32x16_bf16 v[208:223], v[160:163], v[104:107], v[208:223]
	v_add_f32_e32 v246, v69, v246
	v_exp_f32_e32 v86, v86
	v_add_f32_e32 v245, v70, v245
	ds_read_b128 v[156:159], v241 offset:12416
	s_waitcnt lgkmcnt(6)
	v_mfma_f32_32x32x16_bf16 v[224:239], v[164:167], v[104:107], v[224:239]
	v_exp_f32_e32 v87, v87
	v_add_f32_e32 v246, v71, v246
	s_add_i32 m0, s60, 0x21410
	s_nop 0
	global_load_lds_dwordx4 v183, s[42:43]
	ds_read_b128 v[160:163], v242 offset:128
	s_waitcnt lgkmcnt(6)
	v_mfma_f32_32x32x16_bf16 v[208:223], v[168:171], v[108:111], v[208:223]
	v_exp_f32_e32 v88, v88
	v_add_f32_e32 v245, v72, v245
	v_exp_f32_e32 v89, v89
	ds_read_b128 v[164:167], v242 offset:12416
	s_waitcnt lgkmcnt(6)
	v_mfma_f32_32x32x16_bf16 v[224:239], v[172:175], v[108:111], v[224:239]
	v_add_f32_e32 v246, v73, v246
	v_exp_f32_e32 v90, v90
	v_add_f32_e32 v245, v74, v245
	ds_read_b128 v[168:171], v243 offset:128
	s_waitcnt lgkmcnt(6)
	v_mfma_f32_32x32x16_bf16 v[208:223], v[144:147], v[112:115], v[208:223]
	v_exp_f32_e32 v91, v91
	v_add_f32_e32 v246, v75, v246
	s_add_i32 m0, s60, 0x21810
	s_nop 0
	global_load_lds_dwordx4 v184, s[42:43]
	ds_read_b128 v[172:175], v243 offset:12416
	s_waitcnt lgkmcnt(6)
	v_mfma_f32_32x32x16_bf16 v[224:239], v[148:151], v[112:115], v[224:239]
	v_exp_f32_e32 v92, v92
	v_add_f32_e32 v245, v76, v245
	v_exp_f32_e32 v93, v93
	ds_read_b128 v[144:147], v240 offset:256
	s_waitcnt lgkmcnt(6)
	v_mfma_f32_32x32x16_bf16 v[208:223], v[152:155], v[116:119], v[208:223]
	v_add_f32_e32 v246, v77, v246
	v_exp_f32_e32 v94, v94
	v_add_f32_e32 v245, v78, v245
	ds_read_b128 v[148:151], v240 offset:12544
	s_waitcnt lgkmcnt(6)
	v_mfma_f32_32x32x16_bf16 v[224:239], v[156:159], v[116:119], v[224:239]
	v_exp_f32_e32 v95, v95
	v_add_f32_e32 v246, v79, v246
	s_add_i32 m0, s61, 0x8000
	s_nop 0
	global_load_lds_dwordx4 v185, s[46:47]
	ds_read_b128 v[152:155], v241 offset:256
	s_waitcnt lgkmcnt(6)
	v_mfma_f32_32x32x16_bf16 v[208:223], v[160:163], v[120:123], v[208:223]
	v_add_f32_e32 v245, v80, v245
	v_add_f32_e32 v246, v81, v246
	v_add_f32_e32 v245, v82, v245
	ds_read_b128 v[156:159], v241 offset:12544
	s_waitcnt lgkmcnt(6)
	v_mfma_f32_32x32x16_bf16 v[224:239], v[164:167], v[120:123], v[224:239]
	v_add_f32_e32 v246, v83, v246
	v_add_f32_e32 v245, v84, v245
	v_add_f32_e32 v246, v85, v246
	ds_read_b128 v[160:163], v242 offset:256
	s_waitcnt lgkmcnt(6)
	v_mfma_f32_32x32x16_bf16 v[208:223], v[168:171], v[124:127], v[208:223]
	v_add_f32_e32 v245, v86, v245
	v_add_f32_e32 v246, v87, v246
	s_add_i32 m0, s61, 0x8400
	s_nop 0
	global_load_lds_dwordx4 v186, s[46:47]
	ds_read_b128 v[164:167], v242 offset:12544
	s_waitcnt lgkmcnt(6)
	v_mfma_f32_32x32x16_bf16 v[224:239], v[172:175], v[124:127], v[224:239]
	v_add_f32_e32 v245, v88, v245
	v_add_f32_e32 v246, v89, v246
	v_add_f32_e32 v245, v90, v245
	ds_read_b128 v[168:171], v243 offset:256
	s_waitcnt lgkmcnt(6)
	v_mfma_f32_32x32x16_bf16 v[208:223], v[144:147], v[128:131], v[208:223]
	v_add_f32_e32 v246, v91, v246
	v_add_f32_e32 v245, v92, v245
	v_add_f32_e32 v246, v93, v246
	ds_read_b128 v[172:175], v243 offset:12544
	s_waitcnt lgkmcnt(6)
	v_mfma_f32_32x32x16_bf16 v[224:239], v[148:151], v[128:131], v[224:239]
	v_add_f32_e32 v245, v94, v245
	v_add_f32_e32 v246, v95, v246
	s_add_u32 s42, s42, 0x6000
	s_addc_u32 s43, s43, 0
	v_add_u32_e32 v240, 0x6000, v240
	ds_read_b64_tr_b16 v[144:145], v244 offset:0
	ds_read_b64_tr_b16 v[146:147], v244 offset:2048
	s_waitcnt lgkmcnt(7)
	v_mfma_f32_32x32x16_bf16 v[208:223], v[152:155], v[132:135], v[208:223]
	v_cvt_pk_bf16_f32 v64, v64, v65
	v_cvt_pk_bf16_f32 v65, v66, v67
	v_cvt_pk_bf16_f32 v66, v68, v69
	v_add_u32_e32 v241, 0x6000, v241
	ds_read_b64_tr_b16 v[148:149], v244 offset:4096
	ds_read_b64_tr_b16 v[150:151], v244 offset:6144
	s_waitcnt lgkmcnt(8)
	v_mfma_f32_32x32x16_bf16 v[224:239], v[156:159], v[132:135], v[224:239]
	v_cvt_pk_bf16_f32 v67, v70, v71
	v_cvt_pk_bf16_f32 v68, v72, v73
	v_cvt_pk_bf16_f32 v69, v74, v75
	v_add_u32_e32 v242, 0x6000, v242
	ds_read_b64_tr_b16 v[152:153], v244 offset:8192
	ds_read_b64_tr_b16 v[154:155], v244 offset:10240
	s_waitcnt lgkmcnt(9)
	v_mfma_f32_32x32x16_bf16 v[208:223], v[160:163], v[136:139], v[208:223]
	v_cvt_pk_bf16_f32 v70, v76, v77
	v_cvt_pk_bf16_f32 v71, v78, v79
	s_add_u32 s46, s46, 0x40000
	s_addc_u32 s47, s47, 0
	v_add_u32_e32 v243, 0x6000, v243
	ds_read_b64_tr_b16 v[156:157], v244 offset:12288
	ds_read_b64_tr_b16 v[158:159], v244 offset:14336
	s_waitcnt lgkmcnt(10)
	v_mfma_f32_32x32x16_bf16 v[224:239], v[164:167], v[136:139], v[224:239]
	v_cvt_pk_bf16_f32 v80, v80, v81
	v_cvt_pk_bf16_f32 v81, v82, v83
	v_cvt_pk_bf16_f32 v82, v84, v85
	ds_read_b64_tr_b16 v[160:161], v244 offset:512
	ds_read_b64_tr_b16 v[162:163], v244 offset:2560
	s_waitcnt lgkmcnt(11)
	v_mfma_f32_32x32x16_bf16 v[208:223], v[168:171], v[140:143], v[208:223]
	v_cvt_pk_bf16_f32 v83, v86, v87
	v_cvt_pk_bf16_f32 v84, v88, v89
	v_cvt_pk_bf16_f32 v85, v90, v91
	ds_read_b64_tr_b16 v[164:165], v244 offset:4608
	ds_read_b64_tr_b16 v[166:167], v244 offset:6656
	s_waitcnt lgkmcnt(12)
	v_mfma_f32_32x32x16_bf16 v[224:239], v[172:175], v[140:143], v[224:239]
	v_cvt_pk_bf16_f32 v86, v92, v93
	v_cvt_pk_bf16_f32 v87, v94, v95
	ds_read_b64_tr_b16 v[168:169], v244 offset:8704
	ds_read_b64_tr_b16 v[170:171], v244 offset:10752
	s_waitcnt lgkmcnt(12)
	v_mfma_f32_32x32x16_bf16 v[48:63], v[64:67], v[144:147], v[48:63]
	ds_read_b64_tr_b16 v[172:173], v244 offset:12800
	ds_read_b64_tr_b16 v[174:175], v244 offset:14848
	s_waitcnt lgkmcnt(12)
	v_mfma_f32_32x32x16_bf16 v[48:63], v[68:71], v[148:151], v[48:63]
	ds_read_b64_tr_b16 v[144:145], v244 offset:1024
	ds_read_b64_tr_b16 v[146:147], v244 offset:3072
	s_waitcnt lgkmcnt(12)
	v_mfma_f32_32x32x16_bf16 v[48:63], v[80:83], v[152:155], v[48:63]
	v_exp_f32_e32 v208, v208
	v_exp_f32_e32 v209, v209
	ds_read_b64_tr_b16 v[148:149], v244 offset:5120
	ds_read_b64_tr_b16 v[150:151], v244 offset:7168
	s_waitcnt lgkmcnt(12)
	v_mfma_f32_32x32x16_bf16 v[48:63], v[84:87], v[156:159], v[48:63]
	v_exp_f32_e32 v210, v210
	v_exp_f32_e32 v211, v211
	ds_read_b64_tr_b16 v[152:153], v244 offset:9216
	ds_read_b64_tr_b16 v[154:155], v244 offset:11264
	s_waitcnt lgkmcnt(12)
	v_mfma_f32_32x32x16_bf16 v[32:47], v[64:67], v[160:163], v[32:47]
	v_exp_f32_e32 v212, v212
	ds_read_b64_tr_b16 v[156:157], v244 offset:13312
	ds_read_b64_tr_b16 v[158:159], v244 offset:15360
	s_waitcnt lgkmcnt(12)
	v_mfma_f32_32x32x16_bf16 v[32:47], v[68:71], v[164:167], v[32:47]
	v_exp_f32_e32 v213, v213
	ds_read_b64_tr_b16 v[160:161], v244 offset:1536
	ds_read_b64_tr_b16 v[162:163], v244 offset:3584
	s_waitcnt lgkmcnt(12)
	v_mfma_f32_32x32x16_bf16 v[32:47], v[80:83], v[168:171], v[32:47]
	v_exp_f32_e32 v214, v214
	ds_read_b64_tr_b16 v[164:165], v244 offset:5632
	ds_read_b64_tr_b16 v[166:167], v244 offset:7680
	s_waitcnt lgkmcnt(12)
	v_mfma_f32_32x32x16_bf16 v[32:47], v[84:87], v[172:175], v[32:47]
	v_exp_f32_e32 v215, v215
	ds_read_b64_tr_b16 v[168:169], v244 offset:9728
	ds_read_b64_tr_b16 v[170:171], v244 offset:11776
	s_waitcnt lgkmcnt(12)
	v_mfma_f32_32x32x16_bf16 v[16:31], v[64:67], v[144:147], v[16:31]
	v_exp_f32_e32 v216, v216
	ds_read_b64_tr_b16 v[172:173], v244 offset:13824
	ds_read_b64_tr_b16 v[174:175], v244 offset:15872
	s_waitcnt lgkmcnt(12)
	v_mfma_f32_32x32x16_bf16 v[16:31], v[68:71], v[148:151], v[16:31]
	v_exp_f32_e32 v217, v217
	v_add_u32_e32 v244, 0x4000, v244
	ds_read_b128 v[144:147], v240 offset:0
	s_waitcnt lgkmcnt(11)
	v_mfma_f32_32x32x16_bf16 v[16:31], v[80:83], v[152:155], v[16:31]
	v_exp_f32_e32 v218, v218
	ds_read_b128 v[148:151], v240 offset:12288
	s_waitcnt lgkmcnt(10)
	v_mfma_f32_32x32x16_bf16 v[16:31], v[84:87], v[156:159], v[16:31]
	v_exp_f32_e32 v219, v219
	ds_read_b128 v[152:155], v241 offset:0
	s_waitcnt lgkmcnt(9)
	v_mfma_f32_32x32x16_bf16 v[0:15], v[64:67], v[160:163], v[0:15]
	v_exp_f32_e32 v220, v220
	ds_read_b128 v[156:159], v241 offset:12288
	s_waitcnt lgkmcnt(8)
	v_mfma_f32_32x32x16_bf16 v[0:15], v[68:71], v[164:167], v[0:15]
	v_exp_f32_e32 v221, v221
	ds_read_b128 v[160:163], v242 offset:0
	s_waitcnt lgkmcnt(7)
	v_mfma_f32_32x32x16_bf16 v[0:15], v[80:83], v[168:171], v[0:15]
	v_exp_f32_e32 v222, v222
	ds_read_b128 v[164:167], v242 offset:12288
	s_waitcnt lgkmcnt(6)
	v_mfma_f32_32x32x16_bf16 v[0:15], v[84:87], v[172:175], v[0:15]
	v_exp_f32_e32 v223, v223
	s_waitcnt vmcnt(5)
	s_barrier
	ds_read_b128 v[168:171], v243 offset:0
	s_waitcnt lgkmcnt(6)
	v_mfma_f32_32x32x16_bf16 v[64:79], v[144:147], v[96:99], 0
	v_exp_f32_e32 v224, v224
	v_add_f32_e32 v245, v208, v245
	v_exp_f32_e32 v225, v225
	ds_read_b128 v[172:175], v243 offset:12288
	s_waitcnt lgkmcnt(6)
	v_mfma_f32_32x32x16_bf16 v[80:95], v[148:151], v[96:99], 0
	v_add_f32_e32 v246, v209, v246
	v_exp_f32_e32 v226, v226
	v_add_f32_e32 v245, v210, v245
	ds_read_b128 v[144:147], v240 offset:128
	s_waitcnt lgkmcnt(6)
	v_mfma_f32_32x32x16_bf16 v[64:79], v[152:155], v[100:103], v[64:79]
	v_exp_f32_e32 v227, v227
	v_add_f32_e32 v246, v211, v246
	s_add_i32 m0, s60, 0xc000
	s_nop 0
	global_load_lds_dwordx4 v182, s[42:43]
	ds_read_b128 v[148:151], v240 offset:12416
	s_waitcnt lgkmcnt(6)
	v_mfma_f32_32x32x16_bf16 v[80:95], v[156:159], v[100:103], v[80:95]
	v_exp_f32_e32 v228, v228
	v_add_f32_e32 v245, v212, v245
	v_exp_f32_e32 v229, v229
	ds_read_b128 v[152:155], v241 offset:128
	s_waitcnt lgkmcnt(6)
	v_mfma_f32_32x32x16_bf16 v[64:79], v[160:163], v[104:107], v[64:79]
	v_add_f32_e32 v246, v213, v246
	v_exp_f32_e32 v230, v230
	v_add_f32_e32 v245, v214, v245
	ds_read_b128 v[156:159], v241 offset:12416
	s_waitcnt lgkmcnt(6)
	v_mfma_f32_32x32x16_bf16 v[80:95], v[164:167], v[104:107], v[80:95]
	v_exp_f32_e32 v231, v231
	v_add_f32_e32 v246, v215, v246
	s_add_i32 m0, s60, 0xc400
	s_nop 0
	global_load_lds_dwordx4 v183, s[42:43]
	ds_read_b128 v[160:163], v242 offset:128
	s_waitcnt lgkmcnt(6)
	v_mfma_f32_32x32x16_bf16 v[64:79], v[168:171], v[108:111], v[64:79]
	v_exp_f32_e32 v232, v232
	v_add_f32_e32 v245, v216, v245
	v_exp_f32_e32 v233, v233
	ds_read_b128 v[164:167], v242 offset:12416
	s_waitcnt lgkmcnt(6)
	v_mfma_f32_32x32x16_bf16 v[80:95], v[172:175], v[108:111], v[80:95]
	v_add_f32_e32 v246, v217, v246
	v_exp_f32_e32 v234, v234
	v_add_f32_e32 v245, v218, v245
	ds_read_b128 v[168:171], v243 offset:128
	s_waitcnt lgkmcnt(6)
	v_mfma_f32_32x32x16_bf16 v[64:79], v[144:147], v[112:115], v[64:79]
	v_exp_f32_e32 v235, v235
	v_add_f32_e32 v246, v219, v246
	s_add_i32 m0, s60, 0xc800
	s_nop 0
	global_load_lds_dwordx4 v184, s[42:43]
	ds_read_b128 v[172:175], v243 offset:12416
	s_waitcnt lgkmcnt(6)
	v_mfma_f32_32x32x16_bf16 v[80:95], v[148:151], v[112:115], v[80:95]
	v_exp_f32_e32 v236, v236
	v_add_f32_e32 v245, v220, v245
	v_exp_f32_e32 v237, v237
	ds_read_b128 v[144:147], v240 offset:256
	s_waitcnt lgkmcnt(6)
	v_mfma_f32_32x32x16_bf16 v[64:79], v[152:155], v[116:119], v[64:79]
	v_add_f32_e32 v246, v221, v246
	v_exp_f32_e32 v238, v238
	v_add_f32_e32 v245, v222, v245
	ds_read_b128 v[148:151], v240 offset:12544
	s_waitcnt lgkmcnt(6)
	v_mfma_f32_32x32x16_bf16 v[80:95], v[156:159], v[116:119], v[80:95]
	v_exp_f32_e32 v239, v239
	v_add_f32_e32 v246, v223, v246
	s_add_i32 m0, s61, 0x0
	s_nop 0
	global_load_lds_dwordx4 v185, s[46:47]
	ds_read_b128 v[152:155], v241 offset:256
	s_waitcnt lgkmcnt(6)
	v_mfma_f32_32x32x16_bf16 v[64:79], v[160:163], v[120:123], v[64:79]
	v_add_f32_e32 v245, v224, v245
	v_add_f32_e32 v246, v225, v246
	v_add_f32_e32 v245, v226, v245
	ds_read_b128 v[156:159], v241 offset:12544
	s_waitcnt lgkmcnt(6)
	v_mfma_f32_32x32x16_bf16 v[80:95], v[164:167], v[120:123], v[80:95]
	v_add_f32_e32 v246, v227, v246
	v_add_f32_e32 v245, v228, v245
	v_add_f32_e32 v246, v229, v246
	ds_read_b128 v[160:163], v242 offset:256
	s_waitcnt lgkmcnt(6)
	v_mfma_f32_32x32x16_bf16 v[64:79], v[168:171], v[124:127], v[64:79]
	v_add_f32_e32 v245, v230, v245
	v_add_f32_e32 v246, v231, v246
	s_add_i32 m0, s61, 0x400
	s_nop 0
	global_load_lds_dwordx4 v186, s[46:47]
	ds_read_b128 v[164:167], v242 offset:12544
	s_waitcnt lgkmcnt(6)
	v_mfma_f32_32x32x16_bf16 v[80:95], v[172:175], v[124:127], v[80:95]
	v_add_f32_e32 v245, v232, v245
	v_add_f32_e32 v246, v233, v246
	v_add_f32_e32 v245, v234, v245
	ds_read_b128 v[168:171], v243 offset:256
	s_waitcnt lgkmcnt(6)
	v_mfma_f32_32x32x16_bf16 v[64:79], v[144:147], v[128:131], v[64:79]
	v_add_f32_e32 v246, v235, v246
	v_add_f32_e32 v245, v236, v245
	v_add_f32_e32 v246, v237, v246
	ds_read_b128 v[172:175], v243 offset:12544
	s_waitcnt lgkmcnt(6)
	v_mfma_f32_32x32x16_bf16 v[80:95], v[148:151], v[128:131], v[80:95]
	v_add_f32_e32 v245, v238, v245
	v_add_f32_e32 v246, v239, v246
	s_add_u32 s42, s42, 0x6000
	s_addc_u32 s43, s43, 0
	v_add_u32_e32 v240, 0x6000, v240
	ds_read_b64_tr_b16 v[144:145], v244 offset:0
	ds_read_b64_tr_b16 v[146:147], v244 offset:2048
	s_waitcnt lgkmcnt(7)
	v_mfma_f32_32x32x16_bf16 v[64:79], v[152:155], v[132:135], v[64:79]
	v_cvt_pk_bf16_f32 v208, v208, v209
	v_cvt_pk_bf16_f32 v209, v210, v211
	v_cvt_pk_bf16_f32 v210, v212, v213
	v_add_u32_e32 v241, 0x6000, v241
	ds_read_b64_tr_b16 v[148:149], v244 offset:4096
	ds_read_b64_tr_b16 v[150:151], v244 offset:6144
	s_waitcnt lgkmcnt(8)
	v_mfma_f32_32x32x16_bf16 v[80:95], v[156:159], v[132:135], v[80:95]
	v_cvt_pk_bf16_f32 v211, v214, v215
	v_cvt_pk_bf16_f32 v212, v216, v217
	v_cvt_pk_bf16_f32 v213, v218, v219
	v_add_u32_e32 v242, 0x6000, v242
	ds_read_b64_tr_b16 v[152:153], v244 offset:8192
	ds_read_b64_tr_b16 v[154:155], v244 offset:10240
	s_waitcnt lgkmcnt(9)
	v_mfma_f32_32x32x16_bf16 v[64:79], v[160:163], v[136:139], v[64:79]
	v_cvt_pk_bf16_f32 v214, v220, v221
	v_cvt_pk_bf16_f32 v215, v222, v223
	s_add_u32 s46, s46, 0x40000
	s_addc_u32 s47, s47, 0
	v_add_u32_e32 v243, 0x6000, v243
	ds_read_b64_tr_b16 v[156:157], v244 offset:12288
	ds_read_b64_tr_b16 v[158:159], v244 offset:14336
	s_waitcnt lgkmcnt(10)
	v_mfma_f32_32x32x16_bf16 v[80:95], v[164:167], v[136:139], v[80:95]
	v_cvt_pk_bf16_f32 v224, v224, v225
	v_cvt_pk_bf16_f32 v225, v226, v227
	v_cvt_pk_bf16_f32 v226, v228, v229
	ds_read_b64_tr_b16 v[160:161], v244 offset:512
	ds_read_b64_tr_b16 v[162:163], v244 offset:2560
	s_waitcnt lgkmcnt(11)
	v_mfma_f32_32x32x16_bf16 v[64:79], v[168:171], v[140:143], v[64:79]
	v_cvt_pk_bf16_f32 v227, v230, v231
	v_cvt_pk_bf16_f32 v228, v232, v233
	v_cvt_pk_bf16_f32 v229, v234, v235
	ds_read_b64_tr_b16 v[164:165], v244 offset:4608
	ds_read_b64_tr_b16 v[166:167], v244 offset:6656
	s_waitcnt lgkmcnt(12)
	v_mfma_f32_32x32x16_bf16 v[80:95], v[172:175], v[140:143], v[80:95]
	v_cvt_pk_bf16_f32 v230, v236, v237
	v_cvt_pk_bf16_f32 v231, v238, v239
	ds_read_b64_tr_b16 v[168:169], v244 offset:8704
	ds_read_b64_tr_b16 v[170:171], v244 offset:10752
	s_waitcnt lgkmcnt(12)
	v_mfma_f32_32x32x16_bf16 v[48:63], v[208:211], v[144:147], v[48:63]
	ds_read_b64_tr_b16 v[172:173], v244 offset:12800
	ds_read_b64_tr_b16 v[174:175], v244 offset:14848
	s_waitcnt lgkmcnt(12)
	v_mfma_f32_32x32x16_bf16 v[48:63], v[212:215], v[148:151], v[48:63]
	ds_read_b64_tr_b16 v[144:145], v244 offset:1024
	ds_read_b64_tr_b16 v[146:147], v244 offset:3072
	s_waitcnt lgkmcnt(12)
	v_mfma_f32_32x32x16_bf16 v[48:63], v[224:227], v[152:155], v[48:63]
	v_exp_f32_e32 v64, v64
	v_exp_f32_e32 v65, v65
	ds_read_b64_tr_b16 v[148:149], v244 offset:5120
	ds_read_b64_tr_b16 v[150:151], v244 offset:7168
	s_waitcnt lgkmcnt(12)
	v_mfma_f32_32x32x16_bf16 v[48:63], v[228:231], v[156:159], v[48:63]
	v_exp_f32_e32 v66, v66
	v_exp_f32_e32 v67, v67
	ds_read_b64_tr_b16 v[152:153], v244 offset:9216
	ds_read_b64_tr_b16 v[154:155], v244 offset:11264
	s_waitcnt lgkmcnt(12)
	v_mfma_f32_32x32x16_bf16 v[32:47], v[208:211], v[160:163], v[32:47]
	v_exp_f32_e32 v68, v68
	ds_read_b64_tr_b16 v[156:157], v244 offset:13312
	ds_read_b64_tr_b16 v[158:159], v244 offset:15360
	s_waitcnt lgkmcnt(12)
	v_mfma_f32_32x32x16_bf16 v[32:47], v[212:215], v[164:167], v[32:47]
	v_exp_f32_e32 v69, v69
	ds_read_b64_tr_b16 v[160:161], v244 offset:1536
	ds_read_b64_tr_b16 v[162:163], v244 offset:3584
	s_waitcnt lgkmcnt(12)
	v_mfma_f32_32x32x16_bf16 v[32:47], v[224:227], v[168:171], v[32:47]
	v_exp_f32_e32 v70, v70
	ds_read_b64_tr_b16 v[164:165], v244 offset:5632
	ds_read_b64_tr_b16 v[166:167], v244 offset:7680
	s_waitcnt lgkmcnt(12)
	v_mfma_f32_32x32x16_bf16 v[32:47], v[228:231], v[172:175], v[32:47]
	v_exp_f32_e32 v71, v71
	ds_read_b64_tr_b16 v[168:169], v244 offset:9728
	ds_read_b64_tr_b16 v[170:171], v244 offset:11776
	s_waitcnt lgkmcnt(12)
	v_mfma_f32_32x32x16_bf16 v[16:31], v[208:211], v[144:147], v[16:31]
	v_exp_f32_e32 v72, v72
	ds_read_b64_tr_b16 v[172:173], v244 offset:13824
	ds_read_b64_tr_b16 v[174:175], v244 offset:15872
	s_waitcnt lgkmcnt(12)
	v_mfma_f32_32x32x16_bf16 v[16:31], v[212:215], v[148:151], v[16:31]
	v_exp_f32_e32 v73, v73
	v_add_u32_e32 v244, 0x4000, v244
	ds_read_b128 v[144:147], v240 offset:0
	s_waitcnt lgkmcnt(11)
	v_mfma_f32_32x32x16_bf16 v[16:31], v[224:227], v[152:155], v[16:31]
	v_exp_f32_e32 v74, v74
	ds_read_b128 v[148:151], v240 offset:12288
	s_waitcnt lgkmcnt(10)
	v_mfma_f32_32x32x16_bf16 v[16:31], v[228:231], v[156:159], v[16:31]
	v_exp_f32_e32 v75, v75
	ds_read_b128 v[152:155], v241 offset:0
	s_waitcnt lgkmcnt(9)
	v_mfma_f32_32x32x16_bf16 v[0:15], v[208:211], v[160:163], v[0:15]
	v_exp_f32_e32 v76, v76
	ds_read_b128 v[156:159], v241 offset:12288
	s_waitcnt lgkmcnt(8)
	v_mfma_f32_32x32x16_bf16 v[0:15], v[212:215], v[164:167], v[0:15]
	v_exp_f32_e32 v77, v77
	ds_read_b128 v[160:163], v242 offset:0
	s_waitcnt lgkmcnt(7)
	v_mfma_f32_32x32x16_bf16 v[0:15], v[224:227], v[168:171], v[0:15]
	v_exp_f32_e32 v78, v78
	ds_read_b128 v[164:167], v242 offset:12288
	s_waitcnt lgkmcnt(6)
	v_mfma_f32_32x32x16_bf16 v[0:15], v[228:231], v[172:175], v[0:15]
	v_exp_f32_e32 v79, v79
	s_waitcnt vmcnt(5)
	s_barrier
	ds_read_b128 v[168:171], v243 offset:0
	s_waitcnt lgkmcnt(6)
	v_mfma_f32_32x32x16_bf16 v[208:223], v[144:147], v[96:99], 0
	v_exp_f32_e32 v80, v80
	v_add_f32_e32 v245, v64, v245
	v_exp_f32_e32 v81, v81
	ds_read_b128 v[172:175], v243 offset:12288
	s_waitcnt lgkmcnt(6)
	v_mfma_f32_32x32x16_bf16 v[224:239], v[148:151], v[96:99], 0
	v_add_f32_e32 v246, v65, v246
	v_exp_f32_e32 v82, v82
	v_add_f32_e32 v245, v66, v245
	ds_read_b128 v[144:147], v240 offset:128
	s_waitcnt lgkmcnt(6)
	v_mfma_f32_32x32x16_bf16 v[208:223], v[152:155], v[100:103], v[208:223]
	v_exp_f32_e32 v83, v83
	v_add_f32_e32 v246, v67, v246
	s_add_i32 m0, s60, 0x12000
	s_nop 0
	global_load_lds_dwordx4 v182, s[42:43]
	ds_read_b128 v[148:151], v240 offset:12416
	s_waitcnt lgkmcnt(6)
	v_mfma_f32_32x32x16_bf16 v[224:239], v[156:159], v[100:103], v[224:239]
	v_exp_f32_e32 v84, v84
	v_add_f32_e32 v245, v68, v245
	v_exp_f32_e32 v85, v85
	ds_read_b128 v[152:155], v241 offset:128
	s_waitcnt lgkmcnt(6)
	v_mfma_f32_32x32x16_bf16 v[208:223], v[160:163], v[104:107], v[208:223]
	v_add_f32_e32 v246, v69, v246
	v_exp_f32_e32 v86, v86
	v_add_f32_e32 v245, v70, v245
	ds_read_b128 v[156:159], v241 offset:12416
	s_waitcnt lgkmcnt(6)
	v_mfma_f32_32x32x16_bf16 v[224:239], v[164:167], v[104:107], v[224:239]
	v_exp_f32_e32 v87, v87
	v_add_f32_e32 v246, v71, v246
	s_add_i32 m0, s60, 0x12400
	s_nop 0
	global_load_lds_dwordx4 v183, s[42:43]
	ds_read_b128 v[160:163], v242 offset:128
	s_waitcnt lgkmcnt(6)
	v_mfma_f32_32x32x16_bf16 v[208:223], v[168:171], v[108:111], v[208:223]
	v_exp_f32_e32 v88, v88
	v_add_f32_e32 v245, v72, v245
	v_exp_f32_e32 v89, v89
	ds_read_b128 v[164:167], v242 offset:12416
	s_waitcnt lgkmcnt(6)
	v_mfma_f32_32x32x16_bf16 v[224:239], v[172:175], v[108:111], v[224:239]
	v_add_f32_e32 v246, v73, v246
	v_exp_f32_e32 v90, v90
	v_add_f32_e32 v245, v74, v245
	ds_read_b128 v[168:171], v243 offset:128
	s_waitcnt lgkmcnt(6)
	v_mfma_f32_32x32x16_bf16 v[208:223], v[144:147], v[112:115], v[208:223]
	v_exp_f32_e32 v91, v91
	v_add_f32_e32 v246, v75, v246
	s_add_i32 m0, s60, 0x12800
	s_nop 0
	global_load_lds_dwordx4 v184, s[42:43]
	ds_read_b128 v[172:175], v243 offset:12416
	s_waitcnt lgkmcnt(6)
	v_mfma_f32_32x32x16_bf16 v[224:239], v[148:151], v[112:115], v[224:239]
	v_exp_f32_e32 v92, v92
	v_add_f32_e32 v245, v76, v245
	v_exp_f32_e32 v93, v93
	ds_read_b128 v[144:147], v240 offset:256
	s_waitcnt lgkmcnt(6)
	v_mfma_f32_32x32x16_bf16 v[208:223], v[152:155], v[116:119], v[208:223]
	v_add_f32_e32 v246, v77, v246
	v_exp_f32_e32 v94, v94
	v_add_f32_e32 v245, v78, v245
	ds_read_b128 v[148:151], v240 offset:12544
	s_waitcnt lgkmcnt(6)
	v_mfma_f32_32x32x16_bf16 v[224:239], v[156:159], v[116:119], v[224:239]
	v_exp_f32_e32 v95, v95
	v_add_f32_e32 v246, v79, v246
	s_add_i32 m0, s61, 0x4000
	s_nop 0
	global_load_lds_dwordx4 v185, s[46:47]
	ds_read_b128 v[152:155], v241 offset:256
	s_waitcnt lgkmcnt(6)
	v_mfma_f32_32x32x16_bf16 v[208:223], v[160:163], v[120:123], v[208:223]
	v_add_f32_e32 v245, v80, v245
	v_add_f32_e32 v246, v81, v246
	v_add_f32_e32 v245, v82, v245
	ds_read_b128 v[156:159], v241 offset:12544
	s_waitcnt lgkmcnt(6)
	v_mfma_f32_32x32x16_bf16 v[224:239], v[164:167], v[120:123], v[224:239]
	v_add_f32_e32 v246, v83, v246
	v_add_f32_e32 v245, v84, v245
	v_add_f32_e32 v246, v85, v246
	ds_read_b128 v[160:163], v242 offset:256
	s_waitcnt lgkmcnt(6)
	v_mfma_f32_32x32x16_bf16 v[208:223], v[168:171], v[124:127], v[208:223]
	v_add_f32_e32 v245, v86, v245
	v_add_f32_e32 v246, v87, v246
	s_add_i32 m0, s61, 0x4400
	s_nop 0
	global_load_lds_dwordx4 v186, s[46:47]
	ds_read_b128 v[164:167], v242 offset:12544
	s_waitcnt lgkmcnt(6)
	v_mfma_f32_32x32x16_bf16 v[224:239], v[172:175], v[124:127], v[224:239]
	v_add_f32_e32 v245, v88, v245
	v_add_f32_e32 v246, v89, v246
	v_add_f32_e32 v245, v90, v245
	ds_read_b128 v[168:171], v243 offset:256
	s_waitcnt lgkmcnt(6)
	v_mfma_f32_32x32x16_bf16 v[208:223], v[144:147], v[128:131], v[208:223]
	v_add_f32_e32 v246, v91, v246
	v_add_f32_e32 v245, v92, v245
	v_add_f32_e32 v246, v93, v246
	ds_read_b128 v[172:175], v243 offset:12544
	s_waitcnt lgkmcnt(6)
	v_mfma_f32_32x32x16_bf16 v[224:239], v[148:151], v[128:131], v[224:239]
	v_add_f32_e32 v245, v94, v245
	v_add_f32_e32 v246, v95, v246
	s_add_u32 s42, s42, 0x6000
	s_addc_u32 s43, s43, 0
	v_add_u32_e32 v240, 0x9010, v240
	ds_read_b64_tr_b16 v[144:145], v244 offset:0
	ds_read_b64_tr_b16 v[146:147], v244 offset:2048
	s_waitcnt lgkmcnt(7)
	v_mfma_f32_32x32x16_bf16 v[208:223], v[152:155], v[132:135], v[208:223]
	v_cvt_pk_bf16_f32 v64, v64, v65
	v_cvt_pk_bf16_f32 v65, v66, v67
	v_cvt_pk_bf16_f32 v66, v68, v69
	v_add_u32_e32 v241, 0x9010, v241
	ds_read_b64_tr_b16 v[148:149], v244 offset:4096
	ds_read_b64_tr_b16 v[150:151], v244 offset:6144
	s_waitcnt lgkmcnt(8)
	v_mfma_f32_32x32x16_bf16 v[224:239], v[156:159], v[132:135], v[224:239]
	v_cvt_pk_bf16_f32 v67, v70, v71
	v_cvt_pk_bf16_f32 v68, v72, v73
	v_cvt_pk_bf16_f32 v69, v74, v75
	v_add_u32_e32 v242, 0x9010, v242
	ds_read_b64_tr_b16 v[152:153], v244 offset:8192
	ds_read_b64_tr_b16 v[154:155], v244 offset:10240
	s_waitcnt lgkmcnt(9)
	v_mfma_f32_32x32x16_bf16 v[208:223], v[160:163], v[136:139], v[208:223]
	v_cvt_pk_bf16_f32 v70, v76, v77
	v_cvt_pk_bf16_f32 v71, v78, v79
	s_add_u32 s46, s46, 0x40000
	s_addc_u32 s47, s47, 0
	v_add_u32_e32 v243, 0x9010, v243
	ds_read_b64_tr_b16 v[156:157], v244 offset:12288
	ds_read_b64_tr_b16 v[158:159], v244 offset:14336
	s_waitcnt lgkmcnt(10)
	v_mfma_f32_32x32x16_bf16 v[224:239], v[164:167], v[136:139], v[224:239]
	v_cvt_pk_bf16_f32 v80, v80, v81
	v_cvt_pk_bf16_f32 v81, v82, v83
	v_cvt_pk_bf16_f32 v82, v84, v85
	ds_read_b64_tr_b16 v[160:161], v244 offset:512
	ds_read_b64_tr_b16 v[162:163], v244 offset:2560
	s_waitcnt lgkmcnt(11)
	v_mfma_f32_32x32x16_bf16 v[208:223], v[168:171], v[140:143], v[208:223]
	v_cvt_pk_bf16_f32 v83, v86, v87
	v_cvt_pk_bf16_f32 v84, v88, v89
	v_cvt_pk_bf16_f32 v85, v90, v91
	ds_read_b64_tr_b16 v[164:165], v244 offset:4608
	ds_read_b64_tr_b16 v[166:167], v244 offset:6656
	s_waitcnt lgkmcnt(12)
	v_mfma_f32_32x32x16_bf16 v[224:239], v[172:175], v[140:143], v[224:239]
	v_cvt_pk_bf16_f32 v86, v92, v93
	v_cvt_pk_bf16_f32 v87, v94, v95
	ds_read_b64_tr_b16 v[168:169], v244 offset:8704
	ds_read_b64_tr_b16 v[170:171], v244 offset:10752
	s_waitcnt lgkmcnt(12)
	v_mfma_f32_32x32x16_bf16 v[48:63], v[64:67], v[144:147], v[48:63]
	ds_read_b64_tr_b16 v[172:173], v244 offset:12800
	ds_read_b64_tr_b16 v[174:175], v244 offset:14848
	s_waitcnt lgkmcnt(12)
	v_mfma_f32_32x32x16_bf16 v[48:63], v[68:71], v[148:151], v[48:63]
	ds_read_b64_tr_b16 v[144:145], v244 offset:1024
	ds_read_b64_tr_b16 v[146:147], v244 offset:3072
	s_waitcnt lgkmcnt(12)
	v_mfma_f32_32x32x16_bf16 v[48:63], v[80:83], v[152:155], v[48:63]
	v_exp_f32_e32 v208, v208
	v_exp_f32_e32 v209, v209
	ds_read_b64_tr_b16 v[148:149], v244 offset:5120
	ds_read_b64_tr_b16 v[150:151], v244 offset:7168
	s_waitcnt lgkmcnt(12)
	v_mfma_f32_32x32x16_bf16 v[48:63], v[84:87], v[156:159], v[48:63]
	v_exp_f32_e32 v210, v210
	v_exp_f32_e32 v211, v211
	ds_read_b64_tr_b16 v[152:153], v244 offset:9216
	ds_read_b64_tr_b16 v[154:155], v244 offset:11264
	s_waitcnt lgkmcnt(12)
	v_mfma_f32_32x32x16_bf16 v[32:47], v[64:67], v[160:163], v[32:47]
	v_exp_f32_e32 v212, v212
	ds_read_b64_tr_b16 v[156:157], v244 offset:13312
	ds_read_b64_tr_b16 v[158:159], v244 offset:15360
	s_waitcnt lgkmcnt(12)
	v_mfma_f32_32x32x16_bf16 v[32:47], v[68:71], v[164:167], v[32:47]
	v_exp_f32_e32 v213, v213
	ds_read_b64_tr_b16 v[160:161], v244 offset:1536
	ds_read_b64_tr_b16 v[162:163], v244 offset:3584
	s_waitcnt lgkmcnt(12)
	v_mfma_f32_32x32x16_bf16 v[32:47], v[80:83], v[168:171], v[32:47]
	v_exp_f32_e32 v214, v214
	ds_read_b64_tr_b16 v[164:165], v244 offset:5632
	ds_read_b64_tr_b16 v[166:167], v244 offset:7680
	s_waitcnt lgkmcnt(12)
	v_mfma_f32_32x32x16_bf16 v[32:47], v[84:87], v[172:175], v[32:47]
	v_exp_f32_e32 v215, v215
	ds_read_b64_tr_b16 v[168:169], v244 offset:9728
	ds_read_b64_tr_b16 v[170:171], v244 offset:11776
	s_waitcnt lgkmcnt(12)
	v_mfma_f32_32x32x16_bf16 v[16:31], v[64:67], v[144:147], v[16:31]
	v_exp_f32_e32 v216, v216
	ds_read_b64_tr_b16 v[172:173], v244 offset:13824
	ds_read_b64_tr_b16 v[174:175], v244 offset:15872
	s_waitcnt lgkmcnt(12)
	v_mfma_f32_32x32x16_bf16 v[16:31], v[68:71], v[148:151], v[16:31]
	v_exp_f32_e32 v217, v217
	v_add_u32_e32 v244, 0xffff8000, v244
	ds_read_b128 v[144:147], v240 offset:0
	s_waitcnt lgkmcnt(11)
	v_mfma_f32_32x32x16_bf16 v[16:31], v[80:83], v[152:155], v[16:31]
	v_exp_f32_e32 v218, v218
	ds_read_b128 v[148:151], v240 offset:12288
	s_waitcnt lgkmcnt(10)
	v_mfma_f32_32x32x16_bf16 v[16:31], v[84:87], v[156:159], v[16:31]
	v_exp_f32_e32 v219, v219
	ds_read_b128 v[152:155], v241 offset:0
	s_waitcnt lgkmcnt(9)
	v_mfma_f32_32x32x16_bf16 v[0:15], v[64:67], v[160:163], v[0:15]
	v_exp_f32_e32 v220, v220
	ds_read_b128 v[156:159], v241 offset:12288
	s_waitcnt lgkmcnt(8)
	v_mfma_f32_32x32x16_bf16 v[0:15], v[68:71], v[164:167], v[0:15]
	v_exp_f32_e32 v221, v221
	ds_read_b128 v[160:163], v242 offset:0
	s_waitcnt lgkmcnt(7)
	v_mfma_f32_32x32x16_bf16 v[0:15], v[80:83], v[168:171], v[0:15]
	v_exp_f32_e32 v222, v222
	ds_read_b128 v[164:167], v242 offset:12288
	s_waitcnt lgkmcnt(6)
	v_mfma_f32_32x32x16_bf16 v[0:15], v[84:87], v[172:175], v[0:15]
	v_exp_f32_e32 v223, v223
	s_waitcnt vmcnt(5)
	s_barrier
	ds_read_b128 v[168:171], v243 offset:0
	s_waitcnt lgkmcnt(6)
	v_mfma_f32_32x32x16_bf16 v[64:79], v[144:147], v[96:99], 0
	v_exp_f32_e32 v224, v224
	v_add_f32_e32 v245, v208, v245
	v_exp_f32_e32 v225, v225
	ds_read_b128 v[172:175], v243 offset:12288
	s_waitcnt lgkmcnt(6)
	v_mfma_f32_32x32x16_bf16 v[80:95], v[148:151], v[96:99], 0
	v_add_f32_e32 v246, v209, v246
	v_exp_f32_e32 v226, v226
	v_add_f32_e32 v245, v210, v245
	ds_read_b128 v[144:147], v240 offset:128
	s_waitcnt lgkmcnt(6)
	v_mfma_f32_32x32x16_bf16 v[64:79], v[152:155], v[100:103], v[64:79]
	v_exp_f32_e32 v227, v227
	v_add_f32_e32 v246, v211, v246
	s_add_i32 m0, s60, 0x18000
	s_nop 0
	global_load_lds_dwordx4 v182, s[42:43]
	ds_read_b128 v[148:151], v240 offset:12416
	s_waitcnt lgkmcnt(6)
	v_mfma_f32_32x32x16_bf16 v[80:95], v[156:159], v[100:103], v[80:95]
	v_exp_f32_e32 v228, v228
	v_add_f32_e32 v245, v212, v245
	v_exp_f32_e32 v229, v229
	ds_read_b128 v[152:155], v241 offset:128
	s_waitcnt lgkmcnt(6)
	v_mfma_f32_32x32x16_bf16 v[64:79], v[160:163], v[104:107], v[64:79]
	v_add_f32_e32 v246, v213, v246
	v_exp_f32_e32 v230, v230
	v_add_f32_e32 v245, v214, v245
	ds_read_b128 v[156:159], v241 offset:12416
	s_waitcnt lgkmcnt(6)
	v_mfma_f32_32x32x16_bf16 v[80:95], v[164:167], v[104:107], v[80:95]
	v_exp_f32_e32 v231, v231
	v_add_f32_e32 v246, v215, v246
	s_add_i32 m0, s60, 0x18400
	s_nop 0
	global_load_lds_dwordx4 v183, s[42:43]
	ds_read_b128 v[160:163], v242 offset:128
	s_waitcnt lgkmcnt(6)
	v_mfma_f32_32x32x16_bf16 v[64:79], v[168:171], v[108:111], v[64:79]
	v_exp_f32_e32 v232, v232
	v_add_f32_e32 v245, v216, v245
	v_exp_f32_e32 v233, v233
	ds_read_b128 v[164:167], v242 offset:12416
	s_waitcnt lgkmcnt(6)
	v_mfma_f32_32x32x16_bf16 v[80:95], v[172:175], v[108:111], v[80:95]
	v_add_f32_e32 v246, v217, v246
	v_exp_f32_e32 v234, v234
	v_add_f32_e32 v245, v218, v245
	ds_read_b128 v[168:171], v243 offset:128
	s_waitcnt lgkmcnt(6)
	v_mfma_f32_32x32x16_bf16 v[64:79], v[144:147], v[112:115], v[64:79]
	v_exp_f32_e32 v235, v235
	v_add_f32_e32 v246, v219, v246
	s_add_i32 m0, s60, 0x18800
	s_nop 0
	global_load_lds_dwordx4 v184, s[42:43]
	ds_read_b128 v[172:175], v243 offset:12416
	s_waitcnt lgkmcnt(6)
	v_mfma_f32_32x32x16_bf16 v[80:95], v[148:151], v[112:115], v[80:95]
	v_exp_f32_e32 v236, v236
	v_add_f32_e32 v245, v220, v245
	v_exp_f32_e32 v237, v237
	ds_read_b128 v[144:147], v240 offset:256
	s_waitcnt lgkmcnt(6)
	v_mfma_f32_32x32x16_bf16 v[64:79], v[152:155], v[116:119], v[64:79]
	v_add_f32_e32 v246, v221, v246
	v_exp_f32_e32 v238, v238
	v_add_f32_e32 v245, v222, v245
	ds_read_b128 v[148:151], v240 offset:12544
	s_waitcnt lgkmcnt(6)
	v_mfma_f32_32x32x16_bf16 v[80:95], v[156:159], v[116:119], v[80:95]
	v_exp_f32_e32 v239, v239
	v_add_f32_e32 v246, v223, v246
	s_add_i32 m0, s61, 0x8000
	s_nop 0
	global_load_lds_dwordx4 v185, s[46:47]
	ds_read_b128 v[152:155], v241 offset:256
	s_waitcnt lgkmcnt(6)
	v_mfma_f32_32x32x16_bf16 v[64:79], v[160:163], v[120:123], v[64:79]
	v_add_f32_e32 v245, v224, v245
	v_add_f32_e32 v246, v225, v246
	v_add_f32_e32 v245, v226, v245
	ds_read_b128 v[156:159], v241 offset:12544
	s_waitcnt lgkmcnt(6)
	v_mfma_f32_32x32x16_bf16 v[80:95], v[164:167], v[120:123], v[80:95]
	v_add_f32_e32 v246, v227, v246
	v_add_f32_e32 v245, v228, v245
	v_add_f32_e32 v246, v229, v246
	ds_read_b128 v[160:163], v242 offset:256
	s_waitcnt lgkmcnt(6)
	v_mfma_f32_32x32x16_bf16 v[64:79], v[168:171], v[124:127], v[64:79]
	v_add_f32_e32 v245, v230, v245
	v_add_f32_e32 v246, v231, v246
	s_add_i32 m0, s61, 0x8400
	s_nop 0
	global_load_lds_dwordx4 v186, s[46:47]
	ds_read_b128 v[164:167], v242 offset:12544
	s_waitcnt lgkmcnt(6)
	v_mfma_f32_32x32x16_bf16 v[80:95], v[172:175], v[124:127], v[80:95]
	v_add_f32_e32 v245, v232, v245
	v_add_f32_e32 v246, v233, v246
	v_add_f32_e32 v245, v234, v245
	ds_read_b128 v[168:171], v243 offset:256
	s_waitcnt lgkmcnt(6)
	v_mfma_f32_32x32x16_bf16 v[64:79], v[144:147], v[128:131], v[64:79]
	v_add_f32_e32 v246, v235, v246
	v_add_f32_e32 v245, v236, v245
	v_add_f32_e32 v246, v237, v246
	ds_read_b128 v[172:175], v243 offset:12544
	s_waitcnt lgkmcnt(6)
	v_mfma_f32_32x32x16_bf16 v[80:95], v[148:151], v[128:131], v[80:95]
	v_add_f32_e32 v245, v238, v245
	v_add_f32_e32 v246, v239, v246
	s_add_u32 s42, s42, 0x6000
	s_addc_u32 s43, s43, 0
	v_add_u32_e32 v240, 0xfffeaff0, v240
	ds_read_b64_tr_b16 v[144:145], v244 offset:0
	ds_read_b64_tr_b16 v[146:147], v244 offset:2048
	s_waitcnt lgkmcnt(7)
	v_mfma_f32_32x32x16_bf16 v[64:79], v[152:155], v[132:135], v[64:79]
	v_cvt_pk_bf16_f32 v208, v208, v209
	v_cvt_pk_bf16_f32 v209, v210, v211
	v_cvt_pk_bf16_f32 v210, v212, v213
	v_add_u32_e32 v241, 0xfffeaff0, v241
	ds_read_b64_tr_b16 v[148:149], v244 offset:4096
	ds_read_b64_tr_b16 v[150:151], v244 offset:6144
	s_waitcnt lgkmcnt(8)
	v_mfma_f32_32x32x16_bf16 v[80:95], v[156:159], v[132:135], v[80:95]
	v_cvt_pk_bf16_f32 v211, v214, v215
	v_cvt_pk_bf16_f32 v212, v216, v217
	v_cvt_pk_bf16_f32 v213, v218, v219
	v_add_u32_e32 v242, 0xfffeaff0, v242
	ds_read_b64_tr_b16 v[152:153], v244 offset:8192
	ds_read_b64_tr_b16 v[154:155], v244 offset:10240
	s_waitcnt lgkmcnt(9)
	v_mfma_f32_32x32x16_bf16 v[64:79], v[160:163], v[136:139], v[64:79]
	v_cvt_pk_bf16_f32 v214, v220, v221
	v_cvt_pk_bf16_f32 v215, v222, v223
	s_add_u32 s46, s46, 0x40000
	s_addc_u32 s47, s47, 0
	v_add_u32_e32 v243, 0xfffeaff0, v243
	ds_read_b64_tr_b16 v[156:157], v244 offset:12288
	ds_read_b64_tr_b16 v[158:159], v244 offset:14336
	s_waitcnt lgkmcnt(10)
	v_mfma_f32_32x32x16_bf16 v[80:95], v[164:167], v[136:139], v[80:95]
	v_cvt_pk_bf16_f32 v224, v224, v225
	v_cvt_pk_bf16_f32 v225, v226, v227
	v_cvt_pk_bf16_f32 v226, v228, v229
	ds_read_b64_tr_b16 v[160:161], v244 offset:512
	ds_read_b64_tr_b16 v[162:163], v244 offset:2560
	s_waitcnt lgkmcnt(11)
	v_mfma_f32_32x32x16_bf16 v[64:79], v[168:171], v[140:143], v[64:79]
	v_cvt_pk_bf16_f32 v227, v230, v231
	v_cvt_pk_bf16_f32 v228, v232, v233
	v_cvt_pk_bf16_f32 v229, v234, v235
	ds_read_b64_tr_b16 v[164:165], v244 offset:4608
	ds_read_b64_tr_b16 v[166:167], v244 offset:6656
	s_waitcnt lgkmcnt(12)
	v_mfma_f32_32x32x16_bf16 v[80:95], v[172:175], v[140:143], v[80:95]
	v_cvt_pk_bf16_f32 v230, v236, v237
	v_cvt_pk_bf16_f32 v231, v238, v239
	ds_read_b64_tr_b16 v[168:169], v244 offset:8704
	ds_read_b64_tr_b16 v[170:171], v244 offset:10752
	s_waitcnt lgkmcnt(12)
	v_mfma_f32_32x32x16_bf16 v[48:63], v[208:211], v[144:147], v[48:63]
	ds_read_b64_tr_b16 v[172:173], v244 offset:12800
	ds_read_b64_tr_b16 v[174:175], v244 offset:14848
	s_waitcnt lgkmcnt(12)
	v_mfma_f32_32x32x16_bf16 v[48:63], v[212:215], v[148:151], v[48:63]
	ds_read_b64_tr_b16 v[144:145], v244 offset:1024
	ds_read_b64_tr_b16 v[146:147], v244 offset:3072
	s_waitcnt lgkmcnt(12)
	v_mfma_f32_32x32x16_bf16 v[48:63], v[224:227], v[152:155], v[48:63]
	v_exp_f32_e32 v64, v64
	v_exp_f32_e32 v65, v65
	ds_read_b64_tr_b16 v[148:149], v244 offset:5120
	ds_read_b64_tr_b16 v[150:151], v244 offset:7168
	s_waitcnt lgkmcnt(12)
	v_mfma_f32_32x32x16_bf16 v[48:63], v[228:231], v[156:159], v[48:63]
	v_exp_f32_e32 v66, v66
	v_exp_f32_e32 v67, v67
	ds_read_b64_tr_b16 v[152:153], v244 offset:9216
	ds_read_b64_tr_b16 v[154:155], v244 offset:11264
	s_waitcnt lgkmcnt(12)
	v_mfma_f32_32x32x16_bf16 v[32:47], v[208:211], v[160:163], v[32:47]
	v_exp_f32_e32 v68, v68
	ds_read_b64_tr_b16 v[156:157], v244 offset:13312
	ds_read_b64_tr_b16 v[158:159], v244 offset:15360
	s_waitcnt lgkmcnt(12)
	v_mfma_f32_32x32x16_bf16 v[32:47], v[212:215], v[164:167], v[32:47]
	v_exp_f32_e32 v69, v69
	ds_read_b64_tr_b16 v[160:161], v244 offset:1536
	ds_read_b64_tr_b16 v[162:163], v244 offset:3584
	s_waitcnt lgkmcnt(12)
	v_mfma_f32_32x32x16_bf16 v[32:47], v[224:227], v[168:171], v[32:47]
	v_exp_f32_e32 v70, v70
	ds_read_b64_tr_b16 v[164:165], v244 offset:5632
	ds_read_b64_tr_b16 v[166:167], v244 offset:7680
	s_waitcnt lgkmcnt(12)
	v_mfma_f32_32x32x16_bf16 v[32:47], v[228:231], v[172:175], v[32:47]
	v_exp_f32_e32 v71, v71
	ds_read_b64_tr_b16 v[168:169], v244 offset:9728
	ds_read_b64_tr_b16 v[170:171], v244 offset:11776
	s_waitcnt lgkmcnt(12)
	v_mfma_f32_32x32x16_bf16 v[16:31], v[208:211], v[144:147], v[16:31]
	v_exp_f32_e32 v72, v72
	ds_read_b64_tr_b16 v[172:173], v244 offset:13824
	ds_read_b64_tr_b16 v[174:175], v244 offset:15872
	s_waitcnt lgkmcnt(12)
	v_mfma_f32_32x32x16_bf16 v[16:31], v[212:215], v[148:151], v[16:31]
	v_exp_f32_e32 v73, v73
	v_add_u32_e32 v244, 0x4000, v244
	ds_read_b128 v[144:147], v240 offset:0
	s_waitcnt lgkmcnt(11)
	v_mfma_f32_32x32x16_bf16 v[16:31], v[224:227], v[152:155], v[16:31]
	v_exp_f32_e32 v74, v74
	ds_read_b128 v[148:151], v240 offset:12288
	s_waitcnt lgkmcnt(10)
	v_mfma_f32_32x32x16_bf16 v[16:31], v[228:231], v[156:159], v[16:31]
	v_exp_f32_e32 v75, v75
	ds_read_b128 v[152:155], v241 offset:0
	s_waitcnt lgkmcnt(9)
	v_mfma_f32_32x32x16_bf16 v[0:15], v[208:211], v[160:163], v[0:15]
	v_exp_f32_e32 v76, v76
	ds_read_b128 v[156:159], v241 offset:12288
	s_waitcnt lgkmcnt(8)
	v_mfma_f32_32x32x16_bf16 v[0:15], v[212:215], v[164:167], v[0:15]
	v_exp_f32_e32 v77, v77
	ds_read_b128 v[160:163], v242 offset:0
	s_waitcnt lgkmcnt(7)
	v_mfma_f32_32x32x16_bf16 v[0:15], v[224:227], v[168:171], v[0:15]
	v_exp_f32_e32 v78, v78
	ds_read_b128 v[164:167], v242 offset:12288
	s_waitcnt lgkmcnt(6)
	v_mfma_f32_32x32x16_bf16 v[0:15], v[228:231], v[172:175], v[0:15]
	v_exp_f32_e32 v79, v79
	s_waitcnt vmcnt(5)
	s_barrier
	ds_read_b128 v[168:171], v243 offset:0
	s_waitcnt lgkmcnt(6)
	v_mfma_f32_32x32x16_bf16 v[208:223], v[144:147], v[96:99], 0
	v_exp_f32_e32 v80, v80
	v_add_f32_e32 v245, v64, v245
	v_exp_f32_e32 v81, v81
	ds_read_b128 v[172:175], v243 offset:12288
	s_waitcnt lgkmcnt(6)
	v_mfma_f32_32x32x16_bf16 v[224:239], v[148:151], v[96:99], 0
	v_add_f32_e32 v246, v65, v246
	v_exp_f32_e32 v82, v82
	v_add_f32_e32 v245, v66, v245
	ds_read_b128 v[144:147], v240 offset:128
	s_waitcnt lgkmcnt(6)
	v_mfma_f32_32x32x16_bf16 v[208:223], v[152:155], v[100:103], v[208:223]
	v_exp_f32_e32 v83, v83
	v_add_f32_e32 v246, v67, v246
	s_add_i32 m0, s60, 0x21010
	s_nop 0
	global_load_lds_dwordx4 v182, s[42:43]
	ds_read_b128 v[148:151], v240 offset:12416
	s_waitcnt lgkmcnt(6)
	v_mfma_f32_32x32x16_bf16 v[224:239], v[156:159], v[100:103], v[224:239]
	v_exp_f32_e32 v84, v84
	v_add_f32_e32 v245, v68, v245
	v_exp_f32_e32 v85, v85
	ds_read_b128 v[152:155], v241 offset:128
	s_waitcnt lgkmcnt(6)
	v_mfma_f32_32x32x16_bf16 v[208:223], v[160:163], v[104:107], v[208:223]
	v_add_f32_e32 v246, v69, v246
	v_exp_f32_e32 v86, v86
	v_add_f32_e32 v245, v70, v245
	ds_read_b128 v[156:159], v241 offset:12416
	s_waitcnt lgkmcnt(6)
	v_mfma_f32_32x32x16_bf16 v[224:239], v[164:167], v[104:107], v[224:239]
	v_exp_f32_e32 v87, v87
	v_add_f32_e32 v246, v71, v246
	s_add_i32 m0, s60, 0x21410
	s_nop 0
	global_load_lds_dwordx4 v183, s[42:43]
	ds_read_b128 v[160:163], v242 offset:128
	s_waitcnt lgkmcnt(6)
	v_mfma_f32_32x32x16_bf16 v[208:223], v[168:171], v[108:111], v[208:223]
	v_exp_f32_e32 v88, v88
	v_add_f32_e32 v245, v72, v245
	v_exp_f32_e32 v89, v89
	ds_read_b128 v[164:167], v242 offset:12416
	s_waitcnt lgkmcnt(6)
	v_mfma_f32_32x32x16_bf16 v[224:239], v[172:175], v[108:111], v[224:239]
	v_add_f32_e32 v246, v73, v246
	v_exp_f32_e32 v90, v90
	v_add_f32_e32 v245, v74, v245
	ds_read_b128 v[168:171], v243 offset:128
	s_waitcnt lgkmcnt(6)
	v_mfma_f32_32x32x16_bf16 v[208:223], v[144:147], v[112:115], v[208:223]
	v_exp_f32_e32 v91, v91
	v_add_f32_e32 v246, v75, v246
	s_add_i32 m0, s60, 0x21810
	s_nop 0
	global_load_lds_dwordx4 v184, s[42:43]
	ds_read_b128 v[172:175], v243 offset:12416
	s_waitcnt lgkmcnt(6)
	v_mfma_f32_32x32x16_bf16 v[224:239], v[148:151], v[112:115], v[224:239]
	v_exp_f32_e32 v92, v92
	v_add_f32_e32 v245, v76, v245
	v_exp_f32_e32 v93, v93
	ds_read_b128 v[144:147], v240 offset:256
	s_waitcnt lgkmcnt(6)
	v_mfma_f32_32x32x16_bf16 v[208:223], v[152:155], v[116:119], v[208:223]
	v_add_f32_e32 v246, v77, v246
	v_exp_f32_e32 v94, v94
	v_add_f32_e32 v245, v78, v245
	ds_read_b128 v[148:151], v240 offset:12544
	s_waitcnt lgkmcnt(6)
	v_mfma_f32_32x32x16_bf16 v[224:239], v[156:159], v[116:119], v[224:239]
	v_exp_f32_e32 v95, v95
	v_add_f32_e32 v246, v79, v246
	s_add_i32 m0, s61, 0x0
	s_nop 0
	global_load_lds_dwordx4 v185, s[46:47]
	ds_read_b128 v[152:155], v241 offset:256
	s_waitcnt lgkmcnt(6)
	v_mfma_f32_32x32x16_bf16 v[208:223], v[160:163], v[120:123], v[208:223]
	v_add_f32_e32 v245, v80, v245
	v_add_f32_e32 v246, v81, v246
	v_add_f32_e32 v245, v82, v245
	ds_read_b128 v[156:159], v241 offset:12544
	s_waitcnt lgkmcnt(6)
	v_mfma_f32_32x32x16_bf16 v[224:239], v[164:167], v[120:123], v[224:239]
	v_add_f32_e32 v246, v83, v246
	v_add_f32_e32 v245, v84, v245
	v_add_f32_e32 v246, v85, v246
	ds_read_b128 v[160:163], v242 offset:256
	s_waitcnt lgkmcnt(6)
	v_mfma_f32_32x32x16_bf16 v[208:223], v[168:171], v[124:127], v[208:223]
	v_add_f32_e32 v245, v86, v245
	v_add_f32_e32 v246, v87, v246
	s_add_i32 m0, s61, 0x400
	s_nop 0
	global_load_lds_dwordx4 v186, s[46:47]
	ds_read_b128 v[164:167], v242 offset:12544
	s_waitcnt lgkmcnt(6)
	v_mfma_f32_32x32x16_bf16 v[224:239], v[172:175], v[124:127], v[224:239]
	v_add_f32_e32 v245, v88, v245
	v_add_f32_e32 v246, v89, v246
	v_add_f32_e32 v245, v90, v245
	ds_read_b128 v[168:171], v243 offset:256
	s_waitcnt lgkmcnt(6)
	v_mfma_f32_32x32x16_bf16 v[208:223], v[144:147], v[128:131], v[208:223]
	v_add_f32_e32 v246, v91, v246
	v_add_f32_e32 v245, v92, v245
	v_add_f32_e32 v246, v93, v246
	ds_read_b128 v[172:175], v243 offset:12544
	s_waitcnt lgkmcnt(6)
	v_mfma_f32_32x32x16_bf16 v[224:239], v[148:151], v[128:131], v[224:239]
	v_add_f32_e32 v245, v94, v245
	v_add_f32_e32 v246, v95, v246
	s_add_u32 s42, s42, 0x6000
	s_addc_u32 s43, s43, 0
	v_add_u32_e32 v240, 0x6000, v240
	ds_read_b64_tr_b16 v[144:145], v244 offset:0
	ds_read_b64_tr_b16 v[146:147], v244 offset:2048
	s_waitcnt lgkmcnt(7)
	v_mfma_f32_32x32x16_bf16 v[208:223], v[152:155], v[132:135], v[208:223]
	v_cvt_pk_bf16_f32 v64, v64, v65
	v_cvt_pk_bf16_f32 v65, v66, v67
	v_cvt_pk_bf16_f32 v66, v68, v69
	v_add_u32_e32 v241, 0x6000, v241
	ds_read_b64_tr_b16 v[148:149], v244 offset:4096
	ds_read_b64_tr_b16 v[150:151], v244 offset:6144
	s_waitcnt lgkmcnt(8)
	v_mfma_f32_32x32x16_bf16 v[224:239], v[156:159], v[132:135], v[224:239]
	v_cvt_pk_bf16_f32 v67, v70, v71
	v_cvt_pk_bf16_f32 v68, v72, v73
	v_cvt_pk_bf16_f32 v69, v74, v75
	v_add_u32_e32 v242, 0x6000, v242
	ds_read_b64_tr_b16 v[152:153], v244 offset:8192
	ds_read_b64_tr_b16 v[154:155], v244 offset:10240
	s_waitcnt lgkmcnt(9)
	v_mfma_f32_32x32x16_bf16 v[208:223], v[160:163], v[136:139], v[208:223]
	v_cvt_pk_bf16_f32 v70, v76, v77
	v_cvt_pk_bf16_f32 v71, v78, v79
	s_add_u32 s46, s46, 0x40000
	s_addc_u32 s47, s47, 0
	v_add_u32_e32 v243, 0x6000, v243
	ds_read_b64_tr_b16 v[156:157], v244 offset:12288
	ds_read_b64_tr_b16 v[158:159], v244 offset:14336
	s_waitcnt lgkmcnt(10)
	v_mfma_f32_32x32x16_bf16 v[224:239], v[164:167], v[136:139], v[224:239]
	v_cvt_pk_bf16_f32 v80, v80, v81
	v_cvt_pk_bf16_f32 v81, v82, v83
	v_cvt_pk_bf16_f32 v82, v84, v85
	ds_read_b64_tr_b16 v[160:161], v244 offset:512
	ds_read_b64_tr_b16 v[162:163], v244 offset:2560
	s_waitcnt lgkmcnt(11)
	v_mfma_f32_32x32x16_bf16 v[208:223], v[168:171], v[140:143], v[208:223]
	v_cvt_pk_bf16_f32 v83, v86, v87
	v_cvt_pk_bf16_f32 v84, v88, v89
	v_cvt_pk_bf16_f32 v85, v90, v91
	ds_read_b64_tr_b16 v[164:165], v244 offset:4608
	ds_read_b64_tr_b16 v[166:167], v244 offset:6656
	s_waitcnt lgkmcnt(12)
	v_mfma_f32_32x32x16_bf16 v[224:239], v[172:175], v[140:143], v[224:239]
	v_cvt_pk_bf16_f32 v86, v92, v93
	v_cvt_pk_bf16_f32 v87, v94, v95
	ds_read_b64_tr_b16 v[168:169], v244 offset:8704
	ds_read_b64_tr_b16 v[170:171], v244 offset:10752
	s_waitcnt lgkmcnt(12)
	v_mfma_f32_32x32x16_bf16 v[48:63], v[64:67], v[144:147], v[48:63]
	ds_read_b64_tr_b16 v[172:173], v244 offset:12800
	ds_read_b64_tr_b16 v[174:175], v244 offset:14848
	s_waitcnt lgkmcnt(12)
	v_mfma_f32_32x32x16_bf16 v[48:63], v[68:71], v[148:151], v[48:63]
	ds_read_b64_tr_b16 v[144:145], v244 offset:1024
	ds_read_b64_tr_b16 v[146:147], v244 offset:3072
	s_waitcnt lgkmcnt(12)
	v_mfma_f32_32x32x16_bf16 v[48:63], v[80:83], v[152:155], v[48:63]
	v_exp_f32_e32 v208, v208
	v_exp_f32_e32 v209, v209
	ds_read_b64_tr_b16 v[148:149], v244 offset:5120
	ds_read_b64_tr_b16 v[150:151], v244 offset:7168
	s_waitcnt lgkmcnt(12)
	v_mfma_f32_32x32x16_bf16 v[48:63], v[84:87], v[156:159], v[48:63]
	v_exp_f32_e32 v210, v210
	v_exp_f32_e32 v211, v211
	ds_read_b64_tr_b16 v[152:153], v244 offset:9216
	ds_read_b64_tr_b16 v[154:155], v244 offset:11264
	s_waitcnt lgkmcnt(12)
	v_mfma_f32_32x32x16_bf16 v[32:47], v[64:67], v[160:163], v[32:47]
	v_exp_f32_e32 v212, v212
	ds_read_b64_tr_b16 v[156:157], v244 offset:13312
	ds_read_b64_tr_b16 v[158:159], v244 offset:15360
	s_waitcnt lgkmcnt(12)
	v_mfma_f32_32x32x16_bf16 v[32:47], v[68:71], v[164:167], v[32:47]
	v_exp_f32_e32 v213, v213
	ds_read_b64_tr_b16 v[160:161], v244 offset:1536
	ds_read_b64_tr_b16 v[162:163], v244 offset:3584
	s_waitcnt lgkmcnt(12)
	v_mfma_f32_32x32x16_bf16 v[32:47], v[80:83], v[168:171], v[32:47]
	v_exp_f32_e32 v214, v214
	ds_read_b64_tr_b16 v[164:165], v244 offset:5632
	ds_read_b64_tr_b16 v[166:167], v244 offset:7680
	s_waitcnt lgkmcnt(12)
	v_mfma_f32_32x32x16_bf16 v[32:47], v[84:87], v[172:175], v[32:47]
	v_exp_f32_e32 v215, v215
	ds_read_b64_tr_b16 v[168:169], v244 offset:9728
	ds_read_b64_tr_b16 v[170:171], v244 offset:11776
	s_waitcnt lgkmcnt(12)
	v_mfma_f32_32x32x16_bf16 v[16:31], v[64:67], v[144:147], v[16:31]
	v_exp_f32_e32 v216, v216
	ds_read_b64_tr_b16 v[172:173], v244 offset:13824
	ds_read_b64_tr_b16 v[174:175], v244 offset:15872
	s_waitcnt lgkmcnt(12)
	v_mfma_f32_32x32x16_bf16 v[16:31], v[68:71], v[148:151], v[16:31]
	v_exp_f32_e32 v217, v217
	v_add_u32_e32 v244, 0x4000, v244
	ds_read_b128 v[144:147], v240 offset:0
	s_waitcnt lgkmcnt(11)
	v_mfma_f32_32x32x16_bf16 v[16:31], v[80:83], v[152:155], v[16:31]
	v_exp_f32_e32 v218, v218
	ds_read_b128 v[148:151], v240 offset:12288
	s_waitcnt lgkmcnt(10)
	v_mfma_f32_32x32x16_bf16 v[16:31], v[84:87], v[156:159], v[16:31]
	v_exp_f32_e32 v219, v219
	ds_read_b128 v[152:155], v241 offset:0
	s_waitcnt lgkmcnt(9)
	v_mfma_f32_32x32x16_bf16 v[0:15], v[64:67], v[160:163], v[0:15]
	v_exp_f32_e32 v220, v220
	ds_read_b128 v[156:159], v241 offset:12288
	s_waitcnt lgkmcnt(8)
	v_mfma_f32_32x32x16_bf16 v[0:15], v[68:71], v[164:167], v[0:15]
	v_exp_f32_e32 v221, v221
	ds_read_b128 v[160:163], v242 offset:0
	s_waitcnt lgkmcnt(7)
	v_mfma_f32_32x32x16_bf16 v[0:15], v[80:83], v[168:171], v[0:15]
	v_exp_f32_e32 v222, v222
	ds_read_b128 v[164:167], v242 offset:12288
	s_waitcnt lgkmcnt(6)
	v_mfma_f32_32x32x16_bf16 v[0:15], v[84:87], v[172:175], v[0:15]
	v_exp_f32_e32 v223, v223
	s_waitcnt vmcnt(5)
	s_barrier
	ds_read_b128 v[168:171], v243 offset:0
	s_waitcnt lgkmcnt(6)
	v_mfma_f32_32x32x16_bf16 v[64:79], v[144:147], v[96:99], 0
	v_exp_f32_e32 v224, v224
	v_add_f32_e32 v245, v208, v245
	v_exp_f32_e32 v225, v225
	ds_read_b128 v[172:175], v243 offset:12288
	s_waitcnt lgkmcnt(6)
	v_mfma_f32_32x32x16_bf16 v[80:95], v[148:151], v[96:99], 0
	v_add_f32_e32 v246, v209, v246
	v_exp_f32_e32 v226, v226
	v_add_f32_e32 v245, v210, v245
	ds_read_b128 v[144:147], v240 offset:128
	s_waitcnt lgkmcnt(6)
	v_mfma_f32_32x32x16_bf16 v[64:79], v[152:155], v[100:103], v[64:79]
	v_exp_f32_e32 v227, v227
	v_add_f32_e32 v246, v211, v246
	s_add_i32 m0, s60, 0xc000
	s_nop 0
	global_load_lds_dwordx4 v182, s[42:43]
	ds_read_b128 v[148:151], v240 offset:12416
	s_waitcnt lgkmcnt(6)
	v_mfma_f32_32x32x16_bf16 v[80:95], v[156:159], v[100:103], v[80:95]
	v_exp_f32_e32 v228, v228
	v_add_f32_e32 v245, v212, v245
	v_exp_f32_e32 v229, v229
	ds_read_b128 v[152:155], v241 offset:128
	s_waitcnt lgkmcnt(6)
	v_mfma_f32_32x32x16_bf16 v[64:79], v[160:163], v[104:107], v[64:79]
	v_add_f32_e32 v246, v213, v246
	v_exp_f32_e32 v230, v230
	v_add_f32_e32 v245, v214, v245
	ds_read_b128 v[156:159], v241 offset:12416
	s_waitcnt lgkmcnt(6)
	v_mfma_f32_32x32x16_bf16 v[80:95], v[164:167], v[104:107], v[80:95]
	v_exp_f32_e32 v231, v231
	v_add_f32_e32 v246, v215, v246
	s_add_i32 m0, s60, 0xc400
	s_nop 0
	global_load_lds_dwordx4 v183, s[42:43]
	ds_read_b128 v[160:163], v242 offset:128
	s_waitcnt lgkmcnt(6)
	v_mfma_f32_32x32x16_bf16 v[64:79], v[168:171], v[108:111], v[64:79]
	v_exp_f32_e32 v232, v232
	v_add_f32_e32 v245, v216, v245
	v_exp_f32_e32 v233, v233
	ds_read_b128 v[164:167], v242 offset:12416
	s_waitcnt lgkmcnt(6)
	v_mfma_f32_32x32x16_bf16 v[80:95], v[172:175], v[108:111], v[80:95]
	v_add_f32_e32 v246, v217, v246
	v_exp_f32_e32 v234, v234
	v_add_f32_e32 v245, v218, v245
	ds_read_b128 v[168:171], v243 offset:128
	s_waitcnt lgkmcnt(6)
	v_mfma_f32_32x32x16_bf16 v[64:79], v[144:147], v[112:115], v[64:79]
	v_exp_f32_e32 v235, v235
	v_add_f32_e32 v246, v219, v246
	s_add_i32 m0, s60, 0xc800
	s_nop 0
	global_load_lds_dwordx4 v184, s[42:43]
	ds_read_b128 v[172:175], v243 offset:12416
	s_waitcnt lgkmcnt(6)
	v_mfma_f32_32x32x16_bf16 v[80:95], v[148:151], v[112:115], v[80:95]
	v_exp_f32_e32 v236, v236
	v_add_f32_e32 v245, v220, v245
	v_exp_f32_e32 v237, v237
	ds_read_b128 v[144:147], v240 offset:256
	s_waitcnt lgkmcnt(6)
	v_mfma_f32_32x32x16_bf16 v[64:79], v[152:155], v[116:119], v[64:79]
	v_add_f32_e32 v246, v221, v246
	v_exp_f32_e32 v238, v238
	v_add_f32_e32 v245, v222, v245
	ds_read_b128 v[148:151], v240 offset:12544
	s_waitcnt lgkmcnt(6)
	v_mfma_f32_32x32x16_bf16 v[80:95], v[156:159], v[116:119], v[80:95]
	v_exp_f32_e32 v239, v239
	v_add_f32_e32 v246, v223, v246
	s_add_i32 m0, s61, 0x4000
	s_nop 0
	global_load_lds_dwordx4 v185, s[46:47]
	ds_read_b128 v[152:155], v241 offset:256
	s_waitcnt lgkmcnt(6)
	v_mfma_f32_32x32x16_bf16 v[64:79], v[160:163], v[120:123], v[64:79]
	v_add_f32_e32 v245, v224, v245
	v_add_f32_e32 v246, v225, v246
	v_add_f32_e32 v245, v226, v245
	ds_read_b128 v[156:159], v241 offset:12544
	s_waitcnt lgkmcnt(6)
	v_mfma_f32_32x32x16_bf16 v[80:95], v[164:167], v[120:123], v[80:95]
	v_add_f32_e32 v246, v227, v246
	v_add_f32_e32 v245, v228, v245
	v_add_f32_e32 v246, v229, v246
	ds_read_b128 v[160:163], v242 offset:256
	s_waitcnt lgkmcnt(6)
	v_mfma_f32_32x32x16_bf16 v[64:79], v[168:171], v[124:127], v[64:79]
	v_add_f32_e32 v245, v230, v245
	v_add_f32_e32 v246, v231, v246
	s_add_i32 m0, s61, 0x4400
	s_nop 0
	global_load_lds_dwordx4 v186, s[46:47]
	ds_read_b128 v[164:167], v242 offset:12544
	s_waitcnt lgkmcnt(6)
	v_mfma_f32_32x32x16_bf16 v[80:95], v[172:175], v[124:127], v[80:95]
	v_add_f32_e32 v245, v232, v245
	v_add_f32_e32 v246, v233, v246
	v_add_f32_e32 v245, v234, v245
	ds_read_b128 v[168:171], v243 offset:256
	s_waitcnt lgkmcnt(6)
	v_mfma_f32_32x32x16_bf16 v[64:79], v[144:147], v[128:131], v[64:79]
	v_add_f32_e32 v246, v235, v246
	v_add_f32_e32 v245, v236, v245
	v_add_f32_e32 v246, v237, v246
	ds_read_b128 v[172:175], v243 offset:12544
	s_waitcnt lgkmcnt(6)
	v_mfma_f32_32x32x16_bf16 v[80:95], v[148:151], v[128:131], v[80:95]
	v_add_f32_e32 v245, v238, v245
	v_add_f32_e32 v246, v239, v246
	s_add_u32 s42, s42, 0x6000
	s_addc_u32 s43, s43, 0
	v_add_u32_e32 v240, 0x6000, v240
	ds_read_b64_tr_b16 v[144:145], v244 offset:0
	ds_read_b64_tr_b16 v[146:147], v244 offset:2048
	s_waitcnt lgkmcnt(7)
	v_mfma_f32_32x32x16_bf16 v[64:79], v[152:155], v[132:135], v[64:79]
	v_cvt_pk_bf16_f32 v208, v208, v209
	v_cvt_pk_bf16_f32 v209, v210, v211
	v_cvt_pk_bf16_f32 v210, v212, v213
	v_add_u32_e32 v241, 0x6000, v241
	ds_read_b64_tr_b16 v[148:149], v244 offset:4096
	ds_read_b64_tr_b16 v[150:151], v244 offset:6144
	s_waitcnt lgkmcnt(8)
	v_mfma_f32_32x32x16_bf16 v[80:95], v[156:159], v[132:135], v[80:95]
	v_cvt_pk_bf16_f32 v211, v214, v215
	v_cvt_pk_bf16_f32 v212, v216, v217
	v_cvt_pk_bf16_f32 v213, v218, v219
	v_add_u32_e32 v242, 0x6000, v242
	ds_read_b64_tr_b16 v[152:153], v244 offset:8192
	ds_read_b64_tr_b16 v[154:155], v244 offset:10240
	s_waitcnt lgkmcnt(9)
	v_mfma_f32_32x32x16_bf16 v[64:79], v[160:163], v[136:139], v[64:79]
	v_cvt_pk_bf16_f32 v214, v220, v221
	v_cvt_pk_bf16_f32 v215, v222, v223
	s_add_u32 s46, s46, 0x40000
	s_addc_u32 s47, s47, 0
	v_add_u32_e32 v243, 0x6000, v243
	ds_read_b64_tr_b16 v[156:157], v244 offset:12288
	ds_read_b64_tr_b16 v[158:159], v244 offset:14336
	s_waitcnt lgkmcnt(10)
	v_mfma_f32_32x32x16_bf16 v[80:95], v[164:167], v[136:139], v[80:95]
	v_cvt_pk_bf16_f32 v224, v224, v225
	v_cvt_pk_bf16_f32 v225, v226, v227
	v_cvt_pk_bf16_f32 v226, v228, v229
	ds_read_b64_tr_b16 v[160:161], v244 offset:512
	ds_read_b64_tr_b16 v[162:163], v244 offset:2560
	s_waitcnt lgkmcnt(11)
	v_mfma_f32_32x32x16_bf16 v[64:79], v[168:171], v[140:143], v[64:79]
	v_cvt_pk_bf16_f32 v227, v230, v231
	v_cvt_pk_bf16_f32 v228, v232, v233
	v_cvt_pk_bf16_f32 v229, v234, v235
	ds_read_b64_tr_b16 v[164:165], v244 offset:4608
	ds_read_b64_tr_b16 v[166:167], v244 offset:6656
	s_waitcnt lgkmcnt(12)
	v_mfma_f32_32x32x16_bf16 v[80:95], v[172:175], v[140:143], v[80:95]
	v_cvt_pk_bf16_f32 v230, v236, v237
	v_cvt_pk_bf16_f32 v231, v238, v239
	ds_read_b64_tr_b16 v[168:169], v244 offset:8704
	ds_read_b64_tr_b16 v[170:171], v244 offset:10752
	s_waitcnt lgkmcnt(12)
	v_mfma_f32_32x32x16_bf16 v[48:63], v[208:211], v[144:147], v[48:63]
	ds_read_b64_tr_b16 v[172:173], v244 offset:12800
	ds_read_b64_tr_b16 v[174:175], v244 offset:14848
	s_waitcnt lgkmcnt(12)
	v_mfma_f32_32x32x16_bf16 v[48:63], v[212:215], v[148:151], v[48:63]
	ds_read_b64_tr_b16 v[144:145], v244 offset:1024
	ds_read_b64_tr_b16 v[146:147], v244 offset:3072
	s_waitcnt lgkmcnt(12)
	v_mfma_f32_32x32x16_bf16 v[48:63], v[224:227], v[152:155], v[48:63]
	v_exp_f32_e32 v64, v64
	v_exp_f32_e32 v65, v65
	ds_read_b64_tr_b16 v[148:149], v244 offset:5120
	ds_read_b64_tr_b16 v[150:151], v244 offset:7168
	s_waitcnt lgkmcnt(12)
	v_mfma_f32_32x32x16_bf16 v[48:63], v[228:231], v[156:159], v[48:63]
	v_exp_f32_e32 v66, v66
	v_exp_f32_e32 v67, v67
	ds_read_b64_tr_b16 v[152:153], v244 offset:9216
	ds_read_b64_tr_b16 v[154:155], v244 offset:11264
	s_waitcnt lgkmcnt(12)
	v_mfma_f32_32x32x16_bf16 v[32:47], v[208:211], v[160:163], v[32:47]
	v_exp_f32_e32 v68, v68
	ds_read_b64_tr_b16 v[156:157], v244 offset:13312
	ds_read_b64_tr_b16 v[158:159], v244 offset:15360
	s_waitcnt lgkmcnt(12)
	v_mfma_f32_32x32x16_bf16 v[32:47], v[212:215], v[164:167], v[32:47]
	v_exp_f32_e32 v69, v69
	ds_read_b64_tr_b16 v[160:161], v244 offset:1536
	ds_read_b64_tr_b16 v[162:163], v244 offset:3584
	s_waitcnt lgkmcnt(12)
	v_mfma_f32_32x32x16_bf16 v[32:47], v[224:227], v[168:171], v[32:47]
	v_exp_f32_e32 v70, v70
	ds_read_b64_tr_b16 v[164:165], v244 offset:5632
	ds_read_b64_tr_b16 v[166:167], v244 offset:7680
	s_waitcnt lgkmcnt(12)
	v_mfma_f32_32x32x16_bf16 v[32:47], v[228:231], v[172:175], v[32:47]
	v_exp_f32_e32 v71, v71
	ds_read_b64_tr_b16 v[168:169], v244 offset:9728
	ds_read_b64_tr_b16 v[170:171], v244 offset:11776
	s_waitcnt lgkmcnt(12)
	v_mfma_f32_32x32x16_bf16 v[16:31], v[208:211], v[144:147], v[16:31]
	v_exp_f32_e32 v72, v72
	ds_read_b64_tr_b16 v[172:173], v244 offset:13824
	ds_read_b64_tr_b16 v[174:175], v244 offset:15872
	s_waitcnt lgkmcnt(12)
	v_mfma_f32_32x32x16_bf16 v[16:31], v[212:215], v[148:151], v[16:31]
	v_exp_f32_e32 v73, v73
	v_add_u32_e32 v244, 0xffff8000, v244
	ds_read_b128 v[144:147], v240 offset:0
	s_waitcnt lgkmcnt(11)
	v_mfma_f32_32x32x16_bf16 v[16:31], v[224:227], v[152:155], v[16:31]
	v_exp_f32_e32 v74, v74
	ds_read_b128 v[148:151], v240 offset:12288
	s_waitcnt lgkmcnt(10)
	v_mfma_f32_32x32x16_bf16 v[16:31], v[228:231], v[156:159], v[16:31]
	v_exp_f32_e32 v75, v75
	ds_read_b128 v[152:155], v241 offset:0
	s_waitcnt lgkmcnt(9)
	v_mfma_f32_32x32x16_bf16 v[0:15], v[208:211], v[160:163], v[0:15]
	v_exp_f32_e32 v76, v76
	ds_read_b128 v[156:159], v241 offset:12288
	s_waitcnt lgkmcnt(8)
	v_mfma_f32_32x32x16_bf16 v[0:15], v[212:215], v[164:167], v[0:15]
	v_exp_f32_e32 v77, v77
	ds_read_b128 v[160:163], v242 offset:0
	s_waitcnt lgkmcnt(7)
	v_mfma_f32_32x32x16_bf16 v[0:15], v[224:227], v[168:171], v[0:15]
	v_exp_f32_e32 v78, v78
	ds_read_b128 v[164:167], v242 offset:12288
	s_waitcnt lgkmcnt(6)
	v_mfma_f32_32x32x16_bf16 v[0:15], v[228:231], v[172:175], v[0:15]
	v_exp_f32_e32 v79, v79
	s_waitcnt vmcnt(5)
	s_barrier
	ds_read_b128 v[168:171], v243 offset:0
	s_waitcnt lgkmcnt(6)
	v_mfma_f32_32x32x16_bf16 v[208:223], v[144:147], v[96:99], 0
	v_exp_f32_e32 v80, v80
	v_add_f32_e32 v245, v64, v245
	v_exp_f32_e32 v81, v81
	ds_read_b128 v[172:175], v243 offset:12288
	s_waitcnt lgkmcnt(6)
	v_mfma_f32_32x32x16_bf16 v[224:239], v[148:151], v[96:99], 0
	v_add_f32_e32 v246, v65, v246
	v_exp_f32_e32 v82, v82
	v_add_f32_e32 v245, v66, v245
	ds_read_b128 v[144:147], v240 offset:128
	s_waitcnt lgkmcnt(6)
	v_mfma_f32_32x32x16_bf16 v[208:223], v[152:155], v[100:103], v[208:223]
	v_exp_f32_e32 v83, v83
	v_add_f32_e32 v246, v67, v246
	s_add_i32 m0, s60, 0x12000
	s_nop 0
	global_load_lds_dwordx4 v182, s[42:43]
	ds_read_b128 v[148:151], v240 offset:12416
	s_waitcnt lgkmcnt(6)
	v_mfma_f32_32x32x16_bf16 v[224:239], v[156:159], v[100:103], v[224:239]
	v_exp_f32_e32 v84, v84
	v_add_f32_e32 v245, v68, v245
	v_exp_f32_e32 v85, v85
	ds_read_b128 v[152:155], v241 offset:128
	s_waitcnt lgkmcnt(6)
	v_mfma_f32_32x32x16_bf16 v[208:223], v[160:163], v[104:107], v[208:223]
	v_add_f32_e32 v246, v69, v246
	v_exp_f32_e32 v86, v86
	v_add_f32_e32 v245, v70, v245
	ds_read_b128 v[156:159], v241 offset:12416
	s_waitcnt lgkmcnt(6)
	v_mfma_f32_32x32x16_bf16 v[224:239], v[164:167], v[104:107], v[224:239]
	v_exp_f32_e32 v87, v87
	v_add_f32_e32 v246, v71, v246
	s_add_i32 m0, s60, 0x12400
	s_nop 0
	global_load_lds_dwordx4 v183, s[42:43]
	ds_read_b128 v[160:163], v242 offset:128
	s_waitcnt lgkmcnt(6)
	v_mfma_f32_32x32x16_bf16 v[208:223], v[168:171], v[108:111], v[208:223]
	v_exp_f32_e32 v88, v88
	v_add_f32_e32 v245, v72, v245
	v_exp_f32_e32 v89, v89
	ds_read_b128 v[164:167], v242 offset:12416
	s_waitcnt lgkmcnt(6)
	v_mfma_f32_32x32x16_bf16 v[224:239], v[172:175], v[108:111], v[224:239]
	v_add_f32_e32 v246, v73, v246
	v_exp_f32_e32 v90, v90
	v_add_f32_e32 v245, v74, v245
	ds_read_b128 v[168:171], v243 offset:128
	s_waitcnt lgkmcnt(6)
	v_mfma_f32_32x32x16_bf16 v[208:223], v[144:147], v[112:115], v[208:223]
	v_exp_f32_e32 v91, v91
	v_add_f32_e32 v246, v75, v246
	s_add_i32 m0, s60, 0x12800
	s_nop 0
	global_load_lds_dwordx4 v184, s[42:43]
	ds_read_b128 v[172:175], v243 offset:12416
	s_waitcnt lgkmcnt(6)
	v_mfma_f32_32x32x16_bf16 v[224:239], v[148:151], v[112:115], v[224:239]
	v_exp_f32_e32 v92, v92
	v_add_f32_e32 v245, v76, v245
	v_exp_f32_e32 v93, v93
	ds_read_b128 v[144:147], v240 offset:256
	s_waitcnt lgkmcnt(6)
	v_mfma_f32_32x32x16_bf16 v[208:223], v[152:155], v[116:119], v[208:223]
	v_add_f32_e32 v246, v77, v246
	v_exp_f32_e32 v94, v94
	v_add_f32_e32 v245, v78, v245
	ds_read_b128 v[148:151], v240 offset:12544
	s_waitcnt lgkmcnt(6)
	v_mfma_f32_32x32x16_bf16 v[224:239], v[156:159], v[116:119], v[224:239]
	v_exp_f32_e32 v95, v95
	v_add_f32_e32 v246, v79, v246
	s_add_i32 m0, s61, 0x8000
	s_nop 0
	global_load_lds_dwordx4 v185, s[46:47]
	ds_read_b128 v[152:155], v241 offset:256
	s_waitcnt lgkmcnt(6)
	v_mfma_f32_32x32x16_bf16 v[208:223], v[160:163], v[120:123], v[208:223]
	v_add_f32_e32 v245, v80, v245
	v_add_f32_e32 v246, v81, v246
	v_add_f32_e32 v245, v82, v245
	ds_read_b128 v[156:159], v241 offset:12544
	s_waitcnt lgkmcnt(6)
	v_mfma_f32_32x32x16_bf16 v[224:239], v[164:167], v[120:123], v[224:239]
	v_add_f32_e32 v246, v83, v246
	v_add_f32_e32 v245, v84, v245
	v_add_f32_e32 v246, v85, v246
	ds_read_b128 v[160:163], v242 offset:256
	s_waitcnt lgkmcnt(6)
	v_mfma_f32_32x32x16_bf16 v[208:223], v[168:171], v[124:127], v[208:223]
	v_add_f32_e32 v245, v86, v245
	v_add_f32_e32 v246, v87, v246
	s_add_i32 m0, s61, 0x8400
	s_nop 0
	global_load_lds_dwordx4 v186, s[46:47]
	ds_read_b128 v[164:167], v242 offset:12544
	s_waitcnt lgkmcnt(6)
	v_mfma_f32_32x32x16_bf16 v[224:239], v[172:175], v[124:127], v[224:239]
	v_add_f32_e32 v245, v88, v245
	v_add_f32_e32 v246, v89, v246
	v_add_f32_e32 v245, v90, v245
	ds_read_b128 v[168:171], v243 offset:256
	s_waitcnt lgkmcnt(6)
	v_mfma_f32_32x32x16_bf16 v[208:223], v[144:147], v[128:131], v[208:223]
	v_add_f32_e32 v246, v91, v246
	v_add_f32_e32 v245, v92, v245
	v_add_f32_e32 v246, v93, v246
	ds_read_b128 v[172:175], v243 offset:12544
	s_waitcnt lgkmcnt(6)
	v_mfma_f32_32x32x16_bf16 v[224:239], v[148:151], v[128:131], v[224:239]
	v_add_f32_e32 v245, v94, v245
	v_add_f32_e32 v246, v95, v246
	s_add_u32 s42, s42, 0x6000
	s_addc_u32 s43, s43, 0
	v_add_u32_e32 v240, 0x9010, v240
	ds_read_b64_tr_b16 v[144:145], v244 offset:0
	ds_read_b64_tr_b16 v[146:147], v244 offset:2048
	s_waitcnt lgkmcnt(7)
	v_mfma_f32_32x32x16_bf16 v[208:223], v[152:155], v[132:135], v[208:223]
	v_cvt_pk_bf16_f32 v64, v64, v65
	v_cvt_pk_bf16_f32 v65, v66, v67
	v_cvt_pk_bf16_f32 v66, v68, v69
	v_add_u32_e32 v241, 0x9010, v241
	ds_read_b64_tr_b16 v[148:149], v244 offset:4096
	ds_read_b64_tr_b16 v[150:151], v244 offset:6144
	s_waitcnt lgkmcnt(8)
	v_mfma_f32_32x32x16_bf16 v[224:239], v[156:159], v[132:135], v[224:239]
	v_cvt_pk_bf16_f32 v67, v70, v71
	v_cvt_pk_bf16_f32 v68, v72, v73
	v_cvt_pk_bf16_f32 v69, v74, v75
	v_add_u32_e32 v242, 0x9010, v242
	ds_read_b64_tr_b16 v[152:153], v244 offset:8192
	ds_read_b64_tr_b16 v[154:155], v244 offset:10240
	s_waitcnt lgkmcnt(9)
	v_mfma_f32_32x32x16_bf16 v[208:223], v[160:163], v[136:139], v[208:223]
	v_cvt_pk_bf16_f32 v70, v76, v77
	v_cvt_pk_bf16_f32 v71, v78, v79
	s_add_u32 s46, s46, 0x40000
	s_addc_u32 s47, s47, 0
	v_add_u32_e32 v243, 0x9010, v243
	ds_read_b64_tr_b16 v[156:157], v244 offset:12288
	ds_read_b64_tr_b16 v[158:159], v244 offset:14336
	s_waitcnt lgkmcnt(10)
	v_mfma_f32_32x32x16_bf16 v[224:239], v[164:167], v[136:139], v[224:239]
	v_cvt_pk_bf16_f32 v80, v80, v81
	v_cvt_pk_bf16_f32 v81, v82, v83
	v_cvt_pk_bf16_f32 v82, v84, v85
	ds_read_b64_tr_b16 v[160:161], v244 offset:512
	ds_read_b64_tr_b16 v[162:163], v244 offset:2560
	s_waitcnt lgkmcnt(11)
	v_mfma_f32_32x32x16_bf16 v[208:223], v[168:171], v[140:143], v[208:223]
	v_cvt_pk_bf16_f32 v83, v86, v87
	v_cvt_pk_bf16_f32 v84, v88, v89
	v_cvt_pk_bf16_f32 v85, v90, v91
	ds_read_b64_tr_b16 v[164:165], v244 offset:4608
	ds_read_b64_tr_b16 v[166:167], v244 offset:6656
	s_waitcnt lgkmcnt(12)
	v_mfma_f32_32x32x16_bf16 v[224:239], v[172:175], v[140:143], v[224:239]
	v_cvt_pk_bf16_f32 v86, v92, v93
	v_cvt_pk_bf16_f32 v87, v94, v95
	ds_read_b64_tr_b16 v[168:169], v244 offset:8704
	ds_read_b64_tr_b16 v[170:171], v244 offset:10752
	s_waitcnt lgkmcnt(12)
	v_mfma_f32_32x32x16_bf16 v[48:63], v[64:67], v[144:147], v[48:63]
	ds_read_b64_tr_b16 v[172:173], v244 offset:12800
	ds_read_b64_tr_b16 v[174:175], v244 offset:14848
	s_waitcnt lgkmcnt(12)
	v_mfma_f32_32x32x16_bf16 v[48:63], v[68:71], v[148:151], v[48:63]
	ds_read_b64_tr_b16 v[144:145], v244 offset:1024
	ds_read_b64_tr_b16 v[146:147], v244 offset:3072
	s_waitcnt lgkmcnt(12)
	v_mfma_f32_32x32x16_bf16 v[48:63], v[80:83], v[152:155], v[48:63]
	v_exp_f32_e32 v208, v208
	v_exp_f32_e32 v209, v209
	ds_read_b64_tr_b16 v[148:149], v244 offset:5120
	ds_read_b64_tr_b16 v[150:151], v244 offset:7168
	s_waitcnt lgkmcnt(12)
	v_mfma_f32_32x32x16_bf16 v[48:63], v[84:87], v[156:159], v[48:63]
	v_exp_f32_e32 v210, v210
	v_exp_f32_e32 v211, v211
	ds_read_b64_tr_b16 v[152:153], v244 offset:9216
	ds_read_b64_tr_b16 v[154:155], v244 offset:11264
	s_waitcnt lgkmcnt(12)
	v_mfma_f32_32x32x16_bf16 v[32:47], v[64:67], v[160:163], v[32:47]
	v_exp_f32_e32 v212, v212
	ds_read_b64_tr_b16 v[156:157], v244 offset:13312
	ds_read_b64_tr_b16 v[158:159], v244 offset:15360
	s_waitcnt lgkmcnt(12)
	v_mfma_f32_32x32x16_bf16 v[32:47], v[68:71], v[164:167], v[32:47]
	v_exp_f32_e32 v213, v213
	ds_read_b64_tr_b16 v[160:161], v244 offset:1536
	ds_read_b64_tr_b16 v[162:163], v244 offset:3584
	s_waitcnt lgkmcnt(12)
	v_mfma_f32_32x32x16_bf16 v[32:47], v[80:83], v[168:171], v[32:47]
	v_exp_f32_e32 v214, v214
	ds_read_b64_tr_b16 v[164:165], v244 offset:5632
	ds_read_b64_tr_b16 v[166:167], v244 offset:7680
	s_waitcnt lgkmcnt(12)
	v_mfma_f32_32x32x16_bf16 v[32:47], v[84:87], v[172:175], v[32:47]
	v_exp_f32_e32 v215, v215
	ds_read_b64_tr_b16 v[168:169], v244 offset:9728
	ds_read_b64_tr_b16 v[170:171], v244 offset:11776
	s_waitcnt lgkmcnt(12)
	v_mfma_f32_32x32x16_bf16 v[16:31], v[64:67], v[144:147], v[16:31]
	v_exp_f32_e32 v216, v216
	ds_read_b64_tr_b16 v[172:173], v244 offset:13824
	ds_read_b64_tr_b16 v[174:175], v244 offset:15872
	s_waitcnt lgkmcnt(12)
	v_mfma_f32_32x32x16_bf16 v[16:31], v[68:71], v[148:151], v[16:31]
	v_exp_f32_e32 v217, v217
	v_add_u32_e32 v244, 0x4000, v244
	ds_read_b128 v[144:147], v240 offset:0
	s_waitcnt lgkmcnt(11)
	v_mfma_f32_32x32x16_bf16 v[16:31], v[80:83], v[152:155], v[16:31]
	v_exp_f32_e32 v218, v218
	ds_read_b128 v[148:151], v240 offset:12288
	s_waitcnt lgkmcnt(10)
	v_mfma_f32_32x32x16_bf16 v[16:31], v[84:87], v[156:159], v[16:31]
	v_exp_f32_e32 v219, v219
	ds_read_b128 v[152:155], v241 offset:0
	s_waitcnt lgkmcnt(9)
	v_mfma_f32_32x32x16_bf16 v[0:15], v[64:67], v[160:163], v[0:15]
	v_exp_f32_e32 v220, v220
	ds_read_b128 v[156:159], v241 offset:12288
	s_waitcnt lgkmcnt(8)
	v_mfma_f32_32x32x16_bf16 v[0:15], v[68:71], v[164:167], v[0:15]
	v_exp_f32_e32 v221, v221
	ds_read_b128 v[160:163], v242 offset:0
	s_waitcnt lgkmcnt(7)
	v_mfma_f32_32x32x16_bf16 v[0:15], v[80:83], v[168:171], v[0:15]
	v_exp_f32_e32 v222, v222
	ds_read_b128 v[164:167], v242 offset:12288
	s_waitcnt lgkmcnt(6)
	v_mfma_f32_32x32x16_bf16 v[0:15], v[84:87], v[172:175], v[0:15]
	v_exp_f32_e32 v223, v223
	s_waitcnt vmcnt(5)
	s_barrier
	ds_read_b128 v[168:171], v243 offset:0
	s_waitcnt lgkmcnt(6)
	v_mfma_f32_32x32x16_bf16 v[64:79], v[144:147], v[96:99], 0
	v_exp_f32_e32 v224, v224
	v_add_f32_e32 v245, v208, v245
	v_exp_f32_e32 v225, v225
	ds_read_b128 v[172:175], v243 offset:12288
	s_waitcnt lgkmcnt(6)
	v_mfma_f32_32x32x16_bf16 v[80:95], v[148:151], v[96:99], 0
	v_add_f32_e32 v246, v209, v246
	v_exp_f32_e32 v226, v226
	v_add_f32_e32 v245, v210, v245
	ds_read_b128 v[144:147], v240 offset:128
	s_waitcnt lgkmcnt(6)
	v_mfma_f32_32x32x16_bf16 v[64:79], v[152:155], v[100:103], v[64:79]
	v_exp_f32_e32 v227, v227
	v_add_f32_e32 v246, v211, v246
	s_add_i32 m0, s60, 0x18000
	s_nop 0
	global_load_lds_dwordx4 v182, s[42:43]
	ds_read_b128 v[148:151], v240 offset:12416
	s_waitcnt lgkmcnt(6)
	v_mfma_f32_32x32x16_bf16 v[80:95], v[156:159], v[100:103], v[80:95]
	v_exp_f32_e32 v228, v228
	v_add_f32_e32 v245, v212, v245
	v_exp_f32_e32 v229, v229
	ds_read_b128 v[152:155], v241 offset:128
	s_waitcnt lgkmcnt(6)
	v_mfma_f32_32x32x16_bf16 v[64:79], v[160:163], v[104:107], v[64:79]
	v_add_f32_e32 v246, v213, v246
	v_exp_f32_e32 v230, v230
	v_add_f32_e32 v245, v214, v245
	ds_read_b128 v[156:159], v241 offset:12416
	s_waitcnt lgkmcnt(6)
	v_mfma_f32_32x32x16_bf16 v[80:95], v[164:167], v[104:107], v[80:95]
	v_exp_f32_e32 v231, v231
	v_add_f32_e32 v246, v215, v246
	s_add_i32 m0, s60, 0x18400
	s_nop 0
	global_load_lds_dwordx4 v183, s[42:43]
	ds_read_b128 v[160:163], v242 offset:128
	s_waitcnt lgkmcnt(6)
	v_mfma_f32_32x32x16_bf16 v[64:79], v[168:171], v[108:111], v[64:79]
	v_exp_f32_e32 v232, v232
	v_add_f32_e32 v245, v216, v245
	v_exp_f32_e32 v233, v233
	ds_read_b128 v[164:167], v242 offset:12416
	s_waitcnt lgkmcnt(6)
	v_mfma_f32_32x32x16_bf16 v[80:95], v[172:175], v[108:111], v[80:95]
	v_add_f32_e32 v246, v217, v246
	v_exp_f32_e32 v234, v234
	v_add_f32_e32 v245, v218, v245
	ds_read_b128 v[168:171], v243 offset:128
	s_waitcnt lgkmcnt(6)
	v_mfma_f32_32x32x16_bf16 v[64:79], v[144:147], v[112:115], v[64:79]
	v_exp_f32_e32 v235, v235
	v_add_f32_e32 v246, v219, v246
	s_add_i32 m0, s60, 0x18800
	s_nop 0
	global_load_lds_dwordx4 v184, s[42:43]
	ds_read_b128 v[172:175], v243 offset:12416
	s_waitcnt lgkmcnt(6)
	v_mfma_f32_32x32x16_bf16 v[80:95], v[148:151], v[112:115], v[80:95]
	v_exp_f32_e32 v236, v236
	v_add_f32_e32 v245, v220, v245
	v_exp_f32_e32 v237, v237
	ds_read_b128 v[144:147], v240 offset:256
	s_waitcnt lgkmcnt(6)
	v_mfma_f32_32x32x16_bf16 v[64:79], v[152:155], v[116:119], v[64:79]
	v_add_f32_e32 v246, v221, v246
	v_exp_f32_e32 v238, v238
	v_add_f32_e32 v245, v222, v245
	ds_read_b128 v[148:151], v240 offset:12544
	s_waitcnt lgkmcnt(6)
	v_mfma_f32_32x32x16_bf16 v[80:95], v[156:159], v[116:119], v[80:95]
	v_exp_f32_e32 v239, v239
	v_add_f32_e32 v246, v223, v246
	s_add_i32 m0, s61, 0x0
	s_nop 0
	global_load_lds_dwordx4 v185, s[46:47]
	ds_read_b128 v[152:155], v241 offset:256
	s_waitcnt lgkmcnt(6)
	v_mfma_f32_32x32x16_bf16 v[64:79], v[160:163], v[120:123], v[64:79]
	v_add_f32_e32 v245, v224, v245
	v_add_f32_e32 v246, v225, v246
	v_add_f32_e32 v245, v226, v245
	ds_read_b128 v[156:159], v241 offset:12544
	s_waitcnt lgkmcnt(6)
	v_mfma_f32_32x32x16_bf16 v[80:95], v[164:167], v[120:123], v[80:95]
	v_add_f32_e32 v246, v227, v246
	v_add_f32_e32 v245, v228, v245
	v_add_f32_e32 v246, v229, v246
	ds_read_b128 v[160:163], v242 offset:256
	s_waitcnt lgkmcnt(6)
	v_mfma_f32_32x32x16_bf16 v[64:79], v[168:171], v[124:127], v[64:79]
	v_add_f32_e32 v245, v230, v245
	v_add_f32_e32 v246, v231, v246
	s_add_i32 m0, s61, 0x400
	s_nop 0
	global_load_lds_dwordx4 v186, s[46:47]
	ds_read_b128 v[164:167], v242 offset:12544
	s_waitcnt lgkmcnt(6)
	v_mfma_f32_32x32x16_bf16 v[80:95], v[172:175], v[124:127], v[80:95]
	v_add_f32_e32 v245, v232, v245
	v_add_f32_e32 v246, v233, v246
	v_add_f32_e32 v245, v234, v245
	ds_read_b128 v[168:171], v243 offset:256
	s_waitcnt lgkmcnt(6)
	v_mfma_f32_32x32x16_bf16 v[64:79], v[144:147], v[128:131], v[64:79]
	v_add_f32_e32 v246, v235, v246
	v_add_f32_e32 v245, v236, v245
	v_add_f32_e32 v246, v237, v246
	ds_read_b128 v[172:175], v243 offset:12544
	s_waitcnt lgkmcnt(6)
	v_mfma_f32_32x32x16_bf16 v[80:95], v[148:151], v[128:131], v[80:95]
	v_add_f32_e32 v245, v238, v245
	v_add_f32_e32 v246, v239, v246
	s_add_u32 s42, s42, 0x6000
	s_addc_u32 s43, s43, 0
	v_add_u32_e32 v240, 0xfffeaff0, v240
	ds_read_b64_tr_b16 v[144:145], v244 offset:0
	ds_read_b64_tr_b16 v[146:147], v244 offset:2048
	s_waitcnt lgkmcnt(7)
	v_mfma_f32_32x32x16_bf16 v[64:79], v[152:155], v[132:135], v[64:79]
	v_cvt_pk_bf16_f32 v208, v208, v209
	v_cvt_pk_bf16_f32 v209, v210, v211
	v_cvt_pk_bf16_f32 v210, v212, v213
	v_add_u32_e32 v241, 0xfffeaff0, v241
	ds_read_b64_tr_b16 v[148:149], v244 offset:4096
	ds_read_b64_tr_b16 v[150:151], v244 offset:6144
	s_waitcnt lgkmcnt(8)
	v_mfma_f32_32x32x16_bf16 v[80:95], v[156:159], v[132:135], v[80:95]
	v_cvt_pk_bf16_f32 v211, v214, v215
	v_cvt_pk_bf16_f32 v212, v216, v217
	v_cvt_pk_bf16_f32 v213, v218, v219
	v_add_u32_e32 v242, 0xfffeaff0, v242
	ds_read_b64_tr_b16 v[152:153], v244 offset:8192
	ds_read_b64_tr_b16 v[154:155], v244 offset:10240
	s_waitcnt lgkmcnt(9)
	v_mfma_f32_32x32x16_bf16 v[64:79], v[160:163], v[136:139], v[64:79]
	v_cvt_pk_bf16_f32 v214, v220, v221
	v_cvt_pk_bf16_f32 v215, v222, v223
	s_add_u32 s46, s46, 0x40000
	s_addc_u32 s47, s47, 0
	v_add_u32_e32 v243, 0xfffeaff0, v243
	ds_read_b64_tr_b16 v[156:157], v244 offset:12288
	ds_read_b64_tr_b16 v[158:159], v244 offset:14336
	s_waitcnt lgkmcnt(10)
	v_mfma_f32_32x32x16_bf16 v[80:95], v[164:167], v[136:139], v[80:95]
	v_cvt_pk_bf16_f32 v224, v224, v225
	v_cvt_pk_bf16_f32 v225, v226, v227
	v_cvt_pk_bf16_f32 v226, v228, v229
	ds_read_b64_tr_b16 v[160:161], v244 offset:512
	ds_read_b64_tr_b16 v[162:163], v244 offset:2560
	s_waitcnt lgkmcnt(11)
	v_mfma_f32_32x32x16_bf16 v[64:79], v[168:171], v[140:143], v[64:79]
	v_cvt_pk_bf16_f32 v227, v230, v231
	v_cvt_pk_bf16_f32 v228, v232, v233
	v_cvt_pk_bf16_f32 v229, v234, v235
	ds_read_b64_tr_b16 v[164:165], v244 offset:4608
	ds_read_b64_tr_b16 v[166:167], v244 offset:6656
	s_waitcnt lgkmcnt(12)
	v_mfma_f32_32x32x16_bf16 v[80:95], v[172:175], v[140:143], v[80:95]
	v_cvt_pk_bf16_f32 v230, v236, v237
	v_cvt_pk_bf16_f32 v231, v238, v239
	ds_read_b64_tr_b16 v[168:169], v244 offset:8704
	ds_read_b64_tr_b16 v[170:171], v244 offset:10752
	s_waitcnt lgkmcnt(12)
	v_mfma_f32_32x32x16_bf16 v[48:63], v[208:211], v[144:147], v[48:63]
	ds_read_b64_tr_b16 v[172:173], v244 offset:12800
	ds_read_b64_tr_b16 v[174:175], v244 offset:14848
	s_waitcnt lgkmcnt(12)
	v_mfma_f32_32x32x16_bf16 v[48:63], v[212:215], v[148:151], v[48:63]
	ds_read_b64_tr_b16 v[144:145], v244 offset:1024
	ds_read_b64_tr_b16 v[146:147], v244 offset:3072
	s_waitcnt lgkmcnt(12)
	v_mfma_f32_32x32x16_bf16 v[48:63], v[224:227], v[152:155], v[48:63]
	v_exp_f32_e32 v64, v64
	v_exp_f32_e32 v65, v65
	ds_read_b64_tr_b16 v[148:149], v244 offset:5120
	ds_read_b64_tr_b16 v[150:151], v244 offset:7168
	s_waitcnt lgkmcnt(12)
	v_mfma_f32_32x32x16_bf16 v[48:63], v[228:231], v[156:159], v[48:63]
	v_exp_f32_e32 v66, v66
	v_exp_f32_e32 v67, v67
	ds_read_b64_tr_b16 v[152:153], v244 offset:9216
	ds_read_b64_tr_b16 v[154:155], v244 offset:11264
	s_waitcnt lgkmcnt(12)
	v_mfma_f32_32x32x16_bf16 v[32:47], v[208:211], v[160:163], v[32:47]
	v_exp_f32_e32 v68, v68
	ds_read_b64_tr_b16 v[156:157], v244 offset:13312
	ds_read_b64_tr_b16 v[158:159], v244 offset:15360
	s_waitcnt lgkmcnt(12)
	v_mfma_f32_32x32x16_bf16 v[32:47], v[212:215], v[164:167], v[32:47]
	v_exp_f32_e32 v69, v69
	ds_read_b64_tr_b16 v[160:161], v244 offset:1536
	ds_read_b64_tr_b16 v[162:163], v244 offset:3584
	s_waitcnt lgkmcnt(12)
	v_mfma_f32_32x32x16_bf16 v[32:47], v[224:227], v[168:171], v[32:47]
	v_exp_f32_e32 v70, v70
	ds_read_b64_tr_b16 v[164:165], v244 offset:5632
	ds_read_b64_tr_b16 v[166:167], v244 offset:7680
	s_waitcnt lgkmcnt(12)
	v_mfma_f32_32x32x16_bf16 v[32:47], v[228:231], v[172:175], v[32:47]
	v_exp_f32_e32 v71, v71
	ds_read_b64_tr_b16 v[168:169], v244 offset:9728
	ds_read_b64_tr_b16 v[170:171], v244 offset:11776
	s_waitcnt lgkmcnt(12)
	v_mfma_f32_32x32x16_bf16 v[16:31], v[208:211], v[144:147], v[16:31]
	v_exp_f32_e32 v72, v72
	ds_read_b64_tr_b16 v[172:173], v244 offset:13824
	ds_read_b64_tr_b16 v[174:175], v244 offset:15872
	s_waitcnt lgkmcnt(12)
	v_mfma_f32_32x32x16_bf16 v[16:31], v[212:215], v[148:151], v[16:31]
	v_exp_f32_e32 v73, v73
	v_add_u32_e32 v244, 0x4000, v244
	ds_read_b128 v[144:147], v240 offset:0
	s_waitcnt lgkmcnt(11)
	v_mfma_f32_32x32x16_bf16 v[16:31], v[224:227], v[152:155], v[16:31]
	v_exp_f32_e32 v74, v74
	ds_read_b128 v[148:151], v240 offset:12288
	s_waitcnt lgkmcnt(10)
	v_mfma_f32_32x32x16_bf16 v[16:31], v[228:231], v[156:159], v[16:31]
	v_exp_f32_e32 v75, v75
	ds_read_b128 v[152:155], v241 offset:0
	s_waitcnt lgkmcnt(9)
	v_mfma_f32_32x32x16_bf16 v[0:15], v[208:211], v[160:163], v[0:15]
	v_exp_f32_e32 v76, v76
	ds_read_b128 v[156:159], v241 offset:12288
	s_waitcnt lgkmcnt(8)
	v_mfma_f32_32x32x16_bf16 v[0:15], v[212:215], v[164:167], v[0:15]
	v_exp_f32_e32 v77, v77
	ds_read_b128 v[160:163], v242 offset:0
	s_waitcnt lgkmcnt(7)
	v_mfma_f32_32x32x16_bf16 v[0:15], v[224:227], v[168:171], v[0:15]
	v_exp_f32_e32 v78, v78
	ds_read_b128 v[164:167], v242 offset:12288
	s_waitcnt lgkmcnt(6)
	v_mfma_f32_32x32x16_bf16 v[0:15], v[228:231], v[172:175], v[0:15]
	v_exp_f32_e32 v79, v79
	s_waitcnt vmcnt(5)
	s_barrier
	ds_read_b128 v[168:171], v243 offset:0
	s_waitcnt lgkmcnt(6)
	v_mfma_f32_32x32x16_bf16 v[208:223], v[144:147], v[96:99], 0
	v_exp_f32_e32 v80, v80
	v_add_f32_e32 v245, v64, v245
	v_exp_f32_e32 v81, v81
	ds_read_b128 v[172:175], v243 offset:12288
	s_waitcnt lgkmcnt(6)
	v_mfma_f32_32x32x16_bf16 v[224:239], v[148:151], v[96:99], 0
	v_add_f32_e32 v246, v65, v246
	v_exp_f32_e32 v82, v82
	v_add_f32_e32 v245, v66, v245
	ds_read_b128 v[144:147], v240 offset:128
	s_waitcnt lgkmcnt(6)
	v_mfma_f32_32x32x16_bf16 v[208:223], v[152:155], v[100:103], v[208:223]
	v_exp_f32_e32 v83, v83
	v_add_f32_e32 v246, v67, v246
	s_add_i32 m0, s60, 0x21010
	s_nop 0
	global_load_lds_dwordx4 v182, s[42:43]
	ds_read_b128 v[148:151], v240 offset:12416
	s_waitcnt lgkmcnt(6)
	v_mfma_f32_32x32x16_bf16 v[224:239], v[156:159], v[100:103], v[224:239]
	v_exp_f32_e32 v84, v84
	v_add_f32_e32 v245, v68, v245
	v_exp_f32_e32 v85, v85
	ds_read_b128 v[152:155], v241 offset:128
	s_waitcnt lgkmcnt(6)
	v_mfma_f32_32x32x16_bf16 v[208:223], v[160:163], v[104:107], v[208:223]
	v_add_f32_e32 v246, v69, v246
	v_exp_f32_e32 v86, v86
	v_add_f32_e32 v245, v70, v245
	ds_read_b128 v[156:159], v241 offset:12416
	s_waitcnt lgkmcnt(6)
	v_mfma_f32_32x32x16_bf16 v[224:239], v[164:167], v[104:107], v[224:239]
	v_exp_f32_e32 v87, v87
	v_add_f32_e32 v246, v71, v246
	s_add_i32 m0, s60, 0x21410
	s_nop 0
	global_load_lds_dwordx4 v183, s[42:43]
	ds_read_b128 v[160:163], v242 offset:128
	s_waitcnt lgkmcnt(6)
	v_mfma_f32_32x32x16_bf16 v[208:223], v[168:171], v[108:111], v[208:223]
	v_exp_f32_e32 v88, v88
	v_add_f32_e32 v245, v72, v245
	v_exp_f32_e32 v89, v89
	ds_read_b128 v[164:167], v242 offset:12416
	s_waitcnt lgkmcnt(6)
	v_mfma_f32_32x32x16_bf16 v[224:239], v[172:175], v[108:111], v[224:239]
	v_add_f32_e32 v246, v73, v246
	v_exp_f32_e32 v90, v90
	v_add_f32_e32 v245, v74, v245
	ds_read_b128 v[168:171], v243 offset:128
	s_waitcnt lgkmcnt(6)
	v_mfma_f32_32x32x16_bf16 v[208:223], v[144:147], v[112:115], v[208:223]
	v_exp_f32_e32 v91, v91
	v_add_f32_e32 v246, v75, v246
	s_add_i32 m0, s60, 0x21810
	s_nop 0
	global_load_lds_dwordx4 v184, s[42:43]
	ds_read_b128 v[172:175], v243 offset:12416
	s_waitcnt lgkmcnt(6)
	v_mfma_f32_32x32x16_bf16 v[224:239], v[148:151], v[112:115], v[224:239]
	v_exp_f32_e32 v92, v92
	v_add_f32_e32 v245, v76, v245
	v_exp_f32_e32 v93, v93
	ds_read_b128 v[144:147], v240 offset:256
	s_waitcnt lgkmcnt(6)
	v_mfma_f32_32x32x16_bf16 v[208:223], v[152:155], v[116:119], v[208:223]
	v_add_f32_e32 v246, v77, v246
	v_exp_f32_e32 v94, v94
	v_add_f32_e32 v245, v78, v245
	ds_read_b128 v[148:151], v240 offset:12544
	s_waitcnt lgkmcnt(6)
	v_mfma_f32_32x32x16_bf16 v[224:239], v[156:159], v[116:119], v[224:239]
	v_exp_f32_e32 v95, v95
	v_add_f32_e32 v246, v79, v246
	s_add_i32 m0, s61, 0x4000
	s_nop 0
	global_load_lds_dwordx4 v185, s[46:47]
	ds_read_b128 v[152:155], v241 offset:256
	s_waitcnt lgkmcnt(6)
	v_mfma_f32_32x32x16_bf16 v[208:223], v[160:163], v[120:123], v[208:223]
	v_add_f32_e32 v245, v80, v245
	v_add_f32_e32 v246, v81, v246
	v_add_f32_e32 v245, v82, v245
	ds_read_b128 v[156:159], v241 offset:12544
	s_waitcnt lgkmcnt(6)
	v_mfma_f32_32x32x16_bf16 v[224:239], v[164:167], v[120:123], v[224:239]
	v_add_f32_e32 v246, v83, v246
	v_add_f32_e32 v245, v84, v245
	v_add_f32_e32 v246, v85, v246
	ds_read_b128 v[160:163], v242 offset:256
	s_waitcnt lgkmcnt(6)
	v_mfma_f32_32x32x16_bf16 v[208:223], v[168:171], v[124:127], v[208:223]
	v_add_f32_e32 v245, v86, v245
	v_add_f32_e32 v246, v87, v246
	s_add_i32 m0, s61, 0x4400
	s_nop 0
	global_load_lds_dwordx4 v186, s[46:47]
	ds_read_b128 v[164:167], v242 offset:12544
	s_waitcnt lgkmcnt(6)
	v_mfma_f32_32x32x16_bf16 v[224:239], v[172:175], v[124:127], v[224:239]
	v_add_f32_e32 v245, v88, v245
	v_add_f32_e32 v246, v89, v246
	v_add_f32_e32 v245, v90, v245
	ds_read_b128 v[168:171], v243 offset:256
	s_waitcnt lgkmcnt(6)
	v_mfma_f32_32x32x16_bf16 v[208:223], v[144:147], v[128:131], v[208:223]
	v_add_f32_e32 v246, v91, v246
	v_add_f32_e32 v245, v92, v245
	v_add_f32_e32 v246, v93, v246
	ds_read_b128 v[172:175], v243 offset:12544
	s_waitcnt lgkmcnt(6)
	v_mfma_f32_32x32x16_bf16 v[224:239], v[148:151], v[128:131], v[224:239]
	v_add_f32_e32 v245, v94, v245
	v_add_f32_e32 v246, v95, v246
	s_add_u32 s42, s42, 0x6000
	s_addc_u32 s43, s43, 0
	v_add_u32_e32 v240, 0x6000, v240
	ds_read_b64_tr_b16 v[144:145], v244 offset:0
	ds_read_b64_tr_b16 v[146:147], v244 offset:2048
	s_waitcnt lgkmcnt(7)
	v_mfma_f32_32x32x16_bf16 v[208:223], v[152:155], v[132:135], v[208:223]
	v_cvt_pk_bf16_f32 v64, v64, v65
	v_cvt_pk_bf16_f32 v65, v66, v67
	v_cvt_pk_bf16_f32 v66, v68, v69
	v_add_u32_e32 v241, 0x6000, v241
	ds_read_b64_tr_b16 v[148:149], v244 offset:4096
	ds_read_b64_tr_b16 v[150:151], v244 offset:6144
	s_waitcnt lgkmcnt(8)
	v_mfma_f32_32x32x16_bf16 v[224:239], v[156:159], v[132:135], v[224:239]
	v_cvt_pk_bf16_f32 v67, v70, v71
	v_cvt_pk_bf16_f32 v68, v72, v73
	v_cvt_pk_bf16_f32 v69, v74, v75
	v_add_u32_e32 v242, 0x6000, v242
	ds_read_b64_tr_b16 v[152:153], v244 offset:8192
	ds_read_b64_tr_b16 v[154:155], v244 offset:10240
	s_waitcnt lgkmcnt(9)
	v_mfma_f32_32x32x16_bf16 v[208:223], v[160:163], v[136:139], v[208:223]
	v_cvt_pk_bf16_f32 v70, v76, v77
	v_cvt_pk_bf16_f32 v71, v78, v79
	s_add_u32 s46, s46, 0x40000
	s_addc_u32 s47, s47, 0
	v_add_u32_e32 v243, 0x6000, v243
	ds_read_b64_tr_b16 v[156:157], v244 offset:12288
	ds_read_b64_tr_b16 v[158:159], v244 offset:14336
	s_waitcnt lgkmcnt(10)
	v_mfma_f32_32x32x16_bf16 v[224:239], v[164:167], v[136:139], v[224:239]
	v_cvt_pk_bf16_f32 v80, v80, v81
	v_cvt_pk_bf16_f32 v81, v82, v83
	v_cvt_pk_bf16_f32 v82, v84, v85
	ds_read_b64_tr_b16 v[160:161], v244 offset:512
	ds_read_b64_tr_b16 v[162:163], v244 offset:2560
	s_waitcnt lgkmcnt(11)
	v_mfma_f32_32x32x16_bf16 v[208:223], v[168:171], v[140:143], v[208:223]
	v_cvt_pk_bf16_f32 v83, v86, v87
	v_cvt_pk_bf16_f32 v84, v88, v89
	v_cvt_pk_bf16_f32 v85, v90, v91
	ds_read_b64_tr_b16 v[164:165], v244 offset:4608
	ds_read_b64_tr_b16 v[166:167], v244 offset:6656
	s_waitcnt lgkmcnt(12)
	v_mfma_f32_32x32x16_bf16 v[224:239], v[172:175], v[140:143], v[224:239]
	v_cvt_pk_bf16_f32 v86, v92, v93
	v_cvt_pk_bf16_f32 v87, v94, v95
	ds_read_b64_tr_b16 v[168:169], v244 offset:8704
	ds_read_b64_tr_b16 v[170:171], v244 offset:10752
	s_waitcnt lgkmcnt(12)
	v_mfma_f32_32x32x16_bf16 v[48:63], v[64:67], v[144:147], v[48:63]
	ds_read_b64_tr_b16 v[172:173], v244 offset:12800
	ds_read_b64_tr_b16 v[174:175], v244 offset:14848
	s_waitcnt lgkmcnt(12)
	v_mfma_f32_32x32x16_bf16 v[48:63], v[68:71], v[148:151], v[48:63]
	ds_read_b64_tr_b16 v[144:145], v244 offset:1024
	ds_read_b64_tr_b16 v[146:147], v244 offset:3072
	s_waitcnt lgkmcnt(12)
	v_mfma_f32_32x32x16_bf16 v[48:63], v[80:83], v[152:155], v[48:63]
	v_exp_f32_e32 v208, v208
	v_exp_f32_e32 v209, v209
	ds_read_b64_tr_b16 v[148:149], v244 offset:5120
	ds_read_b64_tr_b16 v[150:151], v244 offset:7168
	s_waitcnt lgkmcnt(12)
	v_mfma_f32_32x32x16_bf16 v[48:63], v[84:87], v[156:159], v[48:63]
	v_exp_f32_e32 v210, v210
	v_exp_f32_e32 v211, v211
	ds_read_b64_tr_b16 v[152:153], v244 offset:9216
	ds_read_b64_tr_b16 v[154:155], v244 offset:11264
	s_waitcnt lgkmcnt(12)
	v_mfma_f32_32x32x16_bf16 v[32:47], v[64:67], v[160:163], v[32:47]
	v_exp_f32_e32 v212, v212
	ds_read_b64_tr_b16 v[156:157], v244 offset:13312
	ds_read_b64_tr_b16 v[158:159], v244 offset:15360
	s_waitcnt lgkmcnt(12)
	v_mfma_f32_32x32x16_bf16 v[32:47], v[68:71], v[164:167], v[32:47]
	v_exp_f32_e32 v213, v213
	ds_read_b64_tr_b16 v[160:161], v244 offset:1536
	ds_read_b64_tr_b16 v[162:163], v244 offset:3584
	s_waitcnt lgkmcnt(12)
	v_mfma_f32_32x32x16_bf16 v[32:47], v[80:83], v[168:171], v[32:47]
	v_exp_f32_e32 v214, v214
	ds_read_b64_tr_b16 v[164:165], v244 offset:5632
	ds_read_b64_tr_b16 v[166:167], v244 offset:7680
	s_waitcnt lgkmcnt(12)
	v_mfma_f32_32x32x16_bf16 v[32:47], v[84:87], v[172:175], v[32:47]
	v_exp_f32_e32 v215, v215
	ds_read_b64_tr_b16 v[168:169], v244 offset:9728
	ds_read_b64_tr_b16 v[170:171], v244 offset:11776
	s_waitcnt lgkmcnt(12)
	v_mfma_f32_32x32x16_bf16 v[16:31], v[64:67], v[144:147], v[16:31]
	v_exp_f32_e32 v216, v216
	ds_read_b64_tr_b16 v[172:173], v244 offset:13824
	ds_read_b64_tr_b16 v[174:175], v244 offset:15872
	s_waitcnt lgkmcnt(12)
	v_mfma_f32_32x32x16_bf16 v[16:31], v[68:71], v[148:151], v[16:31]
	v_exp_f32_e32 v217, v217
	v_add_u32_e32 v244, 0xffff8000, v244
	ds_read_b128 v[144:147], v240 offset:0
	s_waitcnt lgkmcnt(11)
	v_mfma_f32_32x32x16_bf16 v[16:31], v[80:83], v[152:155], v[16:31]
	v_exp_f32_e32 v218, v218
	ds_read_b128 v[148:151], v240 offset:12288
	s_waitcnt lgkmcnt(10)
	v_mfma_f32_32x32x16_bf16 v[16:31], v[84:87], v[156:159], v[16:31]
	v_exp_f32_e32 v219, v219
	ds_read_b128 v[152:155], v241 offset:0
	s_waitcnt lgkmcnt(9)
	v_mfma_f32_32x32x16_bf16 v[0:15], v[64:67], v[160:163], v[0:15]
	v_exp_f32_e32 v220, v220
	ds_read_b128 v[156:159], v241 offset:12288
	s_waitcnt lgkmcnt(8)
	v_mfma_f32_32x32x16_bf16 v[0:15], v[68:71], v[164:167], v[0:15]
	v_exp_f32_e32 v221, v221
	ds_read_b128 v[160:163], v242 offset:0
	s_waitcnt lgkmcnt(7)
	v_mfma_f32_32x32x16_bf16 v[0:15], v[80:83], v[168:171], v[0:15]
	v_exp_f32_e32 v222, v222
	ds_read_b128 v[164:167], v242 offset:12288
	s_waitcnt lgkmcnt(6)
	v_mfma_f32_32x32x16_bf16 v[0:15], v[84:87], v[172:175], v[0:15]
	v_exp_f32_e32 v223, v223
	s_waitcnt vmcnt(5)
	s_barrier
	ds_read_b128 v[168:171], v243 offset:0
	s_waitcnt lgkmcnt(6)
	v_mfma_f32_32x32x16_bf16 v[64:79], v[144:147], v[96:99], 0
	v_exp_f32_e32 v224, v224
	v_add_f32_e32 v245, v208, v245
	v_exp_f32_e32 v225, v225
	ds_read_b128 v[172:175], v243 offset:12288
	s_waitcnt lgkmcnt(6)
	v_mfma_f32_32x32x16_bf16 v[80:95], v[148:151], v[96:99], 0
	v_add_f32_e32 v246, v209, v246
	v_exp_f32_e32 v226, v226
	v_add_f32_e32 v245, v210, v245
	ds_read_b128 v[144:147], v240 offset:128
	s_waitcnt lgkmcnt(6)
	v_mfma_f32_32x32x16_bf16 v[64:79], v[152:155], v[100:103], v[64:79]
	v_exp_f32_e32 v227, v227
	v_add_f32_e32 v246, v211, v246
	s_add_i32 m0, s60, 0xc000
	s_nop 0
	global_load_lds_dwordx4 v182, s[42:43]
	ds_read_b128 v[148:151], v240 offset:12416
	s_waitcnt lgkmcnt(6)
	v_mfma_f32_32x32x16_bf16 v[80:95], v[156:159], v[100:103], v[80:95]
	v_exp_f32_e32 v228, v228
	v_add_f32_e32 v245, v212, v245
	v_exp_f32_e32 v229, v229
	ds_read_b128 v[152:155], v241 offset:128
	s_waitcnt lgkmcnt(6)
	v_mfma_f32_32x32x16_bf16 v[64:79], v[160:163], v[104:107], v[64:79]
	v_add_f32_e32 v246, v213, v246
	v_exp_f32_e32 v230, v230
	v_add_f32_e32 v245, v214, v245
	ds_read_b128 v[156:159], v241 offset:12416
	s_waitcnt lgkmcnt(6)
	v_mfma_f32_32x32x16_bf16 v[80:95], v[164:167], v[104:107], v[80:95]
	v_exp_f32_e32 v231, v231
	v_add_f32_e32 v246, v215, v246
	s_add_i32 m0, s60, 0xc400
	s_nop 0
	global_load_lds_dwordx4 v183, s[42:43]
	ds_read_b128 v[160:163], v242 offset:128
	s_waitcnt lgkmcnt(6)
	v_mfma_f32_32x32x16_bf16 v[64:79], v[168:171], v[108:111], v[64:79]
	v_exp_f32_e32 v232, v232
	v_add_f32_e32 v245, v216, v245
	v_exp_f32_e32 v233, v233
	ds_read_b128 v[164:167], v242 offset:12416
	s_waitcnt lgkmcnt(6)
	v_mfma_f32_32x32x16_bf16 v[80:95], v[172:175], v[108:111], v[80:95]
	v_add_f32_e32 v246, v217, v246
	v_exp_f32_e32 v234, v234
	v_add_f32_e32 v245, v218, v245
	ds_read_b128 v[168:171], v243 offset:128
	s_waitcnt lgkmcnt(6)
	v_mfma_f32_32x32x16_bf16 v[64:79], v[144:147], v[112:115], v[64:79]
	v_exp_f32_e32 v235, v235
	v_add_f32_e32 v246, v219, v246
	s_add_i32 m0, s60, 0xc800
	s_nop 0
	global_load_lds_dwordx4 v184, s[42:43]
	ds_read_b128 v[172:175], v243 offset:12416
	s_waitcnt lgkmcnt(6)
	v_mfma_f32_32x32x16_bf16 v[80:95], v[148:151], v[112:115], v[80:95]
	v_exp_f32_e32 v236, v236
	v_add_f32_e32 v245, v220, v245
	v_exp_f32_e32 v237, v237
	ds_read_b128 v[144:147], v240 offset:256
	s_waitcnt lgkmcnt(6)
	v_mfma_f32_32x32x16_bf16 v[64:79], v[152:155], v[116:119], v[64:79]
	v_add_f32_e32 v246, v221, v246
	v_exp_f32_e32 v238, v238
	v_add_f32_e32 v245, v222, v245
	ds_read_b128 v[148:151], v240 offset:12544
	s_waitcnt lgkmcnt(6)
	v_mfma_f32_32x32x16_bf16 v[80:95], v[156:159], v[116:119], v[80:95]
	v_exp_f32_e32 v239, v239
	v_add_f32_e32 v246, v223, v246
	s_add_i32 m0, s61, 0x8000
	s_nop 0
	global_load_lds_dwordx4 v185, s[46:47]
	ds_read_b128 v[152:155], v241 offset:256
	s_waitcnt lgkmcnt(6)
	v_mfma_f32_32x32x16_bf16 v[64:79], v[160:163], v[120:123], v[64:79]
	v_add_f32_e32 v245, v224, v245
	v_add_f32_e32 v246, v225, v246
	v_add_f32_e32 v245, v226, v245
	ds_read_b128 v[156:159], v241 offset:12544
	s_waitcnt lgkmcnt(6)
	v_mfma_f32_32x32x16_bf16 v[80:95], v[164:167], v[120:123], v[80:95]
	v_add_f32_e32 v246, v227, v246
	v_add_f32_e32 v245, v228, v245
	v_add_f32_e32 v246, v229, v246
	ds_read_b128 v[160:163], v242 offset:256
	s_waitcnt lgkmcnt(6)
	v_mfma_f32_32x32x16_bf16 v[64:79], v[168:171], v[124:127], v[64:79]
	v_add_f32_e32 v245, v230, v245
	v_add_f32_e32 v246, v231, v246
	s_add_i32 m0, s61, 0x8400
	s_nop 0
	global_load_lds_dwordx4 v186, s[46:47]
	ds_read_b128 v[164:167], v242 offset:12544
	s_waitcnt lgkmcnt(6)
	v_mfma_f32_32x32x16_bf16 v[80:95], v[172:175], v[124:127], v[80:95]
	v_add_f32_e32 v245, v232, v245
	v_add_f32_e32 v246, v233, v246
	v_add_f32_e32 v245, v234, v245
	ds_read_b128 v[168:171], v243 offset:256
	s_waitcnt lgkmcnt(6)
	v_mfma_f32_32x32x16_bf16 v[64:79], v[144:147], v[128:131], v[64:79]
	v_add_f32_e32 v246, v235, v246
	v_add_f32_e32 v245, v236, v245
	v_add_f32_e32 v246, v237, v246
	ds_read_b128 v[172:175], v243 offset:12544
	s_waitcnt lgkmcnt(6)
	v_mfma_f32_32x32x16_bf16 v[80:95], v[148:151], v[128:131], v[80:95]
	v_add_f32_e32 v245, v238, v245
	v_add_f32_e32 v246, v239, v246
	s_add_u32 s42, s42, 0x6000
	s_addc_u32 s43, s43, 0
	v_add_u32_e32 v240, 0x6000, v240
	ds_read_b64_tr_b16 v[144:145], v244 offset:0
	ds_read_b64_tr_b16 v[146:147], v244 offset:2048
	s_waitcnt lgkmcnt(7)
	v_mfma_f32_32x32x16_bf16 v[64:79], v[152:155], v[132:135], v[64:79]
	v_cvt_pk_bf16_f32 v208, v208, v209
	v_cvt_pk_bf16_f32 v209, v210, v211
	v_cvt_pk_bf16_f32 v210, v212, v213
	v_add_u32_e32 v241, 0x6000, v241
	ds_read_b64_tr_b16 v[148:149], v244 offset:4096
	ds_read_b64_tr_b16 v[150:151], v244 offset:6144
	s_waitcnt lgkmcnt(8)
	v_mfma_f32_32x32x16_bf16 v[80:95], v[156:159], v[132:135], v[80:95]
	v_cvt_pk_bf16_f32 v211, v214, v215
	v_cvt_pk_bf16_f32 v212, v216, v217
	v_cvt_pk_bf16_f32 v213, v218, v219
	v_add_u32_e32 v242, 0x6000, v242
	ds_read_b64_tr_b16 v[152:153], v244 offset:8192
	ds_read_b64_tr_b16 v[154:155], v244 offset:10240
	s_waitcnt lgkmcnt(9)
	v_mfma_f32_32x32x16_bf16 v[64:79], v[160:163], v[136:139], v[64:79]
	v_cvt_pk_bf16_f32 v214, v220, v221
	v_cvt_pk_bf16_f32 v215, v222, v223
	s_add_u32 s46, s46, 0x40000
	s_addc_u32 s47, s47, 0
	v_add_u32_e32 v243, 0x6000, v243
	ds_read_b64_tr_b16 v[156:157], v244 offset:12288
	ds_read_b64_tr_b16 v[158:159], v244 offset:14336
	s_waitcnt lgkmcnt(10)
	v_mfma_f32_32x32x16_bf16 v[80:95], v[164:167], v[136:139], v[80:95]
	v_cvt_pk_bf16_f32 v224, v224, v225
	v_cvt_pk_bf16_f32 v225, v226, v227
	v_cvt_pk_bf16_f32 v226, v228, v229
	ds_read_b64_tr_b16 v[160:161], v244 offset:512
	ds_read_b64_tr_b16 v[162:163], v244 offset:2560
	s_waitcnt lgkmcnt(11)
	v_mfma_f32_32x32x16_bf16 v[64:79], v[168:171], v[140:143], v[64:79]
	v_cvt_pk_bf16_f32 v227, v230, v231
	v_cvt_pk_bf16_f32 v228, v232, v233
	v_cvt_pk_bf16_f32 v229, v234, v235
	ds_read_b64_tr_b16 v[164:165], v244 offset:4608
	ds_read_b64_tr_b16 v[166:167], v244 offset:6656
	s_waitcnt lgkmcnt(12)
	v_mfma_f32_32x32x16_bf16 v[80:95], v[172:175], v[140:143], v[80:95]
	v_cvt_pk_bf16_f32 v230, v236, v237
	v_cvt_pk_bf16_f32 v231, v238, v239
	ds_read_b64_tr_b16 v[168:169], v244 offset:8704
	ds_read_b64_tr_b16 v[170:171], v244 offset:10752
	s_waitcnt lgkmcnt(12)
	v_mfma_f32_32x32x16_bf16 v[48:63], v[208:211], v[144:147], v[48:63]
	ds_read_b64_tr_b16 v[172:173], v244 offset:12800
	ds_read_b64_tr_b16 v[174:175], v244 offset:14848
	s_waitcnt lgkmcnt(12)
	v_mfma_f32_32x32x16_bf16 v[48:63], v[212:215], v[148:151], v[48:63]
	ds_read_b64_tr_b16 v[144:145], v244 offset:1024
	ds_read_b64_tr_b16 v[146:147], v244 offset:3072
	s_waitcnt lgkmcnt(12)
	v_mfma_f32_32x32x16_bf16 v[48:63], v[224:227], v[152:155], v[48:63]
	v_exp_f32_e32 v64, v64
	v_exp_f32_e32 v65, v65
	ds_read_b64_tr_b16 v[148:149], v244 offset:5120
	ds_read_b64_tr_b16 v[150:151], v244 offset:7168
	s_waitcnt lgkmcnt(12)
	v_mfma_f32_32x32x16_bf16 v[48:63], v[228:231], v[156:159], v[48:63]
	v_exp_f32_e32 v66, v66
	v_exp_f32_e32 v67, v67
	ds_read_b64_tr_b16 v[152:153], v244 offset:9216
	ds_read_b64_tr_b16 v[154:155], v244 offset:11264
	s_waitcnt lgkmcnt(12)
	v_mfma_f32_32x32x16_bf16 v[32:47], v[208:211], v[160:163], v[32:47]
	v_exp_f32_e32 v68, v68
	ds_read_b64_tr_b16 v[156:157], v244 offset:13312
	ds_read_b64_tr_b16 v[158:159], v244 offset:15360
	s_waitcnt lgkmcnt(12)
	v_mfma_f32_32x32x16_bf16 v[32:47], v[212:215], v[164:167], v[32:47]
	v_exp_f32_e32 v69, v69
	ds_read_b64_tr_b16 v[160:161], v244 offset:1536
	ds_read_b64_tr_b16 v[162:163], v244 offset:3584
	s_waitcnt lgkmcnt(12)
	v_mfma_f32_32x32x16_bf16 v[32:47], v[224:227], v[168:171], v[32:47]
	v_exp_f32_e32 v70, v70
	ds_read_b64_tr_b16 v[164:165], v244 offset:5632
	ds_read_b64_tr_b16 v[166:167], v244 offset:7680
	s_waitcnt lgkmcnt(12)
	v_mfma_f32_32x32x16_bf16 v[32:47], v[228:231], v[172:175], v[32:47]
	v_exp_f32_e32 v71, v71
	ds_read_b64_tr_b16 v[168:169], v244 offset:9728
	ds_read_b64_tr_b16 v[170:171], v244 offset:11776
	s_waitcnt lgkmcnt(12)
	v_mfma_f32_32x32x16_bf16 v[16:31], v[208:211], v[144:147], v[16:31]
	v_exp_f32_e32 v72, v72
	ds_read_b64_tr_b16 v[172:173], v244 offset:13824
	ds_read_b64_tr_b16 v[174:175], v244 offset:15872
	s_waitcnt lgkmcnt(12)
	v_mfma_f32_32x32x16_bf16 v[16:31], v[212:215], v[148:151], v[16:31]
	v_exp_f32_e32 v73, v73
	v_add_u32_e32 v244, 0x4000, v244
	ds_read_b128 v[144:147], v240 offset:0
	s_waitcnt lgkmcnt(11)
	v_mfma_f32_32x32x16_bf16 v[16:31], v[224:227], v[152:155], v[16:31]
	v_exp_f32_e32 v74, v74
	ds_read_b128 v[148:151], v240 offset:12288
	s_waitcnt lgkmcnt(10)
	v_mfma_f32_32x32x16_bf16 v[16:31], v[228:231], v[156:159], v[16:31]
	v_exp_f32_e32 v75, v75
	ds_read_b128 v[152:155], v241 offset:0
	s_waitcnt lgkmcnt(9)
	v_mfma_f32_32x32x16_bf16 v[0:15], v[208:211], v[160:163], v[0:15]
	v_exp_f32_e32 v76, v76
	ds_read_b128 v[156:159], v241 offset:12288
	s_waitcnt lgkmcnt(8)
	v_mfma_f32_32x32x16_bf16 v[0:15], v[212:215], v[164:167], v[0:15]
	v_exp_f32_e32 v77, v77
	ds_read_b128 v[160:163], v242 offset:0
	s_waitcnt lgkmcnt(7)
	v_mfma_f32_32x32x16_bf16 v[0:15], v[224:227], v[168:171], v[0:15]
	v_exp_f32_e32 v78, v78
	ds_read_b128 v[164:167], v242 offset:12288
	s_waitcnt lgkmcnt(6)
	v_mfma_f32_32x32x16_bf16 v[0:15], v[228:231], v[172:175], v[0:15]
	v_exp_f32_e32 v79, v79
	s_sub_i32 s78, s78, 1
	s_cmp_lg_u32 s78, 0
	s_cbranch_scc1 .Lattn_loop
	s_waitcnt vmcnt(5)
	s_barrier
	ds_read_b128 v[168:171], v243 offset:0
	s_waitcnt lgkmcnt(6)
	v_mfma_f32_32x32x16_bf16 v[208:223], v[144:147], v[96:99], 0
	v_exp_f32_e32 v80, v80
	v_add_f32_e32 v245, v64, v245
	v_exp_f32_e32 v81, v81
	ds_read_b128 v[172:175], v243 offset:12288
	s_waitcnt lgkmcnt(6)
	v_mfma_f32_32x32x16_bf16 v[224:239], v[148:151], v[96:99], 0
	v_add_f32_e32 v246, v65, v246
	v_exp_f32_e32 v82, v82
	v_add_f32_e32 v245, v66, v245
	ds_read_b128 v[144:147], v240 offset:128
	s_waitcnt lgkmcnt(6)
	v_mfma_f32_32x32x16_bf16 v[208:223], v[152:155], v[100:103], v[208:223]
	v_exp_f32_e32 v83, v83
	v_add_f32_e32 v246, v67, v246
	s_add_i32 m0, s60, 0x12000
	s_nop 0
	global_load_lds_dwordx4 v182, s[42:43]
	ds_read_b128 v[148:151], v240 offset:12416
	s_waitcnt lgkmcnt(6)
	v_mfma_f32_32x32x16_bf16 v[224:239], v[156:159], v[100:103], v[224:239]
	v_exp_f32_e32 v84, v84
	v_add_f32_e32 v245, v68, v245
	v_exp_f32_e32 v85, v85
	ds_read_b128 v[152:155], v241 offset:128
	s_waitcnt lgkmcnt(6)
	v_mfma_f32_32x32x16_bf16 v[208:223], v[160:163], v[104:107], v[208:223]
	v_add_f32_e32 v246, v69, v246
	v_exp_f32_e32 v86, v86
	v_add_f32_e32 v245, v70, v245
	ds_read_b128 v[156:159], v241 offset:12416
	s_waitcnt lgkmcnt(6)
	v_mfma_f32_32x32x16_bf16 v[224:239], v[164:167], v[104:107], v[224:239]
	v_exp_f32_e32 v87, v87
	v_add_f32_e32 v246, v71, v246
	s_add_i32 m0, s60, 0x12400
	s_nop 0
	global_load_lds_dwordx4 v183, s[42:43]
	ds_read_b128 v[160:163], v242 offset:128
	s_waitcnt lgkmcnt(6)
	v_mfma_f32_32x32x16_bf16 v[208:223], v[168:171], v[108:111], v[208:223]
	v_exp_f32_e32 v88, v88
	v_add_f32_e32 v245, v72, v245
	v_exp_f32_e32 v89, v89
	ds_read_b128 v[164:167], v242 offset:12416
	s_waitcnt lgkmcnt(6)
	v_mfma_f32_32x32x16_bf16 v[224:239], v[172:175], v[108:111], v[224:239]
	v_add_f32_e32 v246, v73, v246
	v_exp_f32_e32 v90, v90
	v_add_f32_e32 v245, v74, v245
	ds_read_b128 v[168:171], v243 offset:128
	s_waitcnt lgkmcnt(6)
	v_mfma_f32_32x32x16_bf16 v[208:223], v[144:147], v[112:115], v[208:223]
	v_exp_f32_e32 v91, v91
	v_add_f32_e32 v246, v75, v246
	s_add_i32 m0, s60, 0x12800
	s_nop 0
	global_load_lds_dwordx4 v184, s[42:43]
	ds_read_b128 v[172:175], v243 offset:12416
	s_waitcnt lgkmcnt(6)
	v_mfma_f32_32x32x16_bf16 v[224:239], v[148:151], v[112:115], v[224:239]
	v_exp_f32_e32 v92, v92
	v_add_f32_e32 v245, v76, v245
	v_exp_f32_e32 v93, v93
	ds_read_b128 v[144:147], v240 offset:256
	s_waitcnt lgkmcnt(6)
	v_mfma_f32_32x32x16_bf16 v[208:223], v[152:155], v[116:119], v[208:223]
	v_add_f32_e32 v246, v77, v246
	v_exp_f32_e32 v94, v94
	v_add_f32_e32 v245, v78, v245
	ds_read_b128 v[148:151], v240 offset:12544
	s_waitcnt lgkmcnt(6)
	v_mfma_f32_32x32x16_bf16 v[224:239], v[156:159], v[116:119], v[224:239]
	v_exp_f32_e32 v95, v95
	v_add_f32_e32 v246, v79, v246
	s_add_i32 m0, s61, 0x0
	s_nop 0
	global_load_lds_dwordx4 v185, s[46:47]
	ds_read_b128 v[152:155], v241 offset:256
	s_waitcnt lgkmcnt(6)
	v_mfma_f32_32x32x16_bf16 v[208:223], v[160:163], v[120:123], v[208:223]
	v_add_f32_e32 v245, v80, v245
	v_add_f32_e32 v246, v81, v246
	v_add_f32_e32 v245, v82, v245
	ds_read_b128 v[156:159], v241 offset:12544
	s_waitcnt lgkmcnt(6)
	v_mfma_f32_32x32x16_bf16 v[224:239], v[164:167], v[120:123], v[224:239]
	v_add_f32_e32 v246, v83, v246
	v_add_f32_e32 v245, v84, v245
	v_add_f32_e32 v246, v85, v246
	ds_read_b128 v[160:163], v242 offset:256
	s_waitcnt lgkmcnt(6)
	v_mfma_f32_32x32x16_bf16 v[208:223], v[168:171], v[124:127], v[208:223]
	v_add_f32_e32 v245, v86, v245
	v_add_f32_e32 v246, v87, v246
	s_add_i32 m0, s61, 0x400
	s_nop 0
	global_load_lds_dwordx4 v186, s[46:47]
	ds_read_b128 v[164:167], v242 offset:12544
	s_waitcnt lgkmcnt(6)
	v_mfma_f32_32x32x16_bf16 v[224:239], v[172:175], v[124:127], v[224:239]
	v_add_f32_e32 v245, v88, v245
	v_add_f32_e32 v246, v89, v246
	v_add_f32_e32 v245, v90, v245
	ds_read_b128 v[168:171], v243 offset:256
	s_waitcnt lgkmcnt(6)
	v_mfma_f32_32x32x16_bf16 v[208:223], v[144:147], v[128:131], v[208:223]
	v_add_f32_e32 v246, v91, v246
	v_add_f32_e32 v245, v92, v245
	v_add_f32_e32 v246, v93, v246
	ds_read_b128 v[172:175], v243 offset:12544
	s_waitcnt lgkmcnt(6)
	v_mfma_f32_32x32x16_bf16 v[224:239], v[148:151], v[128:131], v[224:239]
	v_add_f32_e32 v245, v94, v245
	v_add_f32_e32 v246, v95, v246
	s_add_u32 s42, s42, 0x6000
	s_addc_u32 s43, s43, 0
	v_add_u32_e32 v240, 0x9010, v240
	ds_read_b64_tr_b16 v[144:145], v244 offset:0
	ds_read_b64_tr_b16 v[146:147], v244 offset:2048
	s_waitcnt lgkmcnt(7)
	v_mfma_f32_32x32x16_bf16 v[208:223], v[152:155], v[132:135], v[208:223]
	v_cvt_pk_bf16_f32 v64, v64, v65
	v_cvt_pk_bf16_f32 v65, v66, v67
	v_cvt_pk_bf16_f32 v66, v68, v69
	v_add_u32_e32 v241, 0x9010, v241
	ds_read_b64_tr_b16 v[148:149], v244 offset:4096
	ds_read_b64_tr_b16 v[150:151], v244 offset:6144
	s_waitcnt lgkmcnt(8)
	v_mfma_f32_32x32x16_bf16 v[224:239], v[156:159], v[132:135], v[224:239]
	v_cvt_pk_bf16_f32 v67, v70, v71
	v_cvt_pk_bf16_f32 v68, v72, v73
	v_cvt_pk_bf16_f32 v69, v74, v75
	v_add_u32_e32 v242, 0x9010, v242
	ds_read_b64_tr_b16 v[152:153], v244 offset:8192
	ds_read_b64_tr_b16 v[154:155], v244 offset:10240
	s_waitcnt lgkmcnt(9)
	v_mfma_f32_32x32x16_bf16 v[208:223], v[160:163], v[136:139], v[208:223]
	v_cvt_pk_bf16_f32 v70, v76, v77
	v_cvt_pk_bf16_f32 v71, v78, v79
	s_add_u32 s46, s46, 0x40000
	s_addc_u32 s47, s47, 0
	v_add_u32_e32 v243, 0x9010, v243
	ds_read_b64_tr_b16 v[156:157], v244 offset:12288
	ds_read_b64_tr_b16 v[158:159], v244 offset:14336
	s_waitcnt lgkmcnt(10)
	v_mfma_f32_32x32x16_bf16 v[224:239], v[164:167], v[136:139], v[224:239]
	v_cvt_pk_bf16_f32 v80, v80, v81
	v_cvt_pk_bf16_f32 v81, v82, v83
	v_cvt_pk_bf16_f32 v82, v84, v85
	ds_read_b64_tr_b16 v[160:161], v244 offset:512
	ds_read_b64_tr_b16 v[162:163], v244 offset:2560
	s_waitcnt lgkmcnt(11)
	v_mfma_f32_32x32x16_bf16 v[208:223], v[168:171], v[140:143], v[208:223]
	v_cvt_pk_bf16_f32 v83, v86, v87
	v_cvt_pk_bf16_f32 v84, v88, v89
	v_cvt_pk_bf16_f32 v85, v90, v91
	ds_read_b64_tr_b16 v[164:165], v244 offset:4608
	ds_read_b64_tr_b16 v[166:167], v244 offset:6656
	s_waitcnt lgkmcnt(12)
	v_mfma_f32_32x32x16_bf16 v[224:239], v[172:175], v[140:143], v[224:239]
	v_cvt_pk_bf16_f32 v86, v92, v93
	v_cvt_pk_bf16_f32 v87, v94, v95
	ds_read_b64_tr_b16 v[168:169], v244 offset:8704
	ds_read_b64_tr_b16 v[170:171], v244 offset:10752
	s_waitcnt lgkmcnt(12)
	v_mfma_f32_32x32x16_bf16 v[48:63], v[64:67], v[144:147], v[48:63]
	ds_read_b64_tr_b16 v[172:173], v244 offset:12800
	ds_read_b64_tr_b16 v[174:175], v244 offset:14848
	s_waitcnt lgkmcnt(12)
	v_mfma_f32_32x32x16_bf16 v[48:63], v[68:71], v[148:151], v[48:63]
	ds_read_b64_tr_b16 v[144:145], v244 offset:1024
	ds_read_b64_tr_b16 v[146:147], v244 offset:3072
	s_waitcnt lgkmcnt(12)
	v_mfma_f32_32x32x16_bf16 v[48:63], v[80:83], v[152:155], v[48:63]
	v_exp_f32_e32 v208, v208
	v_exp_f32_e32 v209, v209
	ds_read_b64_tr_b16 v[148:149], v244 offset:5120
	ds_read_b64_tr_b16 v[150:151], v244 offset:7168
	s_waitcnt lgkmcnt(12)
	v_mfma_f32_32x32x16_bf16 v[48:63], v[84:87], v[156:159], v[48:63]
	v_exp_f32_e32 v210, v210
	v_exp_f32_e32 v211, v211
	ds_read_b64_tr_b16 v[152:153], v244 offset:9216
	ds_read_b64_tr_b16 v[154:155], v244 offset:11264
	s_waitcnt lgkmcnt(12)
	v_mfma_f32_32x32x16_bf16 v[32:47], v[64:67], v[160:163], v[32:47]
	v_exp_f32_e32 v212, v212
	ds_read_b64_tr_b16 v[156:157], v244 offset:13312
	ds_read_b64_tr_b16 v[158:159], v244 offset:15360
	s_waitcnt lgkmcnt(12)
	v_mfma_f32_32x32x16_bf16 v[32:47], v[68:71], v[164:167], v[32:47]
	v_exp_f32_e32 v213, v213
	ds_read_b64_tr_b16 v[160:161], v244 offset:1536
	ds_read_b64_tr_b16 v[162:163], v244 offset:3584
	s_waitcnt lgkmcnt(12)
	v_mfma_f32_32x32x16_bf16 v[32:47], v[80:83], v[168:171], v[32:47]
	v_exp_f32_e32 v214, v214
	ds_read_b64_tr_b16 v[164:165], v244 offset:5632
	ds_read_b64_tr_b16 v[166:167], v244 offset:7680
	s_waitcnt lgkmcnt(12)
	v_mfma_f32_32x32x16_bf16 v[32:47], v[84:87], v[172:175], v[32:47]
	v_exp_f32_e32 v215, v215
	ds_read_b64_tr_b16 v[168:169], v244 offset:9728
	ds_read_b64_tr_b16 v[170:171], v244 offset:11776
	s_waitcnt lgkmcnt(12)
	v_mfma_f32_32x32x16_bf16 v[16:31], v[64:67], v[144:147], v[16:31]
	v_exp_f32_e32 v216, v216
	ds_read_b64_tr_b16 v[172:173], v244 offset:13824
	ds_read_b64_tr_b16 v[174:175], v244 offset:15872
	s_waitcnt lgkmcnt(12)
	v_mfma_f32_32x32x16_bf16 v[16:31], v[68:71], v[148:151], v[16:31]
	v_exp_f32_e32 v217, v217
	v_add_u32_e32 v244, 0x4000, v244
	ds_read_b128 v[144:147], v240 offset:0
	s_waitcnt lgkmcnt(11)
	v_mfma_f32_32x32x16_bf16 v[16:31], v[80:83], v[152:155], v[16:31]
	v_exp_f32_e32 v218, v218
	ds_read_b128 v[148:151], v240 offset:12288
	s_waitcnt lgkmcnt(10)
	v_mfma_f32_32x32x16_bf16 v[16:31], v[84:87], v[156:159], v[16:31]
	v_exp_f32_e32 v219, v219
	ds_read_b128 v[152:155], v241 offset:0
	s_waitcnt lgkmcnt(9)
	v_mfma_f32_32x32x16_bf16 v[0:15], v[64:67], v[160:163], v[0:15]
	v_exp_f32_e32 v220, v220
	ds_read_b128 v[156:159], v241 offset:12288
	s_waitcnt lgkmcnt(8)
	v_mfma_f32_32x32x16_bf16 v[0:15], v[68:71], v[164:167], v[0:15]
	v_exp_f32_e32 v221, v221
	ds_read_b128 v[160:163], v242 offset:0
	s_waitcnt lgkmcnt(7)
	v_mfma_f32_32x32x16_bf16 v[0:15], v[80:83], v[168:171], v[0:15]
	v_exp_f32_e32 v222, v222
	ds_read_b128 v[164:167], v242 offset:12288
	s_waitcnt lgkmcnt(6)
	v_mfma_f32_32x32x16_bf16 v[0:15], v[84:87], v[172:175], v[0:15]
	v_exp_f32_e32 v223, v223
	s_waitcnt vmcnt(5)
	s_barrier
	ds_read_b128 v[168:171], v243 offset:0
	s_waitcnt lgkmcnt(6)
	v_mfma_f32_32x32x16_bf16 v[64:79], v[144:147], v[96:99], 0
	v_exp_f32_e32 v224, v224
	v_add_f32_e32 v245, v208, v245
	v_exp_f32_e32 v225, v225
	ds_read_b128 v[172:175], v243 offset:12288
	s_waitcnt lgkmcnt(6)
	v_mfma_f32_32x32x16_bf16 v[80:95], v[148:151], v[96:99], 0
	v_add_f32_e32 v246, v209, v246
	v_exp_f32_e32 v226, v226
	v_add_f32_e32 v245, v210, v245
	ds_read_b128 v[144:147], v240 offset:128
	s_waitcnt lgkmcnt(6)
	v_mfma_f32_32x32x16_bf16 v[64:79], v[152:155], v[100:103], v[64:79]
	v_exp_f32_e32 v227, v227
	v_add_f32_e32 v246, v211, v246
	s_add_i32 m0, s60, 0x18000
	s_nop 0
	global_load_lds_dwordx4 v182, s[42:43]
	ds_read_b128 v[148:151], v240 offset:12416
	s_waitcnt lgkmcnt(6)
	v_mfma_f32_32x32x16_bf16 v[80:95], v[156:159], v[100:103], v[80:95]
	v_exp_f32_e32 v228, v228
	v_add_f32_e32 v245, v212, v245
	v_exp_f32_e32 v229, v229
	ds_read_b128 v[152:155], v241 offset:128
	s_waitcnt lgkmcnt(6)
	v_mfma_f32_32x32x16_bf16 v[64:79], v[160:163], v[104:107], v[64:79]
	v_add_f32_e32 v246, v213, v246
	v_exp_f32_e32 v230, v230
	v_add_f32_e32 v245, v214, v245
	ds_read_b128 v[156:159], v241 offset:12416
	s_waitcnt lgkmcnt(6)
	v_mfma_f32_32x32x16_bf16 v[80:95], v[164:167], v[104:107], v[80:95]
	v_exp_f32_e32 v231, v231
	v_add_f32_e32 v246, v215, v246
	s_add_i32 m0, s60, 0x18400
	s_nop 0
	global_load_lds_dwordx4 v183, s[42:43]
	ds_read_b128 v[160:163], v242 offset:128
	s_waitcnt lgkmcnt(6)
	v_mfma_f32_32x32x16_bf16 v[64:79], v[168:171], v[108:111], v[64:79]
	v_exp_f32_e32 v232, v232
	v_add_f32_e32 v245, v216, v245
	v_exp_f32_e32 v233, v233
	ds_read_b128 v[164:167], v242 offset:12416
	s_waitcnt lgkmcnt(6)
	v_mfma_f32_32x32x16_bf16 v[80:95], v[172:175], v[108:111], v[80:95]
	v_add_f32_e32 v246, v217, v246
	v_exp_f32_e32 v234, v234
	v_add_f32_e32 v245, v218, v245
	ds_read_b128 v[168:171], v243 offset:128
	s_waitcnt lgkmcnt(6)
	v_mfma_f32_32x32x16_bf16 v[64:79], v[144:147], v[112:115], v[64:79]
	v_exp_f32_e32 v235, v235
	v_add_f32_e32 v246, v219, v246
	s_add_i32 m0, s60, 0x18800
	s_nop 0
	global_load_lds_dwordx4 v184, s[42:43]
	ds_read_b128 v[172:175], v243 offset:12416
	s_waitcnt lgkmcnt(6)
	v_mfma_f32_32x32x16_bf16 v[80:95], v[148:151], v[112:115], v[80:95]
	v_exp_f32_e32 v236, v236
	v_add_f32_e32 v245, v220, v245
	v_exp_f32_e32 v237, v237
	ds_read_b128 v[144:147], v240 offset:256
	s_waitcnt lgkmcnt(6)
	v_mfma_f32_32x32x16_bf16 v[64:79], v[152:155], v[116:119], v[64:79]
	v_add_f32_e32 v246, v221, v246
	v_exp_f32_e32 v238, v238
	v_add_f32_e32 v245, v222, v245
	ds_read_b128 v[148:151], v240 offset:12544
	s_waitcnt lgkmcnt(6)
	v_mfma_f32_32x32x16_bf16 v[80:95], v[156:159], v[116:119], v[80:95]
	v_exp_f32_e32 v239, v239
	v_add_f32_e32 v246, v223, v246
	s_add_i32 m0, s61, 0x4000
	s_nop 0
	global_load_lds_dwordx4 v185, s[46:47]
	ds_read_b128 v[152:155], v241 offset:256
	s_waitcnt lgkmcnt(6)
	v_mfma_f32_32x32x16_bf16 v[64:79], v[160:163], v[120:123], v[64:79]
	v_add_f32_e32 v245, v224, v245
	v_add_f32_e32 v246, v225, v246
	v_add_f32_e32 v245, v226, v245
	ds_read_b128 v[156:159], v241 offset:12544
	s_waitcnt lgkmcnt(6)
	v_mfma_f32_32x32x16_bf16 v[80:95], v[164:167], v[120:123], v[80:95]
	v_add_f32_e32 v246, v227, v246
	v_add_f32_e32 v245, v228, v245
	v_add_f32_e32 v246, v229, v246
	ds_read_b128 v[160:163], v242 offset:256
	s_waitcnt lgkmcnt(6)
	v_mfma_f32_32x32x16_bf16 v[64:79], v[168:171], v[124:127], v[64:79]
	v_add_f32_e32 v245, v230, v245
	v_add_f32_e32 v246, v231, v246
	s_add_i32 m0, s61, 0x4400
	s_nop 0
	global_load_lds_dwordx4 v186, s[46:47]
	ds_read_b128 v[164:167], v242 offset:12544
	s_waitcnt lgkmcnt(6)
	v_mfma_f32_32x32x16_bf16 v[80:95], v[172:175], v[124:127], v[80:95]
	v_add_f32_e32 v245, v232, v245
	v_add_f32_e32 v246, v233, v246
	v_add_f32_e32 v245, v234, v245
	ds_read_b128 v[168:171], v243 offset:256
	s_waitcnt lgkmcnt(6)
	v_mfma_f32_32x32x16_bf16 v[64:79], v[144:147], v[128:131], v[64:79]
	v_add_f32_e32 v246, v235, v246
	v_add_f32_e32 v245, v236, v245
	v_add_f32_e32 v246, v237, v246
	ds_read_b128 v[172:175], v243 offset:12544
	s_waitcnt lgkmcnt(6)
	v_mfma_f32_32x32x16_bf16 v[80:95], v[148:151], v[128:131], v[80:95]
	v_add_f32_e32 v245, v238, v245
	v_add_f32_e32 v246, v239, v246
	s_add_u32 s42, s42, 0x6000
	s_addc_u32 s43, s43, 0
	v_add_u32_e32 v240, 0xfffeaff0, v240
	ds_read_b64_tr_b16 v[144:145], v244 offset:0
	ds_read_b64_tr_b16 v[146:147], v244 offset:2048
	s_waitcnt lgkmcnt(7)
	v_mfma_f32_32x32x16_bf16 v[64:79], v[152:155], v[132:135], v[64:79]
	v_cvt_pk_bf16_f32 v208, v208, v209
	v_cvt_pk_bf16_f32 v209, v210, v211
	v_cvt_pk_bf16_f32 v210, v212, v213
	v_add_u32_e32 v241, 0xfffeaff0, v241
	ds_read_b64_tr_b16 v[148:149], v244 offset:4096
	ds_read_b64_tr_b16 v[150:151], v244 offset:6144
	s_waitcnt lgkmcnt(8)
	v_mfma_f32_32x32x16_bf16 v[80:95], v[156:159], v[132:135], v[80:95]
	v_cvt_pk_bf16_f32 v211, v214, v215
	v_cvt_pk_bf16_f32 v212, v216, v217
	v_cvt_pk_bf16_f32 v213, v218, v219
	v_add_u32_e32 v242, 0xfffeaff0, v242
	ds_read_b64_tr_b16 v[152:153], v244 offset:8192
	ds_read_b64_tr_b16 v[154:155], v244 offset:10240
	s_waitcnt lgkmcnt(9)
	v_mfma_f32_32x32x16_bf16 v[64:79], v[160:163], v[136:139], v[64:79]
	v_cvt_pk_bf16_f32 v214, v220, v221
	v_cvt_pk_bf16_f32 v215, v222, v223
	s_add_u32 s46, s46, 0x40000
	s_addc_u32 s47, s47, 0
	v_add_u32_e32 v243, 0xfffeaff0, v243
	ds_read_b64_tr_b16 v[156:157], v244 offset:12288
	ds_read_b64_tr_b16 v[158:159], v244 offset:14336
	s_waitcnt lgkmcnt(10)
	v_mfma_f32_32x32x16_bf16 v[80:95], v[164:167], v[136:139], v[80:95]
	v_cvt_pk_bf16_f32 v224, v224, v225
	v_cvt_pk_bf16_f32 v225, v226, v227
	v_cvt_pk_bf16_f32 v226, v228, v229
	ds_read_b64_tr_b16 v[160:161], v244 offset:512
	ds_read_b64_tr_b16 v[162:163], v244 offset:2560
	s_waitcnt lgkmcnt(11)
	v_mfma_f32_32x32x16_bf16 v[64:79], v[168:171], v[140:143], v[64:79]
	v_cvt_pk_bf16_f32 v227, v230, v231
	v_cvt_pk_bf16_f32 v228, v232, v233
	v_cvt_pk_bf16_f32 v229, v234, v235
	ds_read_b64_tr_b16 v[164:165], v244 offset:4608
	ds_read_b64_tr_b16 v[166:167], v244 offset:6656
	s_waitcnt lgkmcnt(12)
	v_mfma_f32_32x32x16_bf16 v[80:95], v[172:175], v[140:143], v[80:95]
	v_cvt_pk_bf16_f32 v230, v236, v237
	v_cvt_pk_bf16_f32 v231, v238, v239
	ds_read_b64_tr_b16 v[168:169], v244 offset:8704
	ds_read_b64_tr_b16 v[170:171], v244 offset:10752
	s_waitcnt lgkmcnt(12)
	v_mfma_f32_32x32x16_bf16 v[48:63], v[208:211], v[144:147], v[48:63]
	ds_read_b64_tr_b16 v[172:173], v244 offset:12800
	ds_read_b64_tr_b16 v[174:175], v244 offset:14848
	s_waitcnt lgkmcnt(12)
	v_mfma_f32_32x32x16_bf16 v[48:63], v[212:215], v[148:151], v[48:63]
	ds_read_b64_tr_b16 v[144:145], v244 offset:1024
	ds_read_b64_tr_b16 v[146:147], v244 offset:3072
	s_waitcnt lgkmcnt(12)
	v_mfma_f32_32x32x16_bf16 v[48:63], v[224:227], v[152:155], v[48:63]
	v_exp_f32_e32 v64, v64
	v_exp_f32_e32 v65, v65
	ds_read_b64_tr_b16 v[148:149], v244 offset:5120
	ds_read_b64_tr_b16 v[150:151], v244 offset:7168
	s_waitcnt lgkmcnt(12)
	v_mfma_f32_32x32x16_bf16 v[48:63], v[228:231], v[156:159], v[48:63]
	v_exp_f32_e32 v66, v66
	v_exp_f32_e32 v67, v67
	ds_read_b64_tr_b16 v[152:153], v244 offset:9216
	ds_read_b64_tr_b16 v[154:155], v244 offset:11264
	s_waitcnt lgkmcnt(12)
	v_mfma_f32_32x32x16_bf16 v[32:47], v[208:211], v[160:163], v[32:47]
	v_exp_f32_e32 v68, v68
	ds_read_b64_tr_b16 v[156:157], v244 offset:13312
	ds_read_b64_tr_b16 v[158:159], v244 offset:15360
	s_waitcnt lgkmcnt(12)
	v_mfma_f32_32x32x16_bf16 v[32:47], v[212:215], v[164:167], v[32:47]
	v_exp_f32_e32 v69, v69
	ds_read_b64_tr_b16 v[160:161], v244 offset:1536
	ds_read_b64_tr_b16 v[162:163], v244 offset:3584
	s_waitcnt lgkmcnt(12)
	v_mfma_f32_32x32x16_bf16 v[32:47], v[224:227], v[168:171], v[32:47]
	v_exp_f32_e32 v70, v70
	ds_read_b64_tr_b16 v[164:165], v244 offset:5632
	ds_read_b64_tr_b16 v[166:167], v244 offset:7680
	s_waitcnt lgkmcnt(12)
	v_mfma_f32_32x32x16_bf16 v[32:47], v[228:231], v[172:175], v[32:47]
	v_exp_f32_e32 v71, v71
	ds_read_b64_tr_b16 v[168:169], v244 offset:9728
	ds_read_b64_tr_b16 v[170:171], v244 offset:11776
	s_waitcnt lgkmcnt(12)
	v_mfma_f32_32x32x16_bf16 v[16:31], v[208:211], v[144:147], v[16:31]
	v_exp_f32_e32 v72, v72
	ds_read_b64_tr_b16 v[172:173], v244 offset:13824
	ds_read_b64_tr_b16 v[174:175], v244 offset:15872
	s_waitcnt lgkmcnt(12)
	v_mfma_f32_32x32x16_bf16 v[16:31], v[212:215], v[148:151], v[16:31]
	v_exp_f32_e32 v73, v73
	v_add_u32_e32 v244, 0xffff8000, v244
	ds_read_b128 v[144:147], v240 offset:0
	s_waitcnt lgkmcnt(11)
	v_mfma_f32_32x32x16_bf16 v[16:31], v[224:227], v[152:155], v[16:31]
	v_exp_f32_e32 v74, v74
	ds_read_b128 v[148:151], v240 offset:12288
	s_waitcnt lgkmcnt(10)
	v_mfma_f32_32x32x16_bf16 v[16:31], v[228:231], v[156:159], v[16:31]
	v_exp_f32_e32 v75, v75
	ds_read_b128 v[152:155], v241 offset:0
	s_waitcnt lgkmcnt(9)
	v_mfma_f32_32x32x16_bf16 v[0:15], v[208:211], v[160:163], v[0:15]
	v_exp_f32_e32 v76, v76
	ds_read_b128 v[156:159], v241 offset:12288
	s_waitcnt lgkmcnt(8)
	v_mfma_f32_32x32x16_bf16 v[0:15], v[212:215], v[164:167], v[0:15]
	v_exp_f32_e32 v77, v77
	ds_read_b128 v[160:163], v242 offset:0
	s_waitcnt lgkmcnt(7)
	v_mfma_f32_32x32x16_bf16 v[0:15], v[224:227], v[168:171], v[0:15]
	v_exp_f32_e32 v78, v78
	ds_read_b128 v[164:167], v242 offset:12288
	s_waitcnt lgkmcnt(6)
	v_mfma_f32_32x32x16_bf16 v[0:15], v[228:231], v[172:175], v[0:15]
	v_exp_f32_e32 v79, v79
	s_waitcnt vmcnt(5)
	s_barrier
	ds_read_b128 v[168:171], v243 offset:0
	s_waitcnt lgkmcnt(6)
	v_mfma_f32_32x32x16_bf16 v[208:223], v[144:147], v[96:99], 0
	v_exp_f32_e32 v80, v80
	v_add_f32_e32 v245, v64, v245
	v_exp_f32_e32 v81, v81
	ds_read_b128 v[172:175], v243 offset:12288
	s_waitcnt lgkmcnt(6)
	v_mfma_f32_32x32x16_bf16 v[224:239], v[148:151], v[96:99], 0
	v_add_f32_e32 v246, v65, v246
	v_exp_f32_e32 v82, v82
	v_add_f32_e32 v245, v66, v245
	ds_read_b128 v[144:147], v240 offset:128
	s_waitcnt lgkmcnt(6)
	v_mfma_f32_32x32x16_bf16 v[208:223], v[152:155], v[100:103], v[208:223]
	v_exp_f32_e32 v83, v83
	v_add_f32_e32 v246, v67, v246
	s_add_i32 m0, s60, 0x21010
	s_nop 0
	global_load_lds_dwordx4 v182, s[42:43]
	ds_read_b128 v[148:151], v240 offset:12416
	s_waitcnt lgkmcnt(6)
	v_mfma_f32_32x32x16_bf16 v[224:239], v[156:159], v[100:103], v[224:239]
	v_exp_f32_e32 v84, v84
	v_add_f32_e32 v245, v68, v245
	v_exp_f32_e32 v85, v85
	ds_read_b128 v[152:155], v241 offset:128
	s_waitcnt lgkmcnt(6)
	v_mfma_f32_32x32x16_bf16 v[208:223], v[160:163], v[104:107], v[208:223]
	v_add_f32_e32 v246, v69, v246
	v_exp_f32_e32 v86, v86
	v_add_f32_e32 v245, v70, v245
	ds_read_b128 v[156:159], v241 offset:12416
	s_waitcnt lgkmcnt(6)
	v_mfma_f32_32x32x16_bf16 v[224:239], v[164:167], v[104:107], v[224:239]
	v_exp_f32_e32 v87, v87
	v_add_f32_e32 v246, v71, v246
	s_add_i32 m0, s60, 0x21410
	s_nop 0
	global_load_lds_dwordx4 v183, s[42:43]
	ds_read_b128 v[160:163], v242 offset:128
	s_waitcnt lgkmcnt(6)
	v_mfma_f32_32x32x16_bf16 v[208:223], v[168:171], v[108:111], v[208:223]
	v_exp_f32_e32 v88, v88
	v_add_f32_e32 v245, v72, v245
	v_exp_f32_e32 v89, v89
	ds_read_b128 v[164:167], v242 offset:12416
	s_waitcnt lgkmcnt(6)
	v_mfma_f32_32x32x16_bf16 v[224:239], v[172:175], v[108:111], v[224:239]
	v_add_f32_e32 v246, v73, v246
	v_exp_f32_e32 v90, v90
	v_add_f32_e32 v245, v74, v245
	ds_read_b128 v[168:171], v243 offset:128
	s_waitcnt lgkmcnt(6)
	v_mfma_f32_32x32x16_bf16 v[208:223], v[144:147], v[112:115], v[208:223]
	v_exp_f32_e32 v91, v91
	v_add_f32_e32 v246, v75, v246
	s_add_i32 m0, s60, 0x21810
	s_nop 0
	global_load_lds_dwordx4 v184, s[42:43]
	ds_read_b128 v[172:175], v243 offset:12416
	s_waitcnt lgkmcnt(6)
	v_mfma_f32_32x32x16_bf16 v[224:239], v[148:151], v[112:115], v[224:239]
	v_exp_f32_e32 v92, v92
	v_add_f32_e32 v245, v76, v245
	v_exp_f32_e32 v93, v93
	ds_read_b128 v[144:147], v240 offset:256
	s_waitcnt lgkmcnt(6)
	v_mfma_f32_32x32x16_bf16 v[208:223], v[152:155], v[116:119], v[208:223]
	v_add_f32_e32 v246, v77, v246
	v_exp_f32_e32 v94, v94
	v_add_f32_e32 v245, v78, v245
	ds_read_b128 v[148:151], v240 offset:12544
	s_waitcnt lgkmcnt(6)
	v_mfma_f32_32x32x16_bf16 v[224:239], v[156:159], v[116:119], v[224:239]
	v_exp_f32_e32 v95, v95
	v_add_f32_e32 v246, v79, v246
	s_add_i32 m0, s61, 0x8000
	s_nop 0
	global_load_lds_dwordx4 v185, s[46:47]
	ds_read_b128 v[152:155], v241 offset:256
	s_waitcnt lgkmcnt(6)
	v_mfma_f32_32x32x16_bf16 v[208:223], v[160:163], v[120:123], v[208:223]
	v_add_f32_e32 v245, v80, v245
	v_add_f32_e32 v246, v81, v246
	v_add_f32_e32 v245, v82, v245
	ds_read_b128 v[156:159], v241 offset:12544
	s_waitcnt lgkmcnt(6)
	v_mfma_f32_32x32x16_bf16 v[224:239], v[164:167], v[120:123], v[224:239]
	v_add_f32_e32 v246, v83, v246
	v_add_f32_e32 v245, v84, v245
	v_add_f32_e32 v246, v85, v246
	ds_read_b128 v[160:163], v242 offset:256
	s_waitcnt lgkmcnt(6)
	v_mfma_f32_32x32x16_bf16 v[208:223], v[168:171], v[124:127], v[208:223]
	v_add_f32_e32 v245, v86, v245
	v_add_f32_e32 v246, v87, v246
	s_add_i32 m0, s61, 0x8400
	s_nop 0
	global_load_lds_dwordx4 v186, s[46:47]
	ds_read_b128 v[164:167], v242 offset:12544
	s_waitcnt lgkmcnt(6)
	v_mfma_f32_32x32x16_bf16 v[224:239], v[172:175], v[124:127], v[224:239]
	v_add_f32_e32 v245, v88, v245
	v_add_f32_e32 v246, v89, v246
	v_add_f32_e32 v245, v90, v245
	ds_read_b128 v[168:171], v243 offset:256
	s_waitcnt lgkmcnt(6)
	v_mfma_f32_32x32x16_bf16 v[208:223], v[144:147], v[128:131], v[208:223]
	v_add_f32_e32 v246, v91, v246
	v_add_f32_e32 v245, v92, v245
	v_add_f32_e32 v246, v93, v246
	ds_read_b128 v[172:175], v243 offset:12544
	s_waitcnt lgkmcnt(6)
	v_mfma_f32_32x32x16_bf16 v[224:239], v[148:151], v[128:131], v[224:239]
	v_add_f32_e32 v245, v94, v245
	v_add_f32_e32 v246, v95, v246
	s_add_u32 s42, s42, 0x6000
	s_addc_u32 s43, s43, 0
	v_add_u32_e32 v240, 0x6000, v240
	ds_read_b64_tr_b16 v[144:145], v244 offset:0
	ds_read_b64_tr_b16 v[146:147], v244 offset:2048
	s_waitcnt lgkmcnt(7)
	v_mfma_f32_32x32x16_bf16 v[208:223], v[152:155], v[132:135], v[208:223]
	v_cvt_pk_bf16_f32 v64, v64, v65
	v_cvt_pk_bf16_f32 v65, v66, v67
	v_cvt_pk_bf16_f32 v66, v68, v69
	v_add_u32_e32 v241, 0x6000, v241
	ds_read_b64_tr_b16 v[148:149], v244 offset:4096
	ds_read_b64_tr_b16 v[150:151], v244 offset:6144
	s_waitcnt lgkmcnt(8)
	v_mfma_f32_32x32x16_bf16 v[224:239], v[156:159], v[132:135], v[224:239]
	v_cvt_pk_bf16_f32 v67, v70, v71
	v_cvt_pk_bf16_f32 v68, v72, v73
	v_cvt_pk_bf16_f32 v69, v74, v75
	v_add_u32_e32 v242, 0x6000, v242
	ds_read_b64_tr_b16 v[152:153], v244 offset:8192
	ds_read_b64_tr_b16 v[154:155], v244 offset:10240
	s_waitcnt lgkmcnt(9)
	v_mfma_f32_32x32x16_bf16 v[208:223], v[160:163], v[136:139], v[208:223]
	v_cvt_pk_bf16_f32 v70, v76, v77
	v_cvt_pk_bf16_f32 v71, v78, v79
	s_add_u32 s46, s46, 0x40000
	s_addc_u32 s47, s47, 0
	v_add_u32_e32 v243, 0x6000, v243
	ds_read_b64_tr_b16 v[156:157], v244 offset:12288
	ds_read_b64_tr_b16 v[158:159], v244 offset:14336
	s_waitcnt lgkmcnt(10)
	v_mfma_f32_32x32x16_bf16 v[224:239], v[164:167], v[136:139], v[224:239]
	v_cvt_pk_bf16_f32 v80, v80, v81
	v_cvt_pk_bf16_f32 v81, v82, v83
	v_cvt_pk_bf16_f32 v82, v84, v85
	ds_read_b64_tr_b16 v[160:161], v244 offset:512
	ds_read_b64_tr_b16 v[162:163], v244 offset:2560
	s_waitcnt lgkmcnt(11)
	v_mfma_f32_32x32x16_bf16 v[208:223], v[168:171], v[140:143], v[208:223]
	v_cvt_pk_bf16_f32 v83, v86, v87
	v_cvt_pk_bf16_f32 v84, v88, v89
	v_cvt_pk_bf16_f32 v85, v90, v91
	ds_read_b64_tr_b16 v[164:165], v244 offset:4608
	ds_read_b64_tr_b16 v[166:167], v244 offset:6656
	s_waitcnt lgkmcnt(12)
	v_mfma_f32_32x32x16_bf16 v[224:239], v[172:175], v[140:143], v[224:239]
	v_cvt_pk_bf16_f32 v86, v92, v93
	v_cvt_pk_bf16_f32 v87, v94, v95
	ds_read_b64_tr_b16 v[168:169], v244 offset:8704
	ds_read_b64_tr_b16 v[170:171], v244 offset:10752
	s_waitcnt lgkmcnt(12)
	v_mfma_f32_32x32x16_bf16 v[48:63], v[64:67], v[144:147], v[48:63]
	ds_read_b64_tr_b16 v[172:173], v244 offset:12800
	ds_read_b64_tr_b16 v[174:175], v244 offset:14848
	s_waitcnt lgkmcnt(12)
	v_mfma_f32_32x32x16_bf16 v[48:63], v[68:71], v[148:151], v[48:63]
	ds_read_b64_tr_b16 v[144:145], v244 offset:1024
	ds_read_b64_tr_b16 v[146:147], v244 offset:3072
	s_waitcnt lgkmcnt(12)
	v_mfma_f32_32x32x16_bf16 v[48:63], v[80:83], v[152:155], v[48:63]
	v_exp_f32_e32 v208, v208
	v_exp_f32_e32 v209, v209
	ds_read_b64_tr_b16 v[148:149], v244 offset:5120
	ds_read_b64_tr_b16 v[150:151], v244 offset:7168
	s_waitcnt lgkmcnt(12)
	v_mfma_f32_32x32x16_bf16 v[48:63], v[84:87], v[156:159], v[48:63]
	v_exp_f32_e32 v210, v210
	v_exp_f32_e32 v211, v211
	ds_read_b64_tr_b16 v[152:153], v244 offset:9216
	ds_read_b64_tr_b16 v[154:155], v244 offset:11264
	s_waitcnt lgkmcnt(12)
	v_mfma_f32_32x32x16_bf16 v[32:47], v[64:67], v[160:163], v[32:47]
	v_exp_f32_e32 v212, v212
	ds_read_b64_tr_b16 v[156:157], v244 offset:13312
	ds_read_b64_tr_b16 v[158:159], v244 offset:15360
	s_waitcnt lgkmcnt(12)
	v_mfma_f32_32x32x16_bf16 v[32:47], v[68:71], v[164:167], v[32:47]
	v_exp_f32_e32 v213, v213
	ds_read_b64_tr_b16 v[160:161], v244 offset:1536
	ds_read_b64_tr_b16 v[162:163], v244 offset:3584
	s_waitcnt lgkmcnt(12)
	v_mfma_f32_32x32x16_bf16 v[32:47], v[80:83], v[168:171], v[32:47]
	v_exp_f32_e32 v214, v214
	ds_read_b64_tr_b16 v[164:165], v244 offset:5632
	ds_read_b64_tr_b16 v[166:167], v244 offset:7680
	s_waitcnt lgkmcnt(12)
	v_mfma_f32_32x32x16_bf16 v[32:47], v[84:87], v[172:175], v[32:47]
	v_exp_f32_e32 v215, v215
	ds_read_b64_tr_b16 v[168:169], v244 offset:9728
	ds_read_b64_tr_b16 v[170:171], v244 offset:11776
	s_waitcnt lgkmcnt(12)
	v_mfma_f32_32x32x16_bf16 v[16:31], v[64:67], v[144:147], v[16:31]
	v_exp_f32_e32 v216, v216
	ds_read_b64_tr_b16 v[172:173], v244 offset:13824
	ds_read_b64_tr_b16 v[174:175], v244 offset:15872
	s_waitcnt lgkmcnt(12)
	v_mfma_f32_32x32x16_bf16 v[16:31], v[68:71], v[148:151], v[16:31]
	v_exp_f32_e32 v217, v217
	v_add_u32_e32 v244, 0x4000, v244
	ds_read_b128 v[144:147], v240 offset:0
	s_waitcnt lgkmcnt(11)
	v_mfma_f32_32x32x16_bf16 v[16:31], v[80:83], v[152:155], v[16:31]
	v_exp_f32_e32 v218, v218
	ds_read_b128 v[148:151], v240 offset:12288
	s_waitcnt lgkmcnt(10)
	v_mfma_f32_32x32x16_bf16 v[16:31], v[84:87], v[156:159], v[16:31]
	v_exp_f32_e32 v219, v219
	ds_read_b128 v[152:155], v241 offset:0
	s_waitcnt lgkmcnt(9)
	v_mfma_f32_32x32x16_bf16 v[0:15], v[64:67], v[160:163], v[0:15]
	v_exp_f32_e32 v220, v220
	ds_read_b128 v[156:159], v241 offset:12288
	s_waitcnt lgkmcnt(8)
	v_mfma_f32_32x32x16_bf16 v[0:15], v[68:71], v[164:167], v[0:15]
	v_exp_f32_e32 v221, v221
	ds_read_b128 v[160:163], v242 offset:0
	s_waitcnt lgkmcnt(7)
	v_mfma_f32_32x32x16_bf16 v[0:15], v[80:83], v[168:171], v[0:15]
	v_exp_f32_e32 v222, v222
	ds_read_b128 v[164:167], v242 offset:12288
	s_waitcnt lgkmcnt(6)
	v_mfma_f32_32x32x16_bf16 v[0:15], v[84:87], v[172:175], v[0:15]
	v_exp_f32_e32 v223, v223
	s_waitcnt vmcnt(5)
	s_barrier
	ds_read_b128 v[168:171], v243 offset:0
	s_waitcnt lgkmcnt(6)
	v_mfma_f32_32x32x16_bf16 v[64:79], v[144:147], v[96:99], 0
	v_exp_f32_e32 v224, v224
	v_add_f32_e32 v245, v208, v245
	v_exp_f32_e32 v225, v225
	ds_read_b128 v[172:175], v243 offset:12288
	s_waitcnt lgkmcnt(6)
	v_mfma_f32_32x32x16_bf16 v[80:95], v[148:151], v[96:99], 0
	v_add_f32_e32 v246, v209, v246
	v_exp_f32_e32 v226, v226
	v_add_f32_e32 v245, v210, v245
	ds_read_b128 v[144:147], v240 offset:128
	s_waitcnt lgkmcnt(6)
	v_mfma_f32_32x32x16_bf16 v[64:79], v[152:155], v[100:103], v[64:79]
	v_exp_f32_e32 v227, v227
	v_add_f32_e32 v246, v211, v246
	s_add_i32 m0, s60, 0xc000
	s_nop 0
	global_load_lds_dwordx4 v182, s[42:43]
	ds_read_b128 v[148:151], v240 offset:12416
	s_waitcnt lgkmcnt(6)
	v_mfma_f32_32x32x16_bf16 v[80:95], v[156:159], v[100:103], v[80:95]
	v_exp_f32_e32 v228, v228
	v_add_f32_e32 v245, v212, v245
	v_exp_f32_e32 v229, v229
	ds_read_b128 v[152:155], v241 offset:128
	s_waitcnt lgkmcnt(6)
	v_mfma_f32_32x32x16_bf16 v[64:79], v[160:163], v[104:107], v[64:79]
	v_add_f32_e32 v246, v213, v246
	v_exp_f32_e32 v230, v230
	v_add_f32_e32 v245, v214, v245
	ds_read_b128 v[156:159], v241 offset:12416
	s_waitcnt lgkmcnt(6)
	v_mfma_f32_32x32x16_bf16 v[80:95], v[164:167], v[104:107], v[80:95]
	v_exp_f32_e32 v231, v231
	v_add_f32_e32 v246, v215, v246
	s_add_i32 m0, s60, 0xc400
	s_nop 0
	global_load_lds_dwordx4 v183, s[42:43]
	ds_read_b128 v[160:163], v242 offset:128
	s_waitcnt lgkmcnt(6)
	v_mfma_f32_32x32x16_bf16 v[64:79], v[168:171], v[108:111], v[64:79]
	v_exp_f32_e32 v232, v232
	v_add_f32_e32 v245, v216, v245
	v_exp_f32_e32 v233, v233
	ds_read_b128 v[164:167], v242 offset:12416
	s_waitcnt lgkmcnt(6)
	v_mfma_f32_32x32x16_bf16 v[80:95], v[172:175], v[108:111], v[80:95]
	v_add_f32_e32 v246, v217, v246
	v_exp_f32_e32 v234, v234
	v_add_f32_e32 v245, v218, v245
	ds_read_b128 v[168:171], v243 offset:128
	s_waitcnt lgkmcnt(6)
	v_mfma_f32_32x32x16_bf16 v[64:79], v[144:147], v[112:115], v[64:79]
	v_exp_f32_e32 v235, v235
	v_add_f32_e32 v246, v219, v246
	s_add_i32 m0, s60, 0xc800
	s_nop 0
	global_load_lds_dwordx4 v184, s[42:43]
	ds_read_b128 v[172:175], v243 offset:12416
	s_waitcnt lgkmcnt(6)
	v_mfma_f32_32x32x16_bf16 v[80:95], v[148:151], v[112:115], v[80:95]
	v_exp_f32_e32 v236, v236
	v_add_f32_e32 v245, v220, v245
	v_exp_f32_e32 v237, v237
	ds_read_b128 v[144:147], v240 offset:256
	s_waitcnt lgkmcnt(6)
	v_mfma_f32_32x32x16_bf16 v[64:79], v[152:155], v[116:119], v[64:79]
	v_add_f32_e32 v246, v221, v246
	v_exp_f32_e32 v238, v238
	v_add_f32_e32 v245, v222, v245
	ds_read_b128 v[148:151], v240 offset:12544
	s_waitcnt lgkmcnt(6)
	v_mfma_f32_32x32x16_bf16 v[80:95], v[156:159], v[116:119], v[80:95]
	v_exp_f32_e32 v239, v239
	v_add_f32_e32 v246, v223, v246
	s_add_i32 m0, s61, 0x0
	s_nop 0
	global_load_lds_dwordx4 v185, s[46:47]
	ds_read_b128 v[152:155], v241 offset:256
	s_waitcnt lgkmcnt(6)
	v_mfma_f32_32x32x16_bf16 v[64:79], v[160:163], v[120:123], v[64:79]
	v_add_f32_e32 v245, v224, v245
	v_add_f32_e32 v246, v225, v246
	v_add_f32_e32 v245, v226, v245
	ds_read_b128 v[156:159], v241 offset:12544
	s_waitcnt lgkmcnt(6)
	v_mfma_f32_32x32x16_bf16 v[80:95], v[164:167], v[120:123], v[80:95]
	v_add_f32_e32 v246, v227, v246
	v_add_f32_e32 v245, v228, v245
	v_add_f32_e32 v246, v229, v246
	ds_read_b128 v[160:163], v242 offset:256
	s_waitcnt lgkmcnt(6)
	v_mfma_f32_32x32x16_bf16 v[64:79], v[168:171], v[124:127], v[64:79]
	v_add_f32_e32 v245, v230, v245
	v_add_f32_e32 v246, v231, v246
	s_add_i32 m0, s61, 0x400
	s_nop 0
	global_load_lds_dwordx4 v186, s[46:47]
	ds_read_b128 v[164:167], v242 offset:12544
	s_waitcnt lgkmcnt(6)
	v_mfma_f32_32x32x16_bf16 v[80:95], v[172:175], v[124:127], v[80:95]
	v_add_f32_e32 v245, v232, v245
	v_add_f32_e32 v246, v233, v246
	v_add_f32_e32 v245, v234, v245
	ds_read_b128 v[168:171], v243 offset:256
	s_waitcnt lgkmcnt(6)
	v_mfma_f32_32x32x16_bf16 v[64:79], v[144:147], v[128:131], v[64:79]
	v_add_f32_e32 v246, v235, v246
	v_add_f32_e32 v245, v236, v245
	v_add_f32_e32 v246, v237, v246
	ds_read_b128 v[172:175], v243 offset:12544
	s_waitcnt lgkmcnt(6)
	v_mfma_f32_32x32x16_bf16 v[80:95], v[148:151], v[128:131], v[80:95]
	v_add_f32_e32 v245, v238, v245
	v_add_f32_e32 v246, v239, v246
	s_add_u32 s42, s42, 0x6000
	s_addc_u32 s43, s43, 0
	v_add_u32_e32 v240, 0x6000, v240
	ds_read_b64_tr_b16 v[144:145], v244 offset:0
	ds_read_b64_tr_b16 v[146:147], v244 offset:2048
	s_waitcnt lgkmcnt(7)
	v_mfma_f32_32x32x16_bf16 v[64:79], v[152:155], v[132:135], v[64:79]
	v_cvt_pk_bf16_f32 v208, v208, v209
	v_cvt_pk_bf16_f32 v209, v210, v211
	v_cvt_pk_bf16_f32 v210, v212, v213
	v_add_u32_e32 v241, 0x6000, v241
	ds_read_b64_tr_b16 v[148:149], v244 offset:4096
	ds_read_b64_tr_b16 v[150:151], v244 offset:6144
	s_waitcnt lgkmcnt(8)
	v_mfma_f32_32x32x16_bf16 v[80:95], v[156:159], v[132:135], v[80:95]
	v_cvt_pk_bf16_f32 v211, v214, v215
	v_cvt_pk_bf16_f32 v212, v216, v217
	v_cvt_pk_bf16_f32 v213, v218, v219
	v_add_u32_e32 v242, 0x6000, v242
	ds_read_b64_tr_b16 v[152:153], v244 offset:8192
	ds_read_b64_tr_b16 v[154:155], v244 offset:10240
	s_waitcnt lgkmcnt(9)
	v_mfma_f32_32x32x16_bf16 v[64:79], v[160:163], v[136:139], v[64:79]
	v_cvt_pk_bf16_f32 v214, v220, v221
	v_cvt_pk_bf16_f32 v215, v222, v223
	s_add_u32 s46, s46, 0x40000
	s_addc_u32 s47, s47, 0
	v_add_u32_e32 v243, 0x6000, v243
	ds_read_b64_tr_b16 v[156:157], v244 offset:12288
	ds_read_b64_tr_b16 v[158:159], v244 offset:14336
	s_waitcnt lgkmcnt(10)
	v_mfma_f32_32x32x16_bf16 v[80:95], v[164:167], v[136:139], v[80:95]
	v_cvt_pk_bf16_f32 v224, v224, v225
	v_cvt_pk_bf16_f32 v225, v226, v227
	v_cvt_pk_bf16_f32 v226, v228, v229
	ds_read_b64_tr_b16 v[160:161], v244 offset:512
	ds_read_b64_tr_b16 v[162:163], v244 offset:2560
	s_waitcnt lgkmcnt(11)
	v_mfma_f32_32x32x16_bf16 v[64:79], v[168:171], v[140:143], v[64:79]
	v_cvt_pk_bf16_f32 v227, v230, v231
	v_cvt_pk_bf16_f32 v228, v232, v233
	v_cvt_pk_bf16_f32 v229, v234, v235
	ds_read_b64_tr_b16 v[164:165], v244 offset:4608
	ds_read_b64_tr_b16 v[166:167], v244 offset:6656
	s_waitcnt lgkmcnt(12)
	v_mfma_f32_32x32x16_bf16 v[80:95], v[172:175], v[140:143], v[80:95]
	v_cvt_pk_bf16_f32 v230, v236, v237
	v_cvt_pk_bf16_f32 v231, v238, v239
	ds_read_b64_tr_b16 v[168:169], v244 offset:8704
	ds_read_b64_tr_b16 v[170:171], v244 offset:10752
	s_waitcnt lgkmcnt(12)
	v_mfma_f32_32x32x16_bf16 v[48:63], v[208:211], v[144:147], v[48:63]
	ds_read_b64_tr_b16 v[172:173], v244 offset:12800
	ds_read_b64_tr_b16 v[174:175], v244 offset:14848
	s_waitcnt lgkmcnt(12)
	v_mfma_f32_32x32x16_bf16 v[48:63], v[212:215], v[148:151], v[48:63]
	ds_read_b64_tr_b16 v[144:145], v244 offset:1024
	ds_read_b64_tr_b16 v[146:147], v244 offset:3072
	s_waitcnt lgkmcnt(12)
	v_mfma_f32_32x32x16_bf16 v[48:63], v[224:227], v[152:155], v[48:63]
	v_exp_f32_e32 v64, v64
	v_exp_f32_e32 v65, v65
	ds_read_b64_tr_b16 v[148:149], v244 offset:5120
	ds_read_b64_tr_b16 v[150:151], v244 offset:7168
	s_waitcnt lgkmcnt(12)
	v_mfma_f32_32x32x16_bf16 v[48:63], v[228:231], v[156:159], v[48:63]
	v_exp_f32_e32 v66, v66
	v_exp_f32_e32 v67, v67
	ds_read_b64_tr_b16 v[152:153], v244 offset:9216
	ds_read_b64_tr_b16 v[154:155], v244 offset:11264
	s_waitcnt lgkmcnt(12)
	v_mfma_f32_32x32x16_bf16 v[32:47], v[208:211], v[160:163], v[32:47]
	v_exp_f32_e32 v68, v68
	ds_read_b64_tr_b16 v[156:157], v244 offset:13312
	ds_read_b64_tr_b16 v[158:159], v244 offset:15360
	s_waitcnt lgkmcnt(12)
	v_mfma_f32_32x32x16_bf16 v[32:47], v[212:215], v[164:167], v[32:47]
	v_exp_f32_e32 v69, v69
	ds_read_b64_tr_b16 v[160:161], v244 offset:1536
	ds_read_b64_tr_b16 v[162:163], v244 offset:3584
	s_waitcnt lgkmcnt(12)
	v_mfma_f32_32x32x16_bf16 v[32:47], v[224:227], v[168:171], v[32:47]
	v_exp_f32_e32 v70, v70
	ds_read_b64_tr_b16 v[164:165], v244 offset:5632
	ds_read_b64_tr_b16 v[166:167], v244 offset:7680
	s_waitcnt lgkmcnt(12)
	v_mfma_f32_32x32x16_bf16 v[32:47], v[228:231], v[172:175], v[32:47]
	v_exp_f32_e32 v71, v71
	ds_read_b64_tr_b16 v[168:169], v244 offset:9728
	ds_read_b64_tr_b16 v[170:171], v244 offset:11776
	s_waitcnt lgkmcnt(12)
	v_mfma_f32_32x32x16_bf16 v[16:31], v[208:211], v[144:147], v[16:31]
	v_exp_f32_e32 v72, v72
	ds_read_b64_tr_b16 v[172:173], v244 offset:13824
	ds_read_b64_tr_b16 v[174:175], v244 offset:15872
	s_waitcnt lgkmcnt(12)
	v_mfma_f32_32x32x16_bf16 v[16:31], v[212:215], v[148:151], v[16:31]
	v_exp_f32_e32 v73, v73
	v_add_u32_e32 v244, 0x4000, v244
	ds_read_b128 v[144:147], v240 offset:0
	s_waitcnt lgkmcnt(11)
	v_mfma_f32_32x32x16_bf16 v[16:31], v[224:227], v[152:155], v[16:31]
	v_exp_f32_e32 v74, v74
	ds_read_b128 v[148:151], v240 offset:12288
	s_waitcnt lgkmcnt(10)
	v_mfma_f32_32x32x16_bf16 v[16:31], v[228:231], v[156:159], v[16:31]
	v_exp_f32_e32 v75, v75
	ds_read_b128 v[152:155], v241 offset:0
	s_waitcnt lgkmcnt(9)
	v_mfma_f32_32x32x16_bf16 v[0:15], v[208:211], v[160:163], v[0:15]
	v_exp_f32_e32 v76, v76
	ds_read_b128 v[156:159], v241 offset:12288
	s_waitcnt lgkmcnt(8)
	v_mfma_f32_32x32x16_bf16 v[0:15], v[212:215], v[164:167], v[0:15]
	v_exp_f32_e32 v77, v77
	ds_read_b128 v[160:163], v242 offset:0
	s_waitcnt lgkmcnt(7)
	v_mfma_f32_32x32x16_bf16 v[0:15], v[224:227], v[168:171], v[0:15]
	v_exp_f32_e32 v78, v78
	ds_read_b128 v[164:167], v242 offset:12288
	s_waitcnt lgkmcnt(6)
	v_mfma_f32_32x32x16_bf16 v[0:15], v[228:231], v[172:175], v[0:15]
	v_exp_f32_e32 v79, v79
	s_waitcnt vmcnt(5)
	s_barrier
	ds_read_b128 v[168:171], v243 offset:0
	s_waitcnt lgkmcnt(6)
	v_mfma_f32_32x32x16_bf16 v[208:223], v[144:147], v[96:99], 0
	v_exp_f32_e32 v80, v80
	v_add_f32_e32 v245, v64, v245
	v_exp_f32_e32 v81, v81
	ds_read_b128 v[172:175], v243 offset:12288
	s_waitcnt lgkmcnt(6)
	v_mfma_f32_32x32x16_bf16 v[224:239], v[148:151], v[96:99], 0
	v_add_f32_e32 v246, v65, v246
	v_exp_f32_e32 v82, v82
	v_add_f32_e32 v245, v66, v245
	ds_read_b128 v[144:147], v240 offset:128
	s_waitcnt lgkmcnt(6)
	v_mfma_f32_32x32x16_bf16 v[208:223], v[152:155], v[100:103], v[208:223]
	v_exp_f32_e32 v83, v83
	v_add_f32_e32 v246, v67, v246
	s_add_i32 m0, s60, 0x12000
	s_nop 0
	global_load_lds_dwordx4 v182, s[42:43]
	ds_read_b128 v[148:151], v240 offset:12416
	s_waitcnt lgkmcnt(6)
	v_mfma_f32_32x32x16_bf16 v[224:239], v[156:159], v[100:103], v[224:239]
	v_exp_f32_e32 v84, v84
	v_add_f32_e32 v245, v68, v245
	v_exp_f32_e32 v85, v85
	ds_read_b128 v[152:155], v241 offset:128
	s_waitcnt lgkmcnt(6)
	v_mfma_f32_32x32x16_bf16 v[208:223], v[160:163], v[104:107], v[208:223]
	v_add_f32_e32 v246, v69, v246
	v_exp_f32_e32 v86, v86
	v_add_f32_e32 v245, v70, v245
	ds_read_b128 v[156:159], v241 offset:12416
	s_waitcnt lgkmcnt(6)
	v_mfma_f32_32x32x16_bf16 v[224:239], v[164:167], v[104:107], v[224:239]
	v_exp_f32_e32 v87, v87
	v_add_f32_e32 v246, v71, v246
	s_add_i32 m0, s60, 0x12400
	s_nop 0
	global_load_lds_dwordx4 v183, s[42:43]
	ds_read_b128 v[160:163], v242 offset:128
	s_waitcnt lgkmcnt(6)
	v_mfma_f32_32x32x16_bf16 v[208:223], v[168:171], v[108:111], v[208:223]
	v_exp_f32_e32 v88, v88
	v_add_f32_e32 v245, v72, v245
	v_exp_f32_e32 v89, v89
	ds_read_b128 v[164:167], v242 offset:12416
	s_waitcnt lgkmcnt(6)
	v_mfma_f32_32x32x16_bf16 v[224:239], v[172:175], v[108:111], v[224:239]
	v_add_f32_e32 v246, v73, v246
	v_exp_f32_e32 v90, v90
	v_add_f32_e32 v245, v74, v245
	ds_read_b128 v[168:171], v243 offset:128
	s_waitcnt lgkmcnt(6)
	v_mfma_f32_32x32x16_bf16 v[208:223], v[144:147], v[112:115], v[208:223]
	v_exp_f32_e32 v91, v91
	v_add_f32_e32 v246, v75, v246
	s_add_i32 m0, s60, 0x12800
	s_nop 0
	global_load_lds_dwordx4 v184, s[42:43]
	ds_read_b128 v[172:175], v243 offset:12416
	s_waitcnt lgkmcnt(6)
	v_mfma_f32_32x32x16_bf16 v[224:239], v[148:151], v[112:115], v[224:239]
	v_exp_f32_e32 v92, v92
	v_add_f32_e32 v245, v76, v245
	v_exp_f32_e32 v93, v93
	ds_read_b128 v[144:147], v240 offset:256
	s_waitcnt lgkmcnt(6)
	v_mfma_f32_32x32x16_bf16 v[208:223], v[152:155], v[116:119], v[208:223]
	v_add_f32_e32 v246, v77, v246
	v_exp_f32_e32 v94, v94
	v_add_f32_e32 v245, v78, v245
	ds_read_b128 v[148:151], v240 offset:12544
	s_waitcnt lgkmcnt(6)
	v_mfma_f32_32x32x16_bf16 v[224:239], v[156:159], v[116:119], v[224:239]
	v_exp_f32_e32 v95, v95
	v_add_f32_e32 v246, v79, v246
	s_add_i32 m0, s61, 0x4000
	s_nop 0
	global_load_lds_dwordx4 v185, s[46:47]
	ds_read_b128 v[152:155], v241 offset:256
	s_waitcnt lgkmcnt(6)
	v_mfma_f32_32x32x16_bf16 v[208:223], v[160:163], v[120:123], v[208:223]
	v_add_f32_e32 v245, v80, v245
	v_add_f32_e32 v246, v81, v246
	v_add_f32_e32 v245, v82, v245
	ds_read_b128 v[156:159], v241 offset:12544
	s_waitcnt lgkmcnt(6)
	v_mfma_f32_32x32x16_bf16 v[224:239], v[164:167], v[120:123], v[224:239]
	v_add_f32_e32 v246, v83, v246
	v_add_f32_e32 v245, v84, v245
	v_add_f32_e32 v246, v85, v246
	ds_read_b128 v[160:163], v242 offset:256
	s_waitcnt lgkmcnt(6)
	v_mfma_f32_32x32x16_bf16 v[208:223], v[168:171], v[124:127], v[208:223]
	v_add_f32_e32 v245, v86, v245
	v_add_f32_e32 v246, v87, v246
	s_add_i32 m0, s61, 0x4400
	s_nop 0
	global_load_lds_dwordx4 v186, s[46:47]
	ds_read_b128 v[164:167], v242 offset:12544
	s_waitcnt lgkmcnt(6)
	v_mfma_f32_32x32x16_bf16 v[224:239], v[172:175], v[124:127], v[224:239]
	v_add_f32_e32 v245, v88, v245
	v_add_f32_e32 v246, v89, v246
	v_add_f32_e32 v245, v90, v245
	ds_read_b128 v[168:171], v243 offset:256
	s_waitcnt lgkmcnt(6)
	v_mfma_f32_32x32x16_bf16 v[208:223], v[144:147], v[128:131], v[208:223]
	v_add_f32_e32 v246, v91, v246
	v_add_f32_e32 v245, v92, v245
	v_add_f32_e32 v246, v93, v246
	ds_read_b128 v[172:175], v243 offset:12544
	s_waitcnt lgkmcnt(6)
	v_mfma_f32_32x32x16_bf16 v[224:239], v[148:151], v[128:131], v[224:239]
	v_add_f32_e32 v245, v94, v245
	v_add_f32_e32 v246, v95, v246
	s_add_u32 s42, s42, 0x6000
	s_addc_u32 s43, s43, 0
	v_add_u32_e32 v240, 0x9010, v240
	ds_read_b64_tr_b16 v[144:145], v244 offset:0
	ds_read_b64_tr_b16 v[146:147], v244 offset:2048
	s_waitcnt lgkmcnt(7)
	v_mfma_f32_32x32x16_bf16 v[208:223], v[152:155], v[132:135], v[208:223]
	v_cvt_pk_bf16_f32 v64, v64, v65
	v_cvt_pk_bf16_f32 v65, v66, v67
	v_cvt_pk_bf16_f32 v66, v68, v69
	v_add_u32_e32 v241, 0x9010, v241
	ds_read_b64_tr_b16 v[148:149], v244 offset:4096
	ds_read_b64_tr_b16 v[150:151], v244 offset:6144
	s_waitcnt lgkmcnt(8)
	v_mfma_f32_32x32x16_bf16 v[224:239], v[156:159], v[132:135], v[224:239]
	v_cvt_pk_bf16_f32 v67, v70, v71
	v_cvt_pk_bf16_f32 v68, v72, v73
	v_cvt_pk_bf16_f32 v69, v74, v75
	v_add_u32_e32 v242, 0x9010, v242
	ds_read_b64_tr_b16 v[152:153], v244 offset:8192
	ds_read_b64_tr_b16 v[154:155], v244 offset:10240
	s_waitcnt lgkmcnt(9)
	v_mfma_f32_32x32x16_bf16 v[208:223], v[160:163], v[136:139], v[208:223]
	v_cvt_pk_bf16_f32 v70, v76, v77
	v_cvt_pk_bf16_f32 v71, v78, v79
	s_add_u32 s46, s46, 0x40000
	s_addc_u32 s47, s47, 0
	v_add_u32_e32 v243, 0x9010, v243
	ds_read_b64_tr_b16 v[156:157], v244 offset:12288
	ds_read_b64_tr_b16 v[158:159], v244 offset:14336
	s_waitcnt lgkmcnt(10)
	v_mfma_f32_32x32x16_bf16 v[224:239], v[164:167], v[136:139], v[224:239]
	v_cvt_pk_bf16_f32 v80, v80, v81
	v_cvt_pk_bf16_f32 v81, v82, v83
	v_cvt_pk_bf16_f32 v82, v84, v85
	ds_read_b64_tr_b16 v[160:161], v244 offset:512
	ds_read_b64_tr_b16 v[162:163], v244 offset:2560
	s_waitcnt lgkmcnt(11)
	v_mfma_f32_32x32x16_bf16 v[208:223], v[168:171], v[140:143], v[208:223]
	v_cvt_pk_bf16_f32 v83, v86, v87
	v_cvt_pk_bf16_f32 v84, v88, v89
	v_cvt_pk_bf16_f32 v85, v90, v91
	ds_read_b64_tr_b16 v[164:165], v244 offset:4608
	ds_read_b64_tr_b16 v[166:167], v244 offset:6656
	s_waitcnt lgkmcnt(12)
	v_mfma_f32_32x32x16_bf16 v[224:239], v[172:175], v[140:143], v[224:239]
	v_cvt_pk_bf16_f32 v86, v92, v93
	v_cvt_pk_bf16_f32 v87, v94, v95
	ds_read_b64_tr_b16 v[168:169], v244 offset:8704
	ds_read_b64_tr_b16 v[170:171], v244 offset:10752
	s_waitcnt lgkmcnt(12)
	v_mfma_f32_32x32x16_bf16 v[48:63], v[64:67], v[144:147], v[48:63]
	ds_read_b64_tr_b16 v[172:173], v244 offset:12800
	ds_read_b64_tr_b16 v[174:175], v244 offset:14848
	s_waitcnt lgkmcnt(12)
	v_mfma_f32_32x32x16_bf16 v[48:63], v[68:71], v[148:151], v[48:63]
	ds_read_b64_tr_b16 v[144:145], v244 offset:1024
	ds_read_b64_tr_b16 v[146:147], v244 offset:3072
	s_waitcnt lgkmcnt(12)
	v_mfma_f32_32x32x16_bf16 v[48:63], v[80:83], v[152:155], v[48:63]
	v_exp_f32_e32 v208, v208
	v_exp_f32_e32 v209, v209
	ds_read_b64_tr_b16 v[148:149], v244 offset:5120
	ds_read_b64_tr_b16 v[150:151], v244 offset:7168
	s_waitcnt lgkmcnt(12)
	v_mfma_f32_32x32x16_bf16 v[48:63], v[84:87], v[156:159], v[48:63]
	v_exp_f32_e32 v210, v210
	v_exp_f32_e32 v211, v211
	ds_read_b64_tr_b16 v[152:153], v244 offset:9216
	ds_read_b64_tr_b16 v[154:155], v244 offset:11264
	s_waitcnt lgkmcnt(12)
	v_mfma_f32_32x32x16_bf16 v[32:47], v[64:67], v[160:163], v[32:47]
	v_exp_f32_e32 v212, v212
	ds_read_b64_tr_b16 v[156:157], v244 offset:13312
	ds_read_b64_tr_b16 v[158:159], v244 offset:15360
	s_waitcnt lgkmcnt(12)
	v_mfma_f32_32x32x16_bf16 v[32:47], v[68:71], v[164:167], v[32:47]
	v_exp_f32_e32 v213, v213
	ds_read_b64_tr_b16 v[160:161], v244 offset:1536
	ds_read_b64_tr_b16 v[162:163], v244 offset:3584
	s_waitcnt lgkmcnt(12)
	v_mfma_f32_32x32x16_bf16 v[32:47], v[80:83], v[168:171], v[32:47]
	v_exp_f32_e32 v214, v214
	ds_read_b64_tr_b16 v[164:165], v244 offset:5632
	ds_read_b64_tr_b16 v[166:167], v244 offset:7680
	s_waitcnt lgkmcnt(12)
	v_mfma_f32_32x32x16_bf16 v[32:47], v[84:87], v[172:175], v[32:47]
	v_exp_f32_e32 v215, v215
	ds_read_b64_tr_b16 v[168:169], v244 offset:9728
	ds_read_b64_tr_b16 v[170:171], v244 offset:11776
	s_waitcnt lgkmcnt(12)
	v_mfma_f32_32x32x16_bf16 v[16:31], v[64:67], v[144:147], v[16:31]
	v_exp_f32_e32 v216, v216
	ds_read_b64_tr_b16 v[172:173], v244 offset:13824
	ds_read_b64_tr_b16 v[174:175], v244 offset:15872
	s_waitcnt lgkmcnt(12)
	v_mfma_f32_32x32x16_bf16 v[16:31], v[68:71], v[148:151], v[16:31]
	v_exp_f32_e32 v217, v217
	v_add_u32_e32 v244, 0xffff8000, v244
	ds_read_b128 v[144:147], v240 offset:0
	s_waitcnt lgkmcnt(11)
	v_mfma_f32_32x32x16_bf16 v[16:31], v[80:83], v[152:155], v[16:31]
	v_exp_f32_e32 v218, v218
	ds_read_b128 v[148:151], v240 offset:12288
	s_waitcnt lgkmcnt(10)
	v_mfma_f32_32x32x16_bf16 v[16:31], v[84:87], v[156:159], v[16:31]
	v_exp_f32_e32 v219, v219
	ds_read_b128 v[152:155], v241 offset:0
	s_waitcnt lgkmcnt(9)
	v_mfma_f32_32x32x16_bf16 v[0:15], v[64:67], v[160:163], v[0:15]
	v_exp_f32_e32 v220, v220
	ds_read_b128 v[156:159], v241 offset:12288
	s_waitcnt lgkmcnt(8)
	v_mfma_f32_32x32x16_bf16 v[0:15], v[68:71], v[164:167], v[0:15]
	v_exp_f32_e32 v221, v221
	ds_read_b128 v[160:163], v242 offset:0
	s_waitcnt lgkmcnt(7)
	v_mfma_f32_32x32x16_bf16 v[0:15], v[80:83], v[168:171], v[0:15]
	v_exp_f32_e32 v222, v222
	ds_read_b128 v[164:167], v242 offset:12288
	s_waitcnt lgkmcnt(6)
	v_mfma_f32_32x32x16_bf16 v[0:15], v[84:87], v[172:175], v[0:15]
	v_exp_f32_e32 v223, v223
	s_waitcnt vmcnt(0)
	s_barrier
	ds_read_b128 v[168:171], v243 offset:0
	s_waitcnt lgkmcnt(6)
	v_mfma_f32_32x32x16_bf16 v[64:79], v[144:147], v[96:99], 0
	v_exp_f32_e32 v224, v224
	v_add_f32_e32 v245, v208, v245
	v_exp_f32_e32 v225, v225
	ds_read_b128 v[172:175], v243 offset:12288
	s_waitcnt lgkmcnt(6)
	v_mfma_f32_32x32x16_bf16 v[80:95], v[148:151], v[96:99], 0
	v_add_f32_e32 v246, v209, v246
	v_exp_f32_e32 v226, v226
	v_add_f32_e32 v245, v210, v245
	ds_read_b128 v[144:147], v240 offset:128
	s_waitcnt lgkmcnt(6)
	v_mfma_f32_32x32x16_bf16 v[64:79], v[152:155], v[100:103], v[64:79]
	v_exp_f32_e32 v227, v227
	v_add_f32_e32 v246, v211, v246
	v_exp_f32_e32 v228, v228
	ds_read_b128 v[148:151], v240 offset:12416
	s_waitcnt lgkmcnt(6)
	v_mfma_f32_32x32x16_bf16 v[80:95], v[156:159], v[100:103], v[80:95]
	v_add_f32_e32 v245, v212, v245
	v_exp_f32_e32 v229, v229
	v_add_f32_e32 v246, v213, v246
	ds_read_b128 v[152:155], v241 offset:128
	s_waitcnt lgkmcnt(6)
	v_mfma_f32_32x32x16_bf16 v[64:79], v[160:163], v[104:107], v[64:79]
	v_exp_f32_e32 v230, v230
	v_add_f32_e32 v245, v214, v245
	v_exp_f32_e32 v231, v231
	ds_read_b128 v[156:159], v241 offset:12416
	s_waitcnt lgkmcnt(6)
	v_mfma_f32_32x32x16_bf16 v[80:95], v[164:167], v[104:107], v[80:95]
	v_add_f32_e32 v246, v215, v246
	v_exp_f32_e32 v232, v232
	v_add_f32_e32 v245, v216, v245
	ds_read_b128 v[160:163], v242 offset:128
	s_waitcnt lgkmcnt(6)
	v_mfma_f32_32x32x16_bf16 v[64:79], v[168:171], v[108:111], v[64:79]
	v_exp_f32_e32 v233, v233
	v_add_f32_e32 v246, v217, v246
	v_exp_f32_e32 v234, v234
	ds_read_b128 v[164:167], v242 offset:12416
	s_waitcnt lgkmcnt(6)
	v_mfma_f32_32x32x16_bf16 v[80:95], v[172:175], v[108:111], v[80:95]
	v_add_f32_e32 v245, v218, v245
	v_exp_f32_e32 v235, v235
	v_add_f32_e32 v246, v219, v246
	ds_read_b128 v[168:171], v243 offset:128
	s_waitcnt lgkmcnt(6)
	v_mfma_f32_32x32x16_bf16 v[64:79], v[144:147], v[112:115], v[64:79]
	v_exp_f32_e32 v236, v236
	v_add_f32_e32 v245, v220, v245
	v_exp_f32_e32 v237, v237
	ds_read_b128 v[172:175], v243 offset:12416
	s_waitcnt lgkmcnt(6)
	v_mfma_f32_32x32x16_bf16 v[80:95], v[148:151], v[112:115], v[80:95]
	v_add_f32_e32 v246, v221, v246
	v_exp_f32_e32 v238, v238
	v_add_f32_e32 v245, v222, v245
	ds_read_b128 v[144:147], v240 offset:256
	s_waitcnt lgkmcnt(6)
	v_mfma_f32_32x32x16_bf16 v[64:79], v[152:155], v[116:119], v[64:79]
	v_exp_f32_e32 v239, v239
	v_add_f32_e32 v246, v223, v246
	v_add_f32_e32 v245, v224, v245
	ds_read_b128 v[148:151], v240 offset:12544
	s_waitcnt lgkmcnt(6)
	v_mfma_f32_32x32x16_bf16 v[80:95], v[156:159], v[116:119], v[80:95]
	v_add_f32_e32 v246, v225, v246
	v_add_f32_e32 v245, v226, v245
	v_add_f32_e32 v246, v227, v246
	ds_read_b128 v[152:155], v241 offset:256
	s_waitcnt lgkmcnt(6)
	v_mfma_f32_32x32x16_bf16 v[64:79], v[160:163], v[120:123], v[64:79]
	v_add_f32_e32 v245, v228, v245
	v_add_f32_e32 v246, v229, v246
	v_add_f32_e32 v245, v230, v245
	ds_read_b128 v[156:159], v241 offset:12544
	s_waitcnt lgkmcnt(6)
	v_mfma_f32_32x32x16_bf16 v[80:95], v[164:167], v[120:123], v[80:95]
	v_add_f32_e32 v246, v231, v246
	v_add_f32_e32 v245, v232, v245
	v_add_f32_e32 v246, v233, v246
	ds_read_b128 v[160:163], v242 offset:256
	s_waitcnt lgkmcnt(6)
	v_mfma_f32_32x32x16_bf16 v[64:79], v[168:171], v[124:127], v[64:79]
	v_add_f32_e32 v245, v234, v245
	v_add_f32_e32 v246, v235, v246
	v_add_f32_e32 v245, v236, v245
	ds_read_b128 v[164:167], v242 offset:12544
	s_waitcnt lgkmcnt(6)
	v_mfma_f32_32x32x16_bf16 v[80:95], v[172:175], v[124:127], v[80:95]
	v_add_f32_e32 v246, v237, v246
	v_add_f32_e32 v245, v238, v245
	v_add_f32_e32 v246, v239, v246
	ds_read_b128 v[168:171], v243 offset:256
	s_waitcnt lgkmcnt(6)
	v_mfma_f32_32x32x16_bf16 v[64:79], v[144:147], v[128:131], v[64:79]
	v_cvt_pk_bf16_f32 v208, v208, v209
	v_cvt_pk_bf16_f32 v209, v210, v211
	ds_read_b128 v[172:175], v243 offset:12544
	s_waitcnt lgkmcnt(6)
	v_mfma_f32_32x32x16_bf16 v[80:95], v[148:151], v[128:131], v[80:95]
	v_cvt_pk_bf16_f32 v210, v212, v213
	v_cvt_pk_bf16_f32 v211, v214, v215
	ds_read_b64_tr_b16 v[144:145], v244 offset:0
	ds_read_b64_tr_b16 v[146:147], v244 offset:2048
	s_waitcnt lgkmcnt(7)
	v_mfma_f32_32x32x16_bf16 v[64:79], v[152:155], v[132:135], v[64:79]
	v_cvt_pk_bf16_f32 v212, v216, v217
	v_cvt_pk_bf16_f32 v213, v218, v219
	ds_read_b64_tr_b16 v[148:149], v244 offset:4096
	ds_read_b64_tr_b16 v[150:151], v244 offset:6144
	s_waitcnt lgkmcnt(8)
	v_mfma_f32_32x32x16_bf16 v[80:95], v[156:159], v[132:135], v[80:95]
	v_cvt_pk_bf16_f32 v214, v220, v221
	v_cvt_pk_bf16_f32 v215, v222, v223
	ds_read_b64_tr_b16 v[152:153], v244 offset:8192
	ds_read_b64_tr_b16 v[154:155], v244 offset:10240
	s_waitcnt lgkmcnt(9)
	v_mfma_f32_32x32x16_bf16 v[64:79], v[160:163], v[136:139], v[64:79]
	v_cvt_pk_bf16_f32 v224, v224, v225
	v_cvt_pk_bf16_f32 v225, v226, v227
	ds_read_b64_tr_b16 v[156:157], v244 offset:12288
	ds_read_b64_tr_b16 v[158:159], v244 offset:14336
	s_waitcnt lgkmcnt(10)
	v_mfma_f32_32x32x16_bf16 v[80:95], v[164:167], v[136:139], v[80:95]
	v_cvt_pk_bf16_f32 v226, v228, v229
	v_cvt_pk_bf16_f32 v227, v230, v231
	ds_read_b64_tr_b16 v[160:161], v244 offset:512
	ds_read_b64_tr_b16 v[162:163], v244 offset:2560
	s_waitcnt lgkmcnt(11)
	v_mfma_f32_32x32x16_bf16 v[64:79], v[168:171], v[140:143], v[64:79]
	v_cvt_pk_bf16_f32 v228, v232, v233
	v_cvt_pk_bf16_f32 v229, v234, v235
	ds_read_b64_tr_b16 v[164:165], v244 offset:4608
	ds_read_b64_tr_b16 v[166:167], v244 offset:6656
	s_waitcnt lgkmcnt(12)
	v_mfma_f32_32x32x16_bf16 v[80:95], v[172:175], v[140:143], v[80:95]
	v_cvt_pk_bf16_f32 v230, v236, v237
	v_cvt_pk_bf16_f32 v231, v238, v239
	ds_read_b64_tr_b16 v[168:169], v244 offset:8704
	ds_read_b64_tr_b16 v[170:171], v244 offset:10752
	s_waitcnt lgkmcnt(12)
	v_mfma_f32_32x32x16_bf16 v[48:63], v[208:211], v[144:147], v[48:63]
	ds_read_b64_tr_b16 v[172:173], v244 offset:12800
	ds_read_b64_tr_b16 v[174:175], v244 offset:14848
	s_waitcnt lgkmcnt(12)
	v_mfma_f32_32x32x16_bf16 v[48:63], v[212:215], v[148:151], v[48:63]
	ds_read_b64_tr_b16 v[144:145], v244 offset:1024
	ds_read_b64_tr_b16 v[146:147], v244 offset:3072
	s_waitcnt lgkmcnt(12)
	v_mfma_f32_32x32x16_bf16 v[48:63], v[224:227], v[152:155], v[48:63]
	v_exp_f32_e32 v64, v64
	v_exp_f32_e32 v65, v65
	ds_read_b64_tr_b16 v[148:149], v244 offset:5120
	ds_read_b64_tr_b16 v[150:151], v244 offset:7168
	s_waitcnt lgkmcnt(12)
	v_mfma_f32_32x32x16_bf16 v[48:63], v[228:231], v[156:159], v[48:63]
	v_exp_f32_e32 v66, v66
	v_exp_f32_e32 v67, v67
	ds_read_b64_tr_b16 v[152:153], v244 offset:9216
	ds_read_b64_tr_b16 v[154:155], v244 offset:11264
	s_waitcnt lgkmcnt(12)
	v_mfma_f32_32x32x16_bf16 v[32:47], v[208:211], v[160:163], v[32:47]
	v_exp_f32_e32 v68, v68
	ds_read_b64_tr_b16 v[156:157], v244 offset:13312
	ds_read_b64_tr_b16 v[158:159], v244 offset:15360
	s_waitcnt lgkmcnt(12)
	v_mfma_f32_32x32x16_bf16 v[32:47], v[212:215], v[164:167], v[32:47]
	v_exp_f32_e32 v69, v69
	ds_read_b64_tr_b16 v[160:161], v244 offset:1536
	ds_read_b64_tr_b16 v[162:163], v244 offset:3584
	s_waitcnt lgkmcnt(12)
	v_mfma_f32_32x32x16_bf16 v[32:47], v[224:227], v[168:171], v[32:47]
	v_exp_f32_e32 v70, v70
	ds_read_b64_tr_b16 v[164:165], v244 offset:5632
	ds_read_b64_tr_b16 v[166:167], v244 offset:7680
	s_waitcnt lgkmcnt(12)
	v_mfma_f32_32x32x16_bf16 v[32:47], v[228:231], v[172:175], v[32:47]
	v_exp_f32_e32 v71, v71
	ds_read_b64_tr_b16 v[168:169], v244 offset:9728
	ds_read_b64_tr_b16 v[170:171], v244 offset:11776
	s_waitcnt lgkmcnt(12)
	v_mfma_f32_32x32x16_bf16 v[16:31], v[208:211], v[144:147], v[16:31]
	v_exp_f32_e32 v72, v72
	ds_read_b64_tr_b16 v[172:173], v244 offset:13824
	ds_read_b64_tr_b16 v[174:175], v244 offset:15872
	s_waitcnt lgkmcnt(12)
	v_mfma_f32_32x32x16_bf16 v[16:31], v[212:215], v[148:151], v[16:31]
	v_exp_f32_e32 v73, v73
	v_add_u32_e32 v244, 0x4000, v244
	s_waitcnt lgkmcnt(10)
	v_mfma_f32_32x32x16_bf16 v[16:31], v[224:227], v[152:155], v[16:31]
	v_exp_f32_e32 v74, v74
	s_waitcnt lgkmcnt(8)
	v_mfma_f32_32x32x16_bf16 v[16:31], v[228:231], v[156:159], v[16:31]
	v_exp_f32_e32 v75, v75
	s_waitcnt lgkmcnt(6)
	v_mfma_f32_32x32x16_bf16 v[0:15], v[208:211], v[160:163], v[0:15]
	v_exp_f32_e32 v76, v76
	s_waitcnt lgkmcnt(4)
	v_mfma_f32_32x32x16_bf16 v[0:15], v[212:215], v[164:167], v[0:15]
	v_exp_f32_e32 v77, v77
	s_waitcnt lgkmcnt(2)
	v_mfma_f32_32x32x16_bf16 v[0:15], v[224:227], v[168:171], v[0:15]
	v_exp_f32_e32 v78, v78
	s_waitcnt lgkmcnt(0)
	v_mfma_f32_32x32x16_bf16 v[0:15], v[228:231], v[172:175], v[0:15]
	v_exp_f32_e32 v79, v79
	ds_read_b64_tr_b16 v[144:145], v244 offset:0
	ds_read_b64_tr_b16 v[146:147], v244 offset:2048
	ds_read_b64_tr_b16 v[148:149], v244 offset:4096
	ds_read_b64_tr_b16 v[150:151], v244 offset:6144
	ds_read_b64_tr_b16 v[152:153], v244 offset:8192
	ds_read_b64_tr_b16 v[154:155], v244 offset:10240
	ds_read_b64_tr_b16 v[156:157], v244 offset:12288
	ds_read_b64_tr_b16 v[158:159], v244 offset:14336
	ds_read_b64_tr_b16 v[160:161], v244 offset:512
	ds_read_b64_tr_b16 v[162:163], v244 offset:2560
	ds_read_b64_tr_b16 v[164:165], v244 offset:4608
	ds_read_b64_tr_b16 v[166:167], v244 offset:6656
	v_exp_f32_e32 v80, v80
	v_add_f32_e32 v245, v64, v245
	v_exp_f32_e32 v81, v81
	v_add_f32_e32 v246, v65, v246
	v_exp_f32_e32 v82, v82
	v_add_f32_e32 v245, v66, v245
	v_exp_f32_e32 v83, v83
	v_add_f32_e32 v246, v67, v246
	v_exp_f32_e32 v84, v84
	v_add_f32_e32 v245, v68, v245
	v_exp_f32_e32 v85, v85
	v_add_f32_e32 v246, v69, v246
	v_exp_f32_e32 v86, v86
	v_add_f32_e32 v245, v70, v245
	v_exp_f32_e32 v87, v87
	v_add_f32_e32 v246, v71, v246
	v_exp_f32_e32 v88, v88
	v_add_f32_e32 v245, v72, v245
	v_exp_f32_e32 v89, v89
	v_add_f32_e32 v246, v73, v246
	v_exp_f32_e32 v90, v90
	v_add_f32_e32 v245, v74, v245
	v_exp_f32_e32 v91, v91
	v_add_f32_e32 v246, v75, v246
	v_exp_f32_e32 v92, v92
	v_add_f32_e32 v245, v76, v245
	v_exp_f32_e32 v93, v93
	v_add_f32_e32 v246, v77, v246
	v_exp_f32_e32 v94, v94
	v_add_f32_e32 v245, v78, v245
	v_exp_f32_e32 v95, v95
	v_add_f32_e32 v246, v79, v246
	v_add_f32_e32 v245, v80, v245
	v_add_f32_e32 v246, v81, v246
	v_add_f32_e32 v245, v82, v245
	v_add_f32_e32 v246, v83, v246
	v_add_f32_e32 v245, v84, v245
	v_add_f32_e32 v246, v85, v246
	v_add_f32_e32 v245, v86, v245
	v_add_f32_e32 v246, v87, v246
	v_add_f32_e32 v245, v88, v245
	v_add_f32_e32 v246, v89, v246
	v_add_f32_e32 v245, v90, v245
	v_add_f32_e32 v246, v91, v246
	v_add_f32_e32 v245, v92, v245
	v_add_f32_e32 v246, v93, v246
	v_add_f32_e32 v245, v94, v245
	v_add_f32_e32 v246, v95, v246
	v_cvt_pk_bf16_f32 v64, v64, v65
	v_cvt_pk_bf16_f32 v65, v66, v67
	v_cvt_pk_bf16_f32 v66, v68, v69
	v_cvt_pk_bf16_f32 v67, v70, v71
	v_cvt_pk_bf16_f32 v68, v72, v73
	v_cvt_pk_bf16_f32 v69, v74, v75
	v_cvt_pk_bf16_f32 v70, v76, v77
	v_cvt_pk_bf16_f32 v71, v78, v79
	v_cvt_pk_bf16_f32 v80, v80, v81
	v_cvt_pk_bf16_f32 v81, v82, v83
	v_cvt_pk_bf16_f32 v82, v84, v85
	v_cvt_pk_bf16_f32 v83, v86, v87
	v_cvt_pk_bf16_f32 v84, v88, v89
	v_cvt_pk_bf16_f32 v85, v90, v91
	v_cvt_pk_bf16_f32 v86, v92, v93
	v_cvt_pk_bf16_f32 v87, v94, v95
	ds_read_b64_tr_b16 v[168:169], v244 offset:8704
	ds_read_b64_tr_b16 v[170:171], v244 offset:10752
	s_waitcnt lgkmcnt(12)
	v_mfma_f32_32x32x16_bf16 v[48:63], v[64:67], v[144:147], v[48:63]
	ds_read_b64_tr_b16 v[172:173], v244 offset:12800
	ds_read_b64_tr_b16 v[174:175], v244 offset:14848
	s_waitcnt lgkmcnt(12)
	v_mfma_f32_32x32x16_bf16 v[48:63], v[68:71], v[148:151], v[48:63]
	ds_read_b64_tr_b16 v[144:145], v244 offset:1024
	ds_read_b64_tr_b16 v[146:147], v244 offset:3072
	s_waitcnt lgkmcnt(12)
	v_mfma_f32_32x32x16_bf16 v[48:63], v[80:83], v[152:155], v[48:63]
	ds_read_b64_tr_b16 v[148:149], v244 offset:5120
	ds_read_b64_tr_b16 v[150:151], v244 offset:7168
	s_waitcnt lgkmcnt(12)
	v_mfma_f32_32x32x16_bf16 v[48:63], v[84:87], v[156:159], v[48:63]
	ds_read_b64_tr_b16 v[152:153], v244 offset:9216
	ds_read_b64_tr_b16 v[154:155], v244 offset:11264
	s_waitcnt lgkmcnt(12)
	v_mfma_f32_32x32x16_bf16 v[32:47], v[64:67], v[160:163], v[32:47]
	ds_read_b64_tr_b16 v[156:157], v244 offset:13312
	ds_read_b64_tr_b16 v[158:159], v244 offset:15360
	s_waitcnt lgkmcnt(12)
	v_mfma_f32_32x32x16_bf16 v[32:47], v[68:71], v[164:167], v[32:47]
	ds_read_b64_tr_b16 v[160:161], v244 offset:1536
	ds_read_b64_tr_b16 v[162:163], v244 offset:3584
	s_waitcnt lgkmcnt(12)
	v_mfma_f32_32x32x16_bf16 v[32:47], v[80:83], v[168:171], v[32:47]
	ds_read_b64_tr_b16 v[164:165], v244 offset:5632
	ds_read_b64_tr_b16 v[166:167], v244 offset:7680
	s_waitcnt lgkmcnt(12)
	v_mfma_f32_32x32x16_bf16 v[32:47], v[84:87], v[172:175], v[32:47]
	ds_read_b64_tr_b16 v[168:169], v244 offset:9728
	ds_read_b64_tr_b16 v[170:171], v244 offset:11776
	s_waitcnt lgkmcnt(12)
	v_mfma_f32_32x32x16_bf16 v[16:31], v[64:67], v[144:147], v[16:31]
	ds_read_b64_tr_b16 v[172:173], v244 offset:13824
	ds_read_b64_tr_b16 v[174:175], v244 offset:15872
	s_waitcnt lgkmcnt(12)
	v_mfma_f32_32x32x16_bf16 v[16:31], v[68:71], v[148:151], v[16:31]
	s_waitcnt lgkmcnt(10)
	v_mfma_f32_32x32x16_bf16 v[16:31], v[80:83], v[152:155], v[16:31]
	s_waitcnt lgkmcnt(8)
	v_mfma_f32_32x32x16_bf16 v[16:31], v[84:87], v[156:159], v[16:31]
	s_waitcnt lgkmcnt(6)
	v_mfma_f32_32x32x16_bf16 v[0:15], v[64:67], v[160:163], v[0:15]
	s_waitcnt lgkmcnt(4)
	v_mfma_f32_32x32x16_bf16 v[0:15], v[68:71], v[164:167], v[0:15]
	s_waitcnt lgkmcnt(2)
	v_mfma_f32_32x32x16_bf16 v[0:15], v[80:83], v[168:171], v[0:15]
	s_waitcnt lgkmcnt(0)
	v_mfma_f32_32x32x16_bf16 v[0:15], v[84:87], v[172:175], v[0:15]
	v_add_f32_e32 v245, v245, v246
	v_mov_b32_e32 v246, v245
	s_nop 1
	v_permlane32_swap_b32_e32 v245, v246
	v_add_f32_e32 v245, v245, v246
	v_cmp_gt_u32_e32 vcc, 32, v200
	v_lshl_add_u32 v247, v196, 2, s44
	s_and_saveexec_b64 s[42:43], vcc
	ds_write_b32 v247, v245
	s_or_b64 exec, exec, s[42:43]
	s_lshl_b64 s[2:3], s[40:41], 13
	s_or_b64 s[12:13], s[2:3], s[34:35]
	s_mul_i32 s1, s13, 0x3600
	s_mul_hi_u32 s2, s12, 0x3600
	s_add_i32 s1, s2, s1
	s_mul_i32 s14, s12, 0x3600
	s_lshl_b64 s[2:3], s[12:13], 12
	s_lshl_b64 s[12:13], s[12:13], 5
	s_add_u32 s14, s38, s14
	s_addc_u32 s1, s39, s1
	s_add_u32 s15, s72, s2
	s_addc_u32 s30, s73, s3
	s_lshl_b32 s31, s49, 8
	v_lshl_or_b32 v164, v198, 2, s52
	s_add_u32 s2, s14, s31
	s_addc_u32 s3, s1, 0
	s_add_u32 s2, s2, 0x11802c80
	s_addc_u32 s3, s3, 0
	v_subrev_u32_e32 v165, s52, v164
	v_lshl_add_u32 v166, v165, 2, s44
	s_add_u32 s14, s15, s31
	s_addc_u32 s15, s30, 0
	s_add_u32 s1, s74, s12
	s_addc_u32 s12, s75, s13
	s_lshl_b32 s13, s49, 2
	s_add_u32 s42, s1, s13
	s_addc_u32 s43, s12, 0
	v_lshlrev_b32_e32 v167, 1, v196
	v_mul_u32_u24_e32 v168, 0x3600, v164
	v_lshl_add_u32 v169, v164, 12, v167
	v_add_u32_e32 v168, v168, v167
	v_lshlrev_b32_e32 v170, 5, v164
	s_waitcnt lgkmcnt(0)
	ds_read_b32 v128, v166 offset:0
	ds_read_b32 v129, v166 offset:4
	ds_read_b32 v130, v166 offset:8
	ds_read_b32 v131, v166 offset:12
	ds_read_b32 v132, v166 offset:32
	ds_read_b32 v133, v166 offset:36
	ds_read_b32 v134, v166 offset:40
	ds_read_b32 v135, v166 offset:44
	ds_read_b32 v136, v166 offset:64
	ds_read_b32 v137, v166 offset:68
	ds_read_b32 v138, v166 offset:72
	ds_read_b32 v139, v166 offset:76
	ds_read_b32 v140, v166 offset:96
	ds_read_b32 v141, v166 offset:100
	ds_read_b32 v142, v166 offset:104
	ds_read_b32 v143, v166 offset:108
	v_mov_b32_e32 v171, v168
	global_load_ushort v64, v171, s[2:3] offset:0
	global_load_ushort v65, v171, s[2:3] offset:64
	global_load_ushort v66, v171, s[2:3] offset:128
	global_load_ushort v67, v171, s[2:3] offset:192
	v_add_u32_e32 v172, 0x3600, v168
	global_load_ushort v68, v172, s[2:3] offset:0
	global_load_ushort v69, v172, s[2:3] offset:64
	global_load_ushort v70, v172, s[2:3] offset:128
	global_load_ushort v71, v172, s[2:3] offset:192
	v_add_u32_e32 v173, 0x6c00, v168
	global_load_ushort v72, v173, s[2:3] offset:0
	global_load_ushort v73, v173, s[2:3] offset:64
	global_load_ushort v74, v173, s[2:3] offset:128
	global_load_ushort v75, v173, s[2:3] offset:192
	v_add_u32_e32 v174, 0xa200, v168
	global_load_ushort v76, v174, s[2:3] offset:0
	global_load_ushort v77, v174, s[2:3] offset:64
	global_load_ushort v78, v174, s[2:3] offset:128
	global_load_ushort v79, v174, s[2:3] offset:192
	v_add_u32_e32 v171, 0x1b000, v168
	global_load_ushort v80, v171, s[2:3] offset:0
	global_load_ushort v81, v171, s[2:3] offset:64
	global_load_ushort v82, v171, s[2:3] offset:128
	global_load_ushort v83, v171, s[2:3] offset:192
	v_add_u32_e32 v172, 0x1e600, v168
	global_load_ushort v84, v172, s[2:3] offset:0
	global_load_ushort v85, v172, s[2:3] offset:64
	global_load_ushort v86, v172, s[2:3] offset:128
	global_load_ushort v87, v172, s[2:3] offset:192
	v_add_u32_e32 v173, 0x21c00, v168
	global_load_ushort v88, v173, s[2:3] offset:0
	global_load_ushort v89, v173, s[2:3] offset:64
	global_load_ushort v90, v173, s[2:3] offset:128
	global_load_ushort v91, v173, s[2:3] offset:192
	v_add_u32_e32 v174, 0x25200, v168
	global_load_ushort v92, v174, s[2:3] offset:0
	global_load_ushort v93, v174, s[2:3] offset:64
	global_load_ushort v94, v174, s[2:3] offset:128
	global_load_ushort v95, v174, s[2:3] offset:192
	v_add_u32_e32 v171, 0x36000, v168
	global_load_ushort v96, v171, s[2:3] offset:0
	global_load_ushort v97, v171, s[2:3] offset:64
	global_load_ushort v98, v171, s[2:3] offset:128
	global_load_ushort v99, v171, s[2:3] offset:192
	v_add_u32_e32 v172, 0x39600, v168
	global_load_ushort v100, v172, s[2:3] offset:0
	global_load_ushort v101, v172, s[2:3] offset:64
	global_load_ushort v102, v172, s[2:3] offset:128
	global_load_ushort v103, v172, s[2:3] offset:192
	v_add_u32_e32 v173, 0x3cc00, v168
	global_load_ushort v104, v173, s[2:3] offset:0
	global_load_ushort v105, v173, s[2:3] offset:64
	global_load_ushort v106, v173, s[2:3] offset:128
	global_load_ushort v107, v173, s[2:3] offset:192
	v_add_u32_e32 v174, 0x40200, v168
	global_load_ushort v108, v174, s[2:3] offset:0
	global_load_ushort v109, v174, s[2:3] offset:64
	global_load_ushort v110, v174, s[2:3] offset:128
	global_load_ushort v111, v174, s[2:3] offset:192
	v_add_u32_e32 v171, 0x51000, v168
	global_load_ushort v112, v171, s[2:3] offset:0
	global_load_ushort v113, v171, s[2:3] offset:64
	global_load_ushort v114, v171, s[2:3] offset:128
	global_load_ushort v115, v171, s[2:3] offset:192
	v_add_u32_e32 v172, 0x54600, v168
	global_load_ushort v116, v172, s[2:3] offset:0
	global_load_ushort v117, v172, s[2:3] offset:64
	global_load_ushort v118, v172, s[2:3] offset:128
	global_load_ushort v119, v172, s[2:3] offset:192
	v_add_u32_e32 v173, 0x57c00, v168
	global_load_ushort v120, v173, s[2:3] offset:0
	global_load_ushort v121, v173, s[2:3] offset:64
	global_load_ushort v122, v173, s[2:3] offset:128
	global_load_ushort v123, v173, s[2:3] offset:192
	v_add_u32_e32 v174, 0x5b200, v168
	global_load_ushort v124, v174, s[2:3] offset:0
	global_load_ushort v125, v174, s[2:3] offset:64
	global_load_ushort v126, v174, s[2:3] offset:128
	global_load_ushort v127, v174, s[2:3] offset:192
	s_waitcnt lgkmcnt(0)
	v_rcp_f32_e32 v128, v128
	v_rcp_f32_e32 v129, v129
	v_rcp_f32_e32 v130, v130
	v_rcp_f32_e32 v131, v131
	v_rcp_f32_e32 v132, v132
	v_rcp_f32_e32 v133, v133
	v_rcp_f32_e32 v134, v134
	v_rcp_f32_e32 v135, v135
	v_rcp_f32_e32 v136, v136
	v_rcp_f32_e32 v137, v137
	v_rcp_f32_e32 v138, v138
	v_rcp_f32_e32 v139, v139
	v_rcp_f32_e32 v140, v140
	v_rcp_f32_e32 v141, v141
	v_rcp_f32_e32 v142, v142
	v_rcp_f32_e32 v143, v143
	v_mul_f32_e32 v48, v48, v128
	v_mul_f32_e32 v32, v32, v128
	v_mul_f32_e32 v16, v16, v128
	v_mul_f32_e32 v0, v0, v128
	v_mul_f32_e32 v49, v49, v129
	v_mul_f32_e32 v33, v33, v129
	v_mul_f32_e32 v17, v17, v129
	v_mul_f32_e32 v1, v1, v129
	v_mul_f32_e32 v50, v50, v130
	v_mul_f32_e32 v34, v34, v130
	v_mul_f32_e32 v18, v18, v130
	v_mul_f32_e32 v2, v2, v130
	v_mul_f32_e32 v51, v51, v131
	v_mul_f32_e32 v35, v35, v131
	v_mul_f32_e32 v19, v19, v131
	v_mul_f32_e32 v3, v3, v131
	v_mul_f32_e32 v52, v52, v132
	v_mul_f32_e32 v36, v36, v132
	v_mul_f32_e32 v20, v20, v132
	v_mul_f32_e32 v4, v4, v132
	v_mul_f32_e32 v53, v53, v133
	v_mul_f32_e32 v37, v37, v133
	v_mul_f32_e32 v21, v21, v133
	v_mul_f32_e32 v5, v5, v133
	v_mul_f32_e32 v54, v54, v134
	v_mul_f32_e32 v38, v38, v134
	v_mul_f32_e32 v22, v22, v134
	v_mul_f32_e32 v6, v6, v134
	v_mul_f32_e32 v55, v55, v135
	v_mul_f32_e32 v39, v39, v135
	v_mul_f32_e32 v23, v23, v135
	v_mul_f32_e32 v7, v7, v135
	v_mul_f32_e32 v56, v56, v136
	v_mul_f32_e32 v40, v40, v136
	v_mul_f32_e32 v24, v24, v136
	v_mul_f32_e32 v8, v8, v136
	v_mul_f32_e32 v57, v57, v137
	v_mul_f32_e32 v41, v41, v137
	v_mul_f32_e32 v25, v25, v137
	v_mul_f32_e32 v9, v9, v137
	v_mul_f32_e32 v58, v58, v138
	v_mul_f32_e32 v42, v42, v138
	v_mul_f32_e32 v26, v26, v138
	v_mul_f32_e32 v10, v10, v138
	v_mul_f32_e32 v59, v59, v139
	v_mul_f32_e32 v43, v43, v139
	v_mul_f32_e32 v27, v27, v139
	v_mul_f32_e32 v11, v11, v139
	v_mul_f32_e32 v60, v60, v140
	v_mul_f32_e32 v44, v44, v140
	v_mul_f32_e32 v28, v28, v140
	v_mul_f32_e32 v12, v12, v140
	v_mul_f32_e32 v61, v61, v141
	v_mul_f32_e32 v45, v45, v141
	v_mul_f32_e32 v29, v29, v141
	v_mul_f32_e32 v13, v13, v141
	v_mul_f32_e32 v62, v62, v142
	v_mul_f32_e32 v46, v46, v142
	v_mul_f32_e32 v30, v30, v142
	v_mul_f32_e32 v14, v14, v142
	v_mul_f32_e32 v63, v63, v143
	v_mul_f32_e32 v47, v47, v143
	v_mul_f32_e32 v31, v31, v143
	v_mul_f32_e32 v15, v15, v143
	s_waitcnt vmcnt(60)
	v_mov_b32_e32 v182, v169
	v_lshlrev_b32_e32 v64, 16, v64
	v_lshlrev_b32_e32 v65, 16, v65
	v_lshlrev_b32_e32 v66, 16, v66
	v_lshlrev_b32_e32 v67, 16, v67
	v_mul_f32_e32 v208, 0xbfb8aa3b, v64
	v_mul_f32_e32 v214, 0xbfb8aa3b, v65
	v_mul_f32_e32 v220, 0xbfb8aa3b, v66
	v_mul_f32_e32 v226, 0xbfb8aa3b, v67
	v_exp_f32_e32 v208, v208
	v_exp_f32_e32 v214, v214
	v_exp_f32_e32 v220, v220
	v_exp_f32_e32 v226, v226
	v_add_f32_e32 v208, 1.0, v208
	v_add_f32_e32 v214, 1.0, v214
	v_add_f32_e32 v220, 1.0, v220
	v_add_f32_e32 v226, 1.0, v226
	v_div_scale_f32 v209, s[12:13], v208, v208, v64
	v_div_scale_f32 v215, s[12:13], v214, v214, v65
	v_div_scale_f32 v221, s[12:13], v220, v220, v66
	v_div_scale_f32 v227, s[12:13], v226, v226, v67
	v_rcp_f32_e32 v210, v209
	v_rcp_f32_e32 v216, v215
	v_rcp_f32_e32 v222, v221
	v_rcp_f32_e32 v228, v227
	v_fma_f32 v211, -v209, v210, 1.0
	v_fma_f32 v217, -v215, v216, 1.0
	v_fma_f32 v223, -v221, v222, 1.0
	v_fma_f32 v229, -v227, v228, 1.0
	v_fmac_f32_e32 v210, v211, v210
	v_fmac_f32_e32 v216, v217, v216
	v_fmac_f32_e32 v222, v223, v222
	v_fmac_f32_e32 v228, v229, v228
	v_div_scale_f32 v211, vcc, v64, v208, v64
	v_mul_f32_e32 v212, v211, v210
	v_fma_f32 v213, -v209, v212, v211
	v_fmac_f32_e32 v212, v213, v210
	v_fma_f32 v209, -v209, v212, v211
	v_div_fmas_f32 v209, v209, v210, v212
	v_div_fixup_f32 v64, v209, v208, v64
	v_div_scale_f32 v217, vcc, v65, v214, v65
	v_mul_f32_e32 v218, v217, v216
	v_fma_f32 v219, -v215, v218, v217
	v_fmac_f32_e32 v218, v219, v216
	v_fma_f32 v215, -v215, v218, v217
	v_div_fmas_f32 v215, v215, v216, v218
	v_div_fixup_f32 v65, v215, v214, v65
	v_div_scale_f32 v223, vcc, v66, v220, v66
	v_mul_f32_e32 v224, v223, v222
	v_fma_f32 v225, -v221, v224, v223
	v_fmac_f32_e32 v224, v225, v222
	v_fma_f32 v221, -v221, v224, v223
	v_div_fmas_f32 v221, v221, v222, v224
	v_div_fixup_f32 v66, v221, v220, v66
	v_div_scale_f32 v229, vcc, v67, v226, v67
	v_mul_f32_e32 v230, v229, v228
	v_fma_f32 v231, -v227, v230, v229
	v_fmac_f32_e32 v230, v231, v228
	v_fma_f32 v227, -v227, v230, v229
	v_div_fmas_f32 v227, v227, v228, v230
	v_div_fixup_f32 v67, v227, v226, v67
	v_mul_f32_e32 v48, v48, v64
	v_mul_f32_e32 v32, v32, v65
	v_mul_f32_e32 v16, v16, v66
	v_mul_f32_e32 v0, v0, v67
	v_mul_f32_e32 v148, v32, v32
	v_fmac_f32_e32 v148, v48, v48
	v_fmac_f32_e32 v148, v16, v16
	v_fmac_f32_e32 v148, v0, v0
	v_cvt_pk_bf16_f32 v64, v48, v177
	v_cvt_pk_bf16_f32 v65, v32, v177
	v_cvt_pk_bf16_f32 v66, v16, v177
	v_cvt_pk_bf16_f32 v67, v0, v177
	global_store_short v182, v64, s[14:15] offset:0
	global_store_short v182, v65, s[14:15] offset:64
	global_store_short v182, v66, s[14:15] offset:128
	global_store_short v182, v67, s[14:15] offset:192
	s_waitcnt vmcnt(60)
	v_add_u32_e32 v175, 0x1000, v169
	v_lshlrev_b32_e32 v68, 16, v68
	v_lshlrev_b32_e32 v69, 16, v69
	v_lshlrev_b32_e32 v70, 16, v70
	v_lshlrev_b32_e32 v71, 16, v71
	v_mul_f32_e32 v208, 0xbfb8aa3b, v68
	v_mul_f32_e32 v214, 0xbfb8aa3b, v69
	v_mul_f32_e32 v220, 0xbfb8aa3b, v70
	v_mul_f32_e32 v226, 0xbfb8aa3b, v71
	v_exp_f32_e32 v208, v208
	v_exp_f32_e32 v214, v214
	v_exp_f32_e32 v220, v220
	v_exp_f32_e32 v226, v226
	v_add_f32_e32 v208, 1.0, v208
	v_add_f32_e32 v214, 1.0, v214
	v_add_f32_e32 v220, 1.0, v220
	v_add_f32_e32 v226, 1.0, v226
	v_div_scale_f32 v209, s[12:13], v208, v208, v68
	v_div_scale_f32 v215, s[12:13], v214, v214, v69
	v_div_scale_f32 v221, s[12:13], v220, v220, v70
	v_div_scale_f32 v227, s[12:13], v226, v226, v71
	v_rcp_f32_e32 v210, v209
	v_rcp_f32_e32 v216, v215
	v_rcp_f32_e32 v222, v221
	v_rcp_f32_e32 v228, v227
	v_fma_f32 v211, -v209, v210, 1.0
	v_fma_f32 v217, -v215, v216, 1.0
	v_fma_f32 v223, -v221, v222, 1.0
	v_fma_f32 v229, -v227, v228, 1.0
	v_fmac_f32_e32 v210, v211, v210
	v_fmac_f32_e32 v216, v217, v216
	v_fmac_f32_e32 v222, v223, v222
	v_fmac_f32_e32 v228, v229, v228
	v_div_scale_f32 v211, vcc, v68, v208, v68
	v_mul_f32_e32 v212, v211, v210
	v_fma_f32 v213, -v209, v212, v211
	v_fmac_f32_e32 v212, v213, v210
	v_fma_f32 v209, -v209, v212, v211
	v_div_fmas_f32 v209, v209, v210, v212
	v_div_fixup_f32 v68, v209, v208, v68
	v_div_scale_f32 v217, vcc, v69, v214, v69
	v_mul_f32_e32 v218, v217, v216
	v_fma_f32 v219, -v215, v218, v217
	v_fmac_f32_e32 v218, v219, v216
	v_fma_f32 v215, -v215, v218, v217
	v_div_fmas_f32 v215, v215, v216, v218
	v_div_fixup_f32 v69, v215, v214, v69
	v_div_scale_f32 v223, vcc, v70, v220, v70
	v_mul_f32_e32 v224, v223, v222
	v_fma_f32 v225, -v221, v224, v223
	v_fmac_f32_e32 v224, v225, v222
	v_fma_f32 v221, -v221, v224, v223
	v_div_fmas_f32 v221, v221, v222, v224
	v_div_fixup_f32 v70, v221, v220, v70
	v_div_scale_f32 v229, vcc, v71, v226, v71
	v_mul_f32_e32 v230, v229, v228
	v_fma_f32 v231, -v227, v230, v229
	v_fmac_f32_e32 v230, v231, v228
	v_fma_f32 v227, -v227, v230, v229
	v_div_fmas_f32 v227, v227, v228, v230
	v_div_fixup_f32 v71, v227, v226, v71
	v_mul_f32_e32 v49, v49, v68
	v_mul_f32_e32 v33, v33, v69
	v_mul_f32_e32 v17, v17, v70
	v_mul_f32_e32 v1, v1, v71
	v_mul_f32_e32 v149, v33, v33
	v_fmac_f32_e32 v149, v49, v49
	v_fmac_f32_e32 v149, v17, v17
	v_fmac_f32_e32 v149, v1, v1
	v_cvt_pk_bf16_f32 v68, v49, v177
	v_cvt_pk_bf16_f32 v69, v33, v177
	v_cvt_pk_bf16_f32 v70, v17, v177
	v_cvt_pk_bf16_f32 v71, v1, v177
	global_store_short v175, v68, s[14:15] offset:0
	global_store_short v175, v69, s[14:15] offset:64
	global_store_short v175, v70, s[14:15] offset:128
	global_store_short v175, v71, s[14:15] offset:192
	s_waitcnt vmcnt(60)
	v_add_u32_e32 v182, 0x2000, v169
	v_lshlrev_b32_e32 v72, 16, v72
	v_lshlrev_b32_e32 v73, 16, v73
	v_lshlrev_b32_e32 v74, 16, v74
	v_lshlrev_b32_e32 v75, 16, v75
	v_mul_f32_e32 v208, 0xbfb8aa3b, v72
	v_mul_f32_e32 v214, 0xbfb8aa3b, v73
	v_mul_f32_e32 v220, 0xbfb8aa3b, v74
	v_mul_f32_e32 v226, 0xbfb8aa3b, v75
	v_exp_f32_e32 v208, v208
	v_exp_f32_e32 v214, v214
	v_exp_f32_e32 v220, v220
	v_exp_f32_e32 v226, v226
	v_add_f32_e32 v208, 1.0, v208
	v_add_f32_e32 v214, 1.0, v214
	v_add_f32_e32 v220, 1.0, v220
	v_add_f32_e32 v226, 1.0, v226
	v_div_scale_f32 v209, s[12:13], v208, v208, v72
	v_div_scale_f32 v215, s[12:13], v214, v214, v73
	v_div_scale_f32 v221, s[12:13], v220, v220, v74
	v_div_scale_f32 v227, s[12:13], v226, v226, v75
	v_rcp_f32_e32 v210, v209
	v_rcp_f32_e32 v216, v215
	v_rcp_f32_e32 v222, v221
	v_rcp_f32_e32 v228, v227
	v_fma_f32 v211, -v209, v210, 1.0
	v_fma_f32 v217, -v215, v216, 1.0
	v_fma_f32 v223, -v221, v222, 1.0
	v_fma_f32 v229, -v227, v228, 1.0
	v_fmac_f32_e32 v210, v211, v210
	v_fmac_f32_e32 v216, v217, v216
	v_fmac_f32_e32 v222, v223, v222
	v_fmac_f32_e32 v228, v229, v228
	v_div_scale_f32 v211, vcc, v72, v208, v72
	v_mul_f32_e32 v212, v211, v210
	v_fma_f32 v213, -v209, v212, v211
	v_fmac_f32_e32 v212, v213, v210
	v_fma_f32 v209, -v209, v212, v211
	v_div_fmas_f32 v209, v209, v210, v212
	v_div_fixup_f32 v72, v209, v208, v72
	v_div_scale_f32 v217, vcc, v73, v214, v73
	v_mul_f32_e32 v218, v217, v216
	v_fma_f32 v219, -v215, v218, v217
	v_fmac_f32_e32 v218, v219, v216
	v_fma_f32 v215, -v215, v218, v217
	v_div_fmas_f32 v215, v215, v216, v218
	v_div_fixup_f32 v73, v215, v214, v73
	v_div_scale_f32 v223, vcc, v74, v220, v74
	v_mul_f32_e32 v224, v223, v222
	v_fma_f32 v225, -v221, v224, v223
	v_fmac_f32_e32 v224, v225, v222
	v_fma_f32 v221, -v221, v224, v223
	v_div_fmas_f32 v221, v221, v222, v224
	v_div_fixup_f32 v74, v221, v220, v74
	v_div_scale_f32 v229, vcc, v75, v226, v75
	v_mul_f32_e32 v230, v229, v228
	v_fma_f32 v231, -v227, v230, v229
	v_fmac_f32_e32 v230, v231, v228
	v_fma_f32 v227, -v227, v230, v229
	v_div_fmas_f32 v227, v227, v228, v230
	v_div_fixup_f32 v75, v227, v226, v75
	v_mul_f32_e32 v50, v50, v72
	v_mul_f32_e32 v34, v34, v73
	v_mul_f32_e32 v18, v18, v74
	v_mul_f32_e32 v2, v2, v75
	v_mul_f32_e32 v150, v34, v34
	v_fmac_f32_e32 v150, v50, v50
	v_fmac_f32_e32 v150, v18, v18
	v_fmac_f32_e32 v150, v2, v2
	v_cvt_pk_bf16_f32 v72, v50, v177
	v_cvt_pk_bf16_f32 v73, v34, v177
	v_cvt_pk_bf16_f32 v74, v18, v177
	v_cvt_pk_bf16_f32 v75, v2, v177
	global_store_short v182, v72, s[14:15] offset:0
	global_store_short v182, v73, s[14:15] offset:64
	global_store_short v182, v74, s[14:15] offset:128
	global_store_short v182, v75, s[14:15] offset:192
	s_waitcnt vmcnt(60)
	v_add_u32_e32 v175, 0x3000, v169
	v_lshlrev_b32_e32 v76, 16, v76
	v_lshlrev_b32_e32 v77, 16, v77
	v_lshlrev_b32_e32 v78, 16, v78
	v_lshlrev_b32_e32 v79, 16, v79
	v_mul_f32_e32 v208, 0xbfb8aa3b, v76
	v_mul_f32_e32 v214, 0xbfb8aa3b, v77
	v_mul_f32_e32 v220, 0xbfb8aa3b, v78
	v_mul_f32_e32 v226, 0xbfb8aa3b, v79
	v_exp_f32_e32 v208, v208
	v_exp_f32_e32 v214, v214
	v_exp_f32_e32 v220, v220
	v_exp_f32_e32 v226, v226
	v_add_f32_e32 v208, 1.0, v208
	v_add_f32_e32 v214, 1.0, v214
	v_add_f32_e32 v220, 1.0, v220
	v_add_f32_e32 v226, 1.0, v226
	v_div_scale_f32 v209, s[12:13], v208, v208, v76
	v_div_scale_f32 v215, s[12:13], v214, v214, v77
	v_div_scale_f32 v221, s[12:13], v220, v220, v78
	v_div_scale_f32 v227, s[12:13], v226, v226, v79
	v_rcp_f32_e32 v210, v209
	v_rcp_f32_e32 v216, v215
	v_rcp_f32_e32 v222, v221
	v_rcp_f32_e32 v228, v227
	v_fma_f32 v211, -v209, v210, 1.0
	v_fma_f32 v217, -v215, v216, 1.0
	v_fma_f32 v223, -v221, v222, 1.0
	v_fma_f32 v229, -v227, v228, 1.0
	v_fmac_f32_e32 v210, v211, v210
	v_fmac_f32_e32 v216, v217, v216
	v_fmac_f32_e32 v222, v223, v222
	v_fmac_f32_e32 v228, v229, v228
	v_div_scale_f32 v211, vcc, v76, v208, v76
	v_mul_f32_e32 v212, v211, v210
	v_fma_f32 v213, -v209, v212, v211
	v_fmac_f32_e32 v212, v213, v210
	v_fma_f32 v209, -v209, v212, v211
	v_div_fmas_f32 v209, v209, v210, v212
	v_div_fixup_f32 v76, v209, v208, v76
	v_div_scale_f32 v217, vcc, v77, v214, v77
	v_mul_f32_e32 v218, v217, v216
	v_fma_f32 v219, -v215, v218, v217
	v_fmac_f32_e32 v218, v219, v216
	v_fma_f32 v215, -v215, v218, v217
	v_div_fmas_f32 v215, v215, v216, v218
	v_div_fixup_f32 v77, v215, v214, v77
	v_div_scale_f32 v223, vcc, v78, v220, v78
	v_mul_f32_e32 v224, v223, v222
	v_fma_f32 v225, -v221, v224, v223
	v_fmac_f32_e32 v224, v225, v222
	v_fma_f32 v221, -v221, v224, v223
	v_div_fmas_f32 v221, v221, v222, v224
	v_div_fixup_f32 v78, v221, v220, v78
	v_div_scale_f32 v229, vcc, v79, v226, v79
	v_mul_f32_e32 v230, v229, v228
	v_fma_f32 v231, -v227, v230, v229
	v_fmac_f32_e32 v230, v231, v228
	v_fma_f32 v227, -v227, v230, v229
	v_div_fmas_f32 v227, v227, v228, v230
	v_div_fixup_f32 v79, v227, v226, v79
	v_mul_f32_e32 v51, v51, v76
	v_mul_f32_e32 v35, v35, v77
	v_mul_f32_e32 v19, v19, v78
	v_mul_f32_e32 v3, v3, v79
	v_mul_f32_e32 v151, v35, v35
	v_fmac_f32_e32 v151, v51, v51
	v_fmac_f32_e32 v151, v19, v19
	v_fmac_f32_e32 v151, v3, v3
	v_cvt_pk_bf16_f32 v76, v51, v177
	v_cvt_pk_bf16_f32 v77, v35, v177
	v_cvt_pk_bf16_f32 v78, v19, v177
	v_cvt_pk_bf16_f32 v79, v3, v177
	global_store_short v175, v76, s[14:15] offset:0
	global_store_short v175, v77, s[14:15] offset:64
	global_store_short v175, v78, s[14:15] offset:128
	global_store_short v175, v79, s[14:15] offset:192
	s_waitcnt vmcnt(60)
	v_add_u32_e32 v182, 0x8000, v169
	v_lshlrev_b32_e32 v80, 16, v80
	v_lshlrev_b32_e32 v81, 16, v81
	v_lshlrev_b32_e32 v82, 16, v82
	v_lshlrev_b32_e32 v83, 16, v83
	v_mul_f32_e32 v208, 0xbfb8aa3b, v80
	v_mul_f32_e32 v214, 0xbfb8aa3b, v81
	v_mul_f32_e32 v220, 0xbfb8aa3b, v82
	v_mul_f32_e32 v226, 0xbfb8aa3b, v83
	v_exp_f32_e32 v208, v208
	v_exp_f32_e32 v214, v214
	v_exp_f32_e32 v220, v220
	v_exp_f32_e32 v226, v226
	v_add_f32_e32 v208, 1.0, v208
	v_add_f32_e32 v214, 1.0, v214
	v_add_f32_e32 v220, 1.0, v220
	v_add_f32_e32 v226, 1.0, v226
	v_div_scale_f32 v209, s[12:13], v208, v208, v80
	v_div_scale_f32 v215, s[12:13], v214, v214, v81
	v_div_scale_f32 v221, s[12:13], v220, v220, v82
	v_div_scale_f32 v227, s[12:13], v226, v226, v83
	v_rcp_f32_e32 v210, v209
	v_rcp_f32_e32 v216, v215
	v_rcp_f32_e32 v222, v221
	v_rcp_f32_e32 v228, v227
	v_fma_f32 v211, -v209, v210, 1.0
	v_fma_f32 v217, -v215, v216, 1.0
	v_fma_f32 v223, -v221, v222, 1.0
	v_fma_f32 v229, -v227, v228, 1.0
	v_fmac_f32_e32 v210, v211, v210
	v_fmac_f32_e32 v216, v217, v216
	v_fmac_f32_e32 v222, v223, v222
	v_fmac_f32_e32 v228, v229, v228
	v_div_scale_f32 v211, vcc, v80, v208, v80
	v_mul_f32_e32 v212, v211, v210
	v_fma_f32 v213, -v209, v212, v211
	v_fmac_f32_e32 v212, v213, v210
	v_fma_f32 v209, -v209, v212, v211
	v_div_fmas_f32 v209, v209, v210, v212
	v_div_fixup_f32 v80, v209, v208, v80
	v_div_scale_f32 v217, vcc, v81, v214, v81
	v_mul_f32_e32 v218, v217, v216
	v_fma_f32 v219, -v215, v218, v217
	v_fmac_f32_e32 v218, v219, v216
	v_fma_f32 v215, -v215, v218, v217
	v_div_fmas_f32 v215, v215, v216, v218
	v_div_fixup_f32 v81, v215, v214, v81
	v_div_scale_f32 v223, vcc, v82, v220, v82
	v_mul_f32_e32 v224, v223, v222
	v_fma_f32 v225, -v221, v224, v223
	v_fmac_f32_e32 v224, v225, v222
	v_fma_f32 v221, -v221, v224, v223
	v_div_fmas_f32 v221, v221, v222, v224
	v_div_fixup_f32 v82, v221, v220, v82
	v_div_scale_f32 v229, vcc, v83, v226, v83
	v_mul_f32_e32 v230, v229, v228
	v_fma_f32 v231, -v227, v230, v229
	v_fmac_f32_e32 v230, v231, v228
	v_fma_f32 v227, -v227, v230, v229
	v_div_fmas_f32 v227, v227, v228, v230
	v_div_fixup_f32 v83, v227, v226, v83
	v_mul_f32_e32 v52, v52, v80
	v_mul_f32_e32 v36, v36, v81
	v_mul_f32_e32 v20, v20, v82
	v_mul_f32_e32 v4, v4, v83
	v_mul_f32_e32 v152, v36, v36
	v_fmac_f32_e32 v152, v52, v52
	v_fmac_f32_e32 v152, v20, v20
	v_fmac_f32_e32 v152, v4, v4
	v_cvt_pk_bf16_f32 v80, v52, v177
	v_cvt_pk_bf16_f32 v81, v36, v177
	v_cvt_pk_bf16_f32 v82, v20, v177
	v_cvt_pk_bf16_f32 v83, v4, v177
	global_store_short v182, v80, s[14:15] offset:0
	global_store_short v182, v81, s[14:15] offset:64
	global_store_short v182, v82, s[14:15] offset:128
	global_store_short v182, v83, s[14:15] offset:192
	s_waitcnt vmcnt(60)
	v_add_u32_e32 v175, 0x9000, v169
	v_lshlrev_b32_e32 v84, 16, v84
	v_lshlrev_b32_e32 v85, 16, v85
	v_lshlrev_b32_e32 v86, 16, v86
	v_lshlrev_b32_e32 v87, 16, v87
	v_mul_f32_e32 v208, 0xbfb8aa3b, v84
	v_mul_f32_e32 v214, 0xbfb8aa3b, v85
	v_mul_f32_e32 v220, 0xbfb8aa3b, v86
	v_mul_f32_e32 v226, 0xbfb8aa3b, v87
	v_exp_f32_e32 v208, v208
	v_exp_f32_e32 v214, v214
	v_exp_f32_e32 v220, v220
	v_exp_f32_e32 v226, v226
	v_add_f32_e32 v208, 1.0, v208
	v_add_f32_e32 v214, 1.0, v214
	v_add_f32_e32 v220, 1.0, v220
	v_add_f32_e32 v226, 1.0, v226
	v_div_scale_f32 v209, s[12:13], v208, v208, v84
	v_div_scale_f32 v215, s[12:13], v214, v214, v85
	v_div_scale_f32 v221, s[12:13], v220, v220, v86
	v_div_scale_f32 v227, s[12:13], v226, v226, v87
	v_rcp_f32_e32 v210, v209
	v_rcp_f32_e32 v216, v215
	v_rcp_f32_e32 v222, v221
	v_rcp_f32_e32 v228, v227
	v_fma_f32 v211, -v209, v210, 1.0
	v_fma_f32 v217, -v215, v216, 1.0
	v_fma_f32 v223, -v221, v222, 1.0
	v_fma_f32 v229, -v227, v228, 1.0
	v_fmac_f32_e32 v210, v211, v210
	v_fmac_f32_e32 v216, v217, v216
	v_fmac_f32_e32 v222, v223, v222
	v_fmac_f32_e32 v228, v229, v228
	v_div_scale_f32 v211, vcc, v84, v208, v84
	v_mul_f32_e32 v212, v211, v210
	v_fma_f32 v213, -v209, v212, v211
	v_fmac_f32_e32 v212, v213, v210
	v_fma_f32 v209, -v209, v212, v211
	v_div_fmas_f32 v209, v209, v210, v212
	v_div_fixup_f32 v84, v209, v208, v84
	v_div_scale_f32 v217, vcc, v85, v214, v85
	v_mul_f32_e32 v218, v217, v216
	v_fma_f32 v219, -v215, v218, v217
	v_fmac_f32_e32 v218, v219, v216
	v_fma_f32 v215, -v215, v218, v217
	v_div_fmas_f32 v215, v215, v216, v218
	v_div_fixup_f32 v85, v215, v214, v85
	v_div_scale_f32 v223, vcc, v86, v220, v86
	v_mul_f32_e32 v224, v223, v222
	v_fma_f32 v225, -v221, v224, v223
	v_fmac_f32_e32 v224, v225, v222
	v_fma_f32 v221, -v221, v224, v223
	v_div_fmas_f32 v221, v221, v222, v224
	v_div_fixup_f32 v86, v221, v220, v86
	v_div_scale_f32 v229, vcc, v87, v226, v87
	v_mul_f32_e32 v230, v229, v228
	v_fma_f32 v231, -v227, v230, v229
	v_fmac_f32_e32 v230, v231, v228
	v_fma_f32 v227, -v227, v230, v229
	v_div_fmas_f32 v227, v227, v228, v230
	v_div_fixup_f32 v87, v227, v226, v87
	v_mul_f32_e32 v53, v53, v84
	v_mul_f32_e32 v37, v37, v85
	v_mul_f32_e32 v21, v21, v86
	v_mul_f32_e32 v5, v5, v87
	v_mul_f32_e32 v153, v37, v37
	v_fmac_f32_e32 v153, v53, v53
	v_fmac_f32_e32 v153, v21, v21
	v_fmac_f32_e32 v153, v5, v5
	v_cvt_pk_bf16_f32 v84, v53, v177
	v_cvt_pk_bf16_f32 v85, v37, v177
	v_cvt_pk_bf16_f32 v86, v21, v177
	v_cvt_pk_bf16_f32 v87, v5, v177
	global_store_short v175, v84, s[14:15] offset:0
	global_store_short v175, v85, s[14:15] offset:64
	global_store_short v175, v86, s[14:15] offset:128
	global_store_short v175, v87, s[14:15] offset:192
	s_waitcnt vmcnt(60)
	v_add_u32_e32 v182, 0xa000, v169
	v_lshlrev_b32_e32 v88, 16, v88
	v_lshlrev_b32_e32 v89, 16, v89
	v_lshlrev_b32_e32 v90, 16, v90
	v_lshlrev_b32_e32 v91, 16, v91
	v_mul_f32_e32 v208, 0xbfb8aa3b, v88
	v_mul_f32_e32 v214, 0xbfb8aa3b, v89
	v_mul_f32_e32 v220, 0xbfb8aa3b, v90
	v_mul_f32_e32 v226, 0xbfb8aa3b, v91
	v_exp_f32_e32 v208, v208
	v_exp_f32_e32 v214, v214
	v_exp_f32_e32 v220, v220
	v_exp_f32_e32 v226, v226
	v_add_f32_e32 v208, 1.0, v208
	v_add_f32_e32 v214, 1.0, v214
	v_add_f32_e32 v220, 1.0, v220
	v_add_f32_e32 v226, 1.0, v226
	v_div_scale_f32 v209, s[12:13], v208, v208, v88
	v_div_scale_f32 v215, s[12:13], v214, v214, v89
	v_div_scale_f32 v221, s[12:13], v220, v220, v90
	v_div_scale_f32 v227, s[12:13], v226, v226, v91
	v_rcp_f32_e32 v210, v209
	v_rcp_f32_e32 v216, v215
	v_rcp_f32_e32 v222, v221
	v_rcp_f32_e32 v228, v227
	v_fma_f32 v211, -v209, v210, 1.0
	v_fma_f32 v217, -v215, v216, 1.0
	v_fma_f32 v223, -v221, v222, 1.0
	v_fma_f32 v229, -v227, v228, 1.0
	v_fmac_f32_e32 v210, v211, v210
	v_fmac_f32_e32 v216, v217, v216
	v_fmac_f32_e32 v222, v223, v222
	v_fmac_f32_e32 v228, v229, v228
	v_div_scale_f32 v211, vcc, v88, v208, v88
	v_mul_f32_e32 v212, v211, v210
	v_fma_f32 v213, -v209, v212, v211
	v_fmac_f32_e32 v212, v213, v210
	v_fma_f32 v209, -v209, v212, v211
	v_div_fmas_f32 v209, v209, v210, v212
	v_div_fixup_f32 v88, v209, v208, v88
	v_div_scale_f32 v217, vcc, v89, v214, v89
	v_mul_f32_e32 v218, v217, v216
	v_fma_f32 v219, -v215, v218, v217
	v_fmac_f32_e32 v218, v219, v216
	v_fma_f32 v215, -v215, v218, v217
	v_div_fmas_f32 v215, v215, v216, v218
	v_div_fixup_f32 v89, v215, v214, v89
	v_div_scale_f32 v223, vcc, v90, v220, v90
	v_mul_f32_e32 v224, v223, v222
	v_fma_f32 v225, -v221, v224, v223
	v_fmac_f32_e32 v224, v225, v222
	v_fma_f32 v221, -v221, v224, v223
	v_div_fmas_f32 v221, v221, v222, v224
	v_div_fixup_f32 v90, v221, v220, v90
	v_div_scale_f32 v229, vcc, v91, v226, v91
	v_mul_f32_e32 v230, v229, v228
	v_fma_f32 v231, -v227, v230, v229
	v_fmac_f32_e32 v230, v231, v228
	v_fma_f32 v227, -v227, v230, v229
	v_div_fmas_f32 v227, v227, v228, v230
	v_div_fixup_f32 v91, v227, v226, v91
	v_mul_f32_e32 v54, v54, v88
	v_mul_f32_e32 v38, v38, v89
	v_mul_f32_e32 v22, v22, v90
	v_mul_f32_e32 v6, v6, v91
	v_mul_f32_e32 v154, v38, v38
	v_fmac_f32_e32 v154, v54, v54
	v_fmac_f32_e32 v154, v22, v22
	v_fmac_f32_e32 v154, v6, v6
	v_cvt_pk_bf16_f32 v88, v54, v177
	v_cvt_pk_bf16_f32 v89, v38, v177
	v_cvt_pk_bf16_f32 v90, v22, v177
	v_cvt_pk_bf16_f32 v91, v6, v177
	global_store_short v182, v88, s[14:15] offset:0
	global_store_short v182, v89, s[14:15] offset:64
	global_store_short v182, v90, s[14:15] offset:128
	global_store_short v182, v91, s[14:15] offset:192
	s_waitcnt vmcnt(60)
	v_add_u32_e32 v175, 0xb000, v169
	v_lshlrev_b32_e32 v92, 16, v92
	v_lshlrev_b32_e32 v93, 16, v93
	v_lshlrev_b32_e32 v94, 16, v94
	v_lshlrev_b32_e32 v95, 16, v95
	v_mul_f32_e32 v208, 0xbfb8aa3b, v92
	v_mul_f32_e32 v214, 0xbfb8aa3b, v93
	v_mul_f32_e32 v220, 0xbfb8aa3b, v94
	v_mul_f32_e32 v226, 0xbfb8aa3b, v95
	v_exp_f32_e32 v208, v208
	v_exp_f32_e32 v214, v214
	v_exp_f32_e32 v220, v220
	v_exp_f32_e32 v226, v226
	v_add_f32_e32 v208, 1.0, v208
	v_add_f32_e32 v214, 1.0, v214
	v_add_f32_e32 v220, 1.0, v220
	v_add_f32_e32 v226, 1.0, v226
	v_div_scale_f32 v209, s[12:13], v208, v208, v92
	v_div_scale_f32 v215, s[12:13], v214, v214, v93
	v_div_scale_f32 v221, s[12:13], v220, v220, v94
	v_div_scale_f32 v227, s[12:13], v226, v226, v95
	v_rcp_f32_e32 v210, v209
	v_rcp_f32_e32 v216, v215
	v_rcp_f32_e32 v222, v221
	v_rcp_f32_e32 v228, v227
	v_fma_f32 v211, -v209, v210, 1.0
	v_fma_f32 v217, -v215, v216, 1.0
	v_fma_f32 v223, -v221, v222, 1.0
	v_fma_f32 v229, -v227, v228, 1.0
	v_fmac_f32_e32 v210, v211, v210
	v_fmac_f32_e32 v216, v217, v216
	v_fmac_f32_e32 v222, v223, v222
	v_fmac_f32_e32 v228, v229, v228
	v_div_scale_f32 v211, vcc, v92, v208, v92
	v_mul_f32_e32 v212, v211, v210
	v_fma_f32 v213, -v209, v212, v211
	v_fmac_f32_e32 v212, v213, v210
	v_fma_f32 v209, -v209, v212, v211
	v_div_fmas_f32 v209, v209, v210, v212
	v_div_fixup_f32 v92, v209, v208, v92
	v_div_scale_f32 v217, vcc, v93, v214, v93
	v_mul_f32_e32 v218, v217, v216
	v_fma_f32 v219, -v215, v218, v217
	v_fmac_f32_e32 v218, v219, v216
	v_fma_f32 v215, -v215, v218, v217
	v_div_fmas_f32 v215, v215, v216, v218
	v_div_fixup_f32 v93, v215, v214, v93
	v_div_scale_f32 v223, vcc, v94, v220, v94
	v_mul_f32_e32 v224, v223, v222
	v_fma_f32 v225, -v221, v224, v223
	v_fmac_f32_e32 v224, v225, v222
	v_fma_f32 v221, -v221, v224, v223
	v_div_fmas_f32 v221, v221, v222, v224
	v_div_fixup_f32 v94, v221, v220, v94
	v_div_scale_f32 v229, vcc, v95, v226, v95
	v_mul_f32_e32 v230, v229, v228
	v_fma_f32 v231, -v227, v230, v229
	v_fmac_f32_e32 v230, v231, v228
	v_fma_f32 v227, -v227, v230, v229
	v_div_fmas_f32 v227, v227, v228, v230
	v_div_fixup_f32 v95, v227, v226, v95
	v_mul_f32_e32 v55, v55, v92
	v_mul_f32_e32 v39, v39, v93
	v_mul_f32_e32 v23, v23, v94
	v_mul_f32_e32 v7, v7, v95
	v_mul_f32_e32 v155, v39, v39
	v_fmac_f32_e32 v155, v55, v55
	v_fmac_f32_e32 v155, v23, v23
	v_fmac_f32_e32 v155, v7, v7
	v_cvt_pk_bf16_f32 v92, v55, v177
	v_cvt_pk_bf16_f32 v93, v39, v177
	v_cvt_pk_bf16_f32 v94, v23, v177
	v_cvt_pk_bf16_f32 v95, v7, v177
	global_store_short v175, v92, s[14:15] offset:0
	global_store_short v175, v93, s[14:15] offset:64
	global_store_short v175, v94, s[14:15] offset:128
	global_store_short v175, v95, s[14:15] offset:192
	s_waitcnt vmcnt(60)
	v_add_u32_e32 v182, 0x10000, v169
	v_lshlrev_b32_e32 v96, 16, v96
	v_lshlrev_b32_e32 v97, 16, v97
	v_lshlrev_b32_e32 v98, 16, v98
	v_lshlrev_b32_e32 v99, 16, v99
	v_mul_f32_e32 v208, 0xbfb8aa3b, v96
	v_mul_f32_e32 v214, 0xbfb8aa3b, v97
	v_mul_f32_e32 v220, 0xbfb8aa3b, v98
	v_mul_f32_e32 v226, 0xbfb8aa3b, v99
	v_exp_f32_e32 v208, v208
	v_exp_f32_e32 v214, v214
	v_exp_f32_e32 v220, v220
	v_exp_f32_e32 v226, v226
	v_add_f32_e32 v208, 1.0, v208
	v_add_f32_e32 v214, 1.0, v214
	v_add_f32_e32 v220, 1.0, v220
	v_add_f32_e32 v226, 1.0, v226
	v_div_scale_f32 v209, s[12:13], v208, v208, v96
	v_div_scale_f32 v215, s[12:13], v214, v214, v97
	v_div_scale_f32 v221, s[12:13], v220, v220, v98
	v_div_scale_f32 v227, s[12:13], v226, v226, v99
	v_rcp_f32_e32 v210, v209
	v_rcp_f32_e32 v216, v215
	v_rcp_f32_e32 v222, v221
	v_rcp_f32_e32 v228, v227
	v_fma_f32 v211, -v209, v210, 1.0
	v_fma_f32 v217, -v215, v216, 1.0
	v_fma_f32 v223, -v221, v222, 1.0
	v_fma_f32 v229, -v227, v228, 1.0
	v_fmac_f32_e32 v210, v211, v210
	v_fmac_f32_e32 v216, v217, v216
	v_fmac_f32_e32 v222, v223, v222
	v_fmac_f32_e32 v228, v229, v228
	v_div_scale_f32 v211, vcc, v96, v208, v96
	v_mul_f32_e32 v212, v211, v210
	v_fma_f32 v213, -v209, v212, v211
	v_fmac_f32_e32 v212, v213, v210
	v_fma_f32 v209, -v209, v212, v211
	v_div_fmas_f32 v209, v209, v210, v212
	v_div_fixup_f32 v96, v209, v208, v96
	v_div_scale_f32 v217, vcc, v97, v214, v97
	v_mul_f32_e32 v218, v217, v216
	v_fma_f32 v219, -v215, v218, v217
	v_fmac_f32_e32 v218, v219, v216
	v_fma_f32 v215, -v215, v218, v217
	v_div_fmas_f32 v215, v215, v216, v218
	v_div_fixup_f32 v97, v215, v214, v97
	v_div_scale_f32 v223, vcc, v98, v220, v98
	v_mul_f32_e32 v224, v223, v222
	v_fma_f32 v225, -v221, v224, v223
	v_fmac_f32_e32 v224, v225, v222
	v_fma_f32 v221, -v221, v224, v223
	v_div_fmas_f32 v221, v221, v222, v224
	v_div_fixup_f32 v98, v221, v220, v98
	v_div_scale_f32 v229, vcc, v99, v226, v99
	v_mul_f32_e32 v230, v229, v228
	v_fma_f32 v231, -v227, v230, v229
	v_fmac_f32_e32 v230, v231, v228
	v_fma_f32 v227, -v227, v230, v229
	v_div_fmas_f32 v227, v227, v228, v230
	v_div_fixup_f32 v99, v227, v226, v99
	v_mul_f32_e32 v56, v56, v96
	v_mul_f32_e32 v40, v40, v97
	v_mul_f32_e32 v24, v24, v98
	v_mul_f32_e32 v8, v8, v99
	v_mul_f32_e32 v156, v40, v40
	v_fmac_f32_e32 v156, v56, v56
	v_fmac_f32_e32 v156, v24, v24
	v_fmac_f32_e32 v156, v8, v8
	v_cvt_pk_bf16_f32 v96, v56, v177
	v_cvt_pk_bf16_f32 v97, v40, v177
	v_cvt_pk_bf16_f32 v98, v24, v177
	v_cvt_pk_bf16_f32 v99, v8, v177
	global_store_short v182, v96, s[14:15] offset:0
	global_store_short v182, v97, s[14:15] offset:64
	global_store_short v182, v98, s[14:15] offset:128
	global_store_short v182, v99, s[14:15] offset:192
	s_waitcnt vmcnt(60)
	v_add_u32_e32 v175, 0x11000, v169
	v_lshlrev_b32_e32 v100, 16, v100
	v_lshlrev_b32_e32 v101, 16, v101
	v_lshlrev_b32_e32 v102, 16, v102
	v_lshlrev_b32_e32 v103, 16, v103
	v_mul_f32_e32 v208, 0xbfb8aa3b, v100
	v_mul_f32_e32 v214, 0xbfb8aa3b, v101
	v_mul_f32_e32 v220, 0xbfb8aa3b, v102
	v_mul_f32_e32 v226, 0xbfb8aa3b, v103
	v_exp_f32_e32 v208, v208
	v_exp_f32_e32 v214, v214
	v_exp_f32_e32 v220, v220
	v_exp_f32_e32 v226, v226
	v_add_f32_e32 v208, 1.0, v208
	v_add_f32_e32 v214, 1.0, v214
	v_add_f32_e32 v220, 1.0, v220
	v_add_f32_e32 v226, 1.0, v226
	v_div_scale_f32 v209, s[12:13], v208, v208, v100
	v_div_scale_f32 v215, s[12:13], v214, v214, v101
	v_div_scale_f32 v221, s[12:13], v220, v220, v102
	v_div_scale_f32 v227, s[12:13], v226, v226, v103
	v_rcp_f32_e32 v210, v209
	v_rcp_f32_e32 v216, v215
	v_rcp_f32_e32 v222, v221
	v_rcp_f32_e32 v228, v227
	v_fma_f32 v211, -v209, v210, 1.0
	v_fma_f32 v217, -v215, v216, 1.0
	v_fma_f32 v223, -v221, v222, 1.0
	v_fma_f32 v229, -v227, v228, 1.0
	v_fmac_f32_e32 v210, v211, v210
	v_fmac_f32_e32 v216, v217, v216
	v_fmac_f32_e32 v222, v223, v222
	v_fmac_f32_e32 v228, v229, v228
	v_div_scale_f32 v211, vcc, v100, v208, v100
	v_mul_f32_e32 v212, v211, v210
	v_fma_f32 v213, -v209, v212, v211
	v_fmac_f32_e32 v212, v213, v210
	v_fma_f32 v209, -v209, v212, v211
	v_div_fmas_f32 v209, v209, v210, v212
	v_div_fixup_f32 v100, v209, v208, v100
	v_div_scale_f32 v217, vcc, v101, v214, v101
	v_mul_f32_e32 v218, v217, v216
	v_fma_f32 v219, -v215, v218, v217
	v_fmac_f32_e32 v218, v219, v216
	v_fma_f32 v215, -v215, v218, v217
	v_div_fmas_f32 v215, v215, v216, v218
	v_div_fixup_f32 v101, v215, v214, v101
	v_div_scale_f32 v223, vcc, v102, v220, v102
	v_mul_f32_e32 v224, v223, v222
	v_fma_f32 v225, -v221, v224, v223
	v_fmac_f32_e32 v224, v225, v222
	v_fma_f32 v221, -v221, v224, v223
	v_div_fmas_f32 v221, v221, v222, v224
	v_div_fixup_f32 v102, v221, v220, v102
	v_div_scale_f32 v229, vcc, v103, v226, v103
	v_mul_f32_e32 v230, v229, v228
	v_fma_f32 v231, -v227, v230, v229
	v_fmac_f32_e32 v230, v231, v228
	v_fma_f32 v227, -v227, v230, v229
	v_div_fmas_f32 v227, v227, v228, v230
	v_div_fixup_f32 v103, v227, v226, v103
	v_mul_f32_e32 v57, v57, v100
	v_mul_f32_e32 v41, v41, v101
	v_mul_f32_e32 v25, v25, v102
	v_mul_f32_e32 v9, v9, v103
	v_mul_f32_e32 v157, v41, v41
	v_fmac_f32_e32 v157, v57, v57
	v_fmac_f32_e32 v157, v25, v25
	v_fmac_f32_e32 v157, v9, v9
	v_cvt_pk_bf16_f32 v100, v57, v177
	v_cvt_pk_bf16_f32 v101, v41, v177
	v_cvt_pk_bf16_f32 v102, v25, v177
	v_cvt_pk_bf16_f32 v103, v9, v177
	global_store_short v175, v100, s[14:15] offset:0
	global_store_short v175, v101, s[14:15] offset:64
	global_store_short v175, v102, s[14:15] offset:128
	global_store_short v175, v103, s[14:15] offset:192
	s_waitcnt vmcnt(60)
	v_add_u32_e32 v182, 0x12000, v169
	v_lshlrev_b32_e32 v104, 16, v104
	v_lshlrev_b32_e32 v105, 16, v105
	v_lshlrev_b32_e32 v106, 16, v106
	v_lshlrev_b32_e32 v107, 16, v107
	v_mul_f32_e32 v208, 0xbfb8aa3b, v104
	v_mul_f32_e32 v214, 0xbfb8aa3b, v105
	v_mul_f32_e32 v220, 0xbfb8aa3b, v106
	v_mul_f32_e32 v226, 0xbfb8aa3b, v107
	v_exp_f32_e32 v208, v208
	v_exp_f32_e32 v214, v214
	v_exp_f32_e32 v220, v220
	v_exp_f32_e32 v226, v226
	v_add_f32_e32 v208, 1.0, v208
	v_add_f32_e32 v214, 1.0, v214
	v_add_f32_e32 v220, 1.0, v220
	v_add_f32_e32 v226, 1.0, v226
	v_div_scale_f32 v209, s[12:13], v208, v208, v104
	v_div_scale_f32 v215, s[12:13], v214, v214, v105
	v_div_scale_f32 v221, s[12:13], v220, v220, v106
	v_div_scale_f32 v227, s[12:13], v226, v226, v107
	v_rcp_f32_e32 v210, v209
	v_rcp_f32_e32 v216, v215
	v_rcp_f32_e32 v222, v221
	v_rcp_f32_e32 v228, v227
	v_fma_f32 v211, -v209, v210, 1.0
	v_fma_f32 v217, -v215, v216, 1.0
	v_fma_f32 v223, -v221, v222, 1.0
	v_fma_f32 v229, -v227, v228, 1.0
	v_fmac_f32_e32 v210, v211, v210
	v_fmac_f32_e32 v216, v217, v216
	v_fmac_f32_e32 v222, v223, v222
	v_fmac_f32_e32 v228, v229, v228
	v_div_scale_f32 v211, vcc, v104, v208, v104
	v_mul_f32_e32 v212, v211, v210
	v_fma_f32 v213, -v209, v212, v211
	v_fmac_f32_e32 v212, v213, v210
	v_fma_f32 v209, -v209, v212, v211
	v_div_fmas_f32 v209, v209, v210, v212
	v_div_fixup_f32 v104, v209, v208, v104
	v_div_scale_f32 v217, vcc, v105, v214, v105
	v_mul_f32_e32 v218, v217, v216
	v_fma_f32 v219, -v215, v218, v217
	v_fmac_f32_e32 v218, v219, v216
	v_fma_f32 v215, -v215, v218, v217
	v_div_fmas_f32 v215, v215, v216, v218
	v_div_fixup_f32 v105, v215, v214, v105
	v_div_scale_f32 v223, vcc, v106, v220, v106
	v_mul_f32_e32 v224, v223, v222
	v_fma_f32 v225, -v221, v224, v223
	v_fmac_f32_e32 v224, v225, v222
	v_fma_f32 v221, -v221, v224, v223
	v_div_fmas_f32 v221, v221, v222, v224
	v_div_fixup_f32 v106, v221, v220, v106
	v_div_scale_f32 v229, vcc, v107, v226, v107
	v_mul_f32_e32 v230, v229, v228
	v_fma_f32 v231, -v227, v230, v229
	v_fmac_f32_e32 v230, v231, v228
	v_fma_f32 v227, -v227, v230, v229
	v_div_fmas_f32 v227, v227, v228, v230
	v_div_fixup_f32 v107, v227, v226, v107
	v_mul_f32_e32 v58, v58, v104
	v_mul_f32_e32 v42, v42, v105
	v_mul_f32_e32 v26, v26, v106
	v_mul_f32_e32 v10, v10, v107
	v_mul_f32_e32 v158, v42, v42
	v_fmac_f32_e32 v158, v58, v58
	v_fmac_f32_e32 v158, v26, v26
	v_fmac_f32_e32 v158, v10, v10
	v_cvt_pk_bf16_f32 v104, v58, v177
	v_cvt_pk_bf16_f32 v105, v42, v177
	v_cvt_pk_bf16_f32 v106, v26, v177
	v_cvt_pk_bf16_f32 v107, v10, v177
	global_store_short v182, v104, s[14:15] offset:0
	global_store_short v182, v105, s[14:15] offset:64
	global_store_short v182, v106, s[14:15] offset:128
	global_store_short v182, v107, s[14:15] offset:192
	s_waitcnt vmcnt(60)
	v_add_u32_e32 v175, 0x13000, v169
	v_lshlrev_b32_e32 v108, 16, v108
	v_lshlrev_b32_e32 v109, 16, v109
	v_lshlrev_b32_e32 v110, 16, v110
	v_lshlrev_b32_e32 v111, 16, v111
	v_mul_f32_e32 v208, 0xbfb8aa3b, v108
	v_mul_f32_e32 v214, 0xbfb8aa3b, v109
	v_mul_f32_e32 v220, 0xbfb8aa3b, v110
	v_mul_f32_e32 v226, 0xbfb8aa3b, v111
	v_exp_f32_e32 v208, v208
	v_exp_f32_e32 v214, v214
	v_exp_f32_e32 v220, v220
	v_exp_f32_e32 v226, v226
	v_add_f32_e32 v208, 1.0, v208
	v_add_f32_e32 v214, 1.0, v214
	v_add_f32_e32 v220, 1.0, v220
	v_add_f32_e32 v226, 1.0, v226
	v_div_scale_f32 v209, s[12:13], v208, v208, v108
	v_div_scale_f32 v215, s[12:13], v214, v214, v109
	v_div_scale_f32 v221, s[12:13], v220, v220, v110
	v_div_scale_f32 v227, s[12:13], v226, v226, v111
	v_rcp_f32_e32 v210, v209
	v_rcp_f32_e32 v216, v215
	v_rcp_f32_e32 v222, v221
	v_rcp_f32_e32 v228, v227
	v_fma_f32 v211, -v209, v210, 1.0
	v_fma_f32 v217, -v215, v216, 1.0
	v_fma_f32 v223, -v221, v222, 1.0
	v_fma_f32 v229, -v227, v228, 1.0
	v_fmac_f32_e32 v210, v211, v210
	v_fmac_f32_e32 v216, v217, v216
	v_fmac_f32_e32 v222, v223, v222
	v_fmac_f32_e32 v228, v229, v228
	v_div_scale_f32 v211, vcc, v108, v208, v108
	v_mul_f32_e32 v212, v211, v210
	v_fma_f32 v213, -v209, v212, v211
	v_fmac_f32_e32 v212, v213, v210
	v_fma_f32 v209, -v209, v212, v211
	v_div_fmas_f32 v209, v209, v210, v212
	v_div_fixup_f32 v108, v209, v208, v108
	v_div_scale_f32 v217, vcc, v109, v214, v109
	v_mul_f32_e32 v218, v217, v216
	v_fma_f32 v219, -v215, v218, v217
	v_fmac_f32_e32 v218, v219, v216
	v_fma_f32 v215, -v215, v218, v217
	v_div_fmas_f32 v215, v215, v216, v218
	v_div_fixup_f32 v109, v215, v214, v109
	v_div_scale_f32 v223, vcc, v110, v220, v110
	v_mul_f32_e32 v224, v223, v222
	v_fma_f32 v225, -v221, v224, v223
	v_fmac_f32_e32 v224, v225, v222
	v_fma_f32 v221, -v221, v224, v223
	v_div_fmas_f32 v221, v221, v222, v224
	v_div_fixup_f32 v110, v221, v220, v110
	v_div_scale_f32 v229, vcc, v111, v226, v111
	v_mul_f32_e32 v230, v229, v228
	v_fma_f32 v231, -v227, v230, v229
	v_fmac_f32_e32 v230, v231, v228
	v_fma_f32 v227, -v227, v230, v229
	v_div_fmas_f32 v227, v227, v228, v230
	v_div_fixup_f32 v111, v227, v226, v111
	v_mul_f32_e32 v59, v59, v108
	v_mul_f32_e32 v43, v43, v109
	v_mul_f32_e32 v27, v27, v110
	v_mul_f32_e32 v11, v11, v111
	v_mul_f32_e32 v159, v43, v43
	v_fmac_f32_e32 v159, v59, v59
	v_fmac_f32_e32 v159, v27, v27
	v_fmac_f32_e32 v159, v11, v11
	v_cvt_pk_bf16_f32 v108, v59, v177
	v_cvt_pk_bf16_f32 v109, v43, v177
	v_cvt_pk_bf16_f32 v110, v27, v177
	v_cvt_pk_bf16_f32 v111, v11, v177
	global_store_short v175, v108, s[14:15] offset:0
	global_store_short v175, v109, s[14:15] offset:64
	global_store_short v175, v110, s[14:15] offset:128
	global_store_short v175, v111, s[14:15] offset:192
	s_waitcnt vmcnt(60)
	v_add_u32_e32 v182, 0x18000, v169
	v_lshlrev_b32_e32 v112, 16, v112
	v_lshlrev_b32_e32 v113, 16, v113
	v_lshlrev_b32_e32 v114, 16, v114
	v_lshlrev_b32_e32 v115, 16, v115
	v_mul_f32_e32 v208, 0xbfb8aa3b, v112
	v_mul_f32_e32 v214, 0xbfb8aa3b, v113
	v_mul_f32_e32 v220, 0xbfb8aa3b, v114
	v_mul_f32_e32 v226, 0xbfb8aa3b, v115
	v_exp_f32_e32 v208, v208
	v_exp_f32_e32 v214, v214
	v_exp_f32_e32 v220, v220
	v_exp_f32_e32 v226, v226
	v_add_f32_e32 v208, 1.0, v208
	v_add_f32_e32 v214, 1.0, v214
	v_add_f32_e32 v220, 1.0, v220
	v_add_f32_e32 v226, 1.0, v226
	v_div_scale_f32 v209, s[12:13], v208, v208, v112
	v_div_scale_f32 v215, s[12:13], v214, v214, v113
	v_div_scale_f32 v221, s[12:13], v220, v220, v114
	v_div_scale_f32 v227, s[12:13], v226, v226, v115
	v_rcp_f32_e32 v210, v209
	v_rcp_f32_e32 v216, v215
	v_rcp_f32_e32 v222, v221
	v_rcp_f32_e32 v228, v227
	v_fma_f32 v211, -v209, v210, 1.0
	v_fma_f32 v217, -v215, v216, 1.0
	v_fma_f32 v223, -v221, v222, 1.0
	v_fma_f32 v229, -v227, v228, 1.0
	v_fmac_f32_e32 v210, v211, v210
	v_fmac_f32_e32 v216, v217, v216
	v_fmac_f32_e32 v222, v223, v222
	v_fmac_f32_e32 v228, v229, v228
	v_div_scale_f32 v211, vcc, v112, v208, v112
	v_mul_f32_e32 v212, v211, v210
	v_fma_f32 v213, -v209, v212, v211
	v_fmac_f32_e32 v212, v213, v210
	v_fma_f32 v209, -v209, v212, v211
	v_div_fmas_f32 v209, v209, v210, v212
	v_div_fixup_f32 v112, v209, v208, v112
	v_div_scale_f32 v217, vcc, v113, v214, v113
	v_mul_f32_e32 v218, v217, v216
	v_fma_f32 v219, -v215, v218, v217
	v_fmac_f32_e32 v218, v219, v216
	v_fma_f32 v215, -v215, v218, v217
	v_div_fmas_f32 v215, v215, v216, v218
	v_div_fixup_f32 v113, v215, v214, v113
	v_div_scale_f32 v223, vcc, v114, v220, v114
	v_mul_f32_e32 v224, v223, v222
	v_fma_f32 v225, -v221, v224, v223
	v_fmac_f32_e32 v224, v225, v222
	v_fma_f32 v221, -v221, v224, v223
	v_div_fmas_f32 v221, v221, v222, v224
	v_div_fixup_f32 v114, v221, v220, v114
	v_div_scale_f32 v229, vcc, v115, v226, v115
	v_mul_f32_e32 v230, v229, v228
	v_fma_f32 v231, -v227, v230, v229
	v_fmac_f32_e32 v230, v231, v228
	v_fma_f32 v227, -v227, v230, v229
	v_div_fmas_f32 v227, v227, v228, v230
	v_div_fixup_f32 v115, v227, v226, v115
	v_mul_f32_e32 v60, v60, v112
	v_mul_f32_e32 v44, v44, v113
	v_mul_f32_e32 v28, v28, v114
	v_mul_f32_e32 v12, v12, v115
	v_mul_f32_e32 v160, v44, v44
	v_fmac_f32_e32 v160, v60, v60
	v_fmac_f32_e32 v160, v28, v28
	v_fmac_f32_e32 v160, v12, v12
	v_cvt_pk_bf16_f32 v112, v60, v177
	v_cvt_pk_bf16_f32 v113, v44, v177
	v_cvt_pk_bf16_f32 v114, v28, v177
	v_cvt_pk_bf16_f32 v115, v12, v177
	global_store_short v182, v112, s[14:15] offset:0
	global_store_short v182, v113, s[14:15] offset:64
	global_store_short v182, v114, s[14:15] offset:128
	global_store_short v182, v115, s[14:15] offset:192
	s_waitcnt vmcnt(60)
	v_add_u32_e32 v175, 0x19000, v169
	v_lshlrev_b32_e32 v116, 16, v116
	v_lshlrev_b32_e32 v117, 16, v117
	v_lshlrev_b32_e32 v118, 16, v118
	v_lshlrev_b32_e32 v119, 16, v119
	v_mul_f32_e32 v208, 0xbfb8aa3b, v116
	v_mul_f32_e32 v214, 0xbfb8aa3b, v117
	v_mul_f32_e32 v220, 0xbfb8aa3b, v118
	v_mul_f32_e32 v226, 0xbfb8aa3b, v119
	v_exp_f32_e32 v208, v208
	v_exp_f32_e32 v214, v214
	v_exp_f32_e32 v220, v220
	v_exp_f32_e32 v226, v226
	v_add_f32_e32 v208, 1.0, v208
	v_add_f32_e32 v214, 1.0, v214
	v_add_f32_e32 v220, 1.0, v220
	v_add_f32_e32 v226, 1.0, v226
	v_div_scale_f32 v209, s[12:13], v208, v208, v116
	v_div_scale_f32 v215, s[12:13], v214, v214, v117
	v_div_scale_f32 v221, s[12:13], v220, v220, v118
	v_div_scale_f32 v227, s[12:13], v226, v226, v119
	v_rcp_f32_e32 v210, v209
	v_rcp_f32_e32 v216, v215
	v_rcp_f32_e32 v222, v221
	v_rcp_f32_e32 v228, v227
	v_fma_f32 v211, -v209, v210, 1.0
	v_fma_f32 v217, -v215, v216, 1.0
	v_fma_f32 v223, -v221, v222, 1.0
	v_fma_f32 v229, -v227, v228, 1.0
	v_fmac_f32_e32 v210, v211, v210
	v_fmac_f32_e32 v216, v217, v216
	v_fmac_f32_e32 v222, v223, v222
	v_fmac_f32_e32 v228, v229, v228
	v_div_scale_f32 v211, vcc, v116, v208, v116
	v_mul_f32_e32 v212, v211, v210
	v_fma_f32 v213, -v209, v212, v211
	v_fmac_f32_e32 v212, v213, v210
	v_fma_f32 v209, -v209, v212, v211
	v_div_fmas_f32 v209, v209, v210, v212
	v_div_fixup_f32 v116, v209, v208, v116
	v_div_scale_f32 v217, vcc, v117, v214, v117
	v_mul_f32_e32 v218, v217, v216
	v_fma_f32 v219, -v215, v218, v217
	v_fmac_f32_e32 v218, v219, v216
	v_fma_f32 v215, -v215, v218, v217
	v_div_fmas_f32 v215, v215, v216, v218
	v_div_fixup_f32 v117, v215, v214, v117
	v_div_scale_f32 v223, vcc, v118, v220, v118
	v_mul_f32_e32 v224, v223, v222
	v_fma_f32 v225, -v221, v224, v223
	v_fmac_f32_e32 v224, v225, v222
	v_fma_f32 v221, -v221, v224, v223
	v_div_fmas_f32 v221, v221, v222, v224
	v_div_fixup_f32 v118, v221, v220, v118
	v_div_scale_f32 v229, vcc, v119, v226, v119
	v_mul_f32_e32 v230, v229, v228
	v_fma_f32 v231, -v227, v230, v229
	v_fmac_f32_e32 v230, v231, v228
	v_fma_f32 v227, -v227, v230, v229
	v_div_fmas_f32 v227, v227, v228, v230
	v_div_fixup_f32 v119, v227, v226, v119
	v_mul_f32_e32 v61, v61, v116
	v_mul_f32_e32 v45, v45, v117
	v_mul_f32_e32 v29, v29, v118
	v_mul_f32_e32 v13, v13, v119
	v_mul_f32_e32 v161, v45, v45
	v_fmac_f32_e32 v161, v61, v61
	v_fmac_f32_e32 v161, v29, v29
	v_fmac_f32_e32 v161, v13, v13
	v_cvt_pk_bf16_f32 v116, v61, v177
	v_cvt_pk_bf16_f32 v117, v45, v177
	v_cvt_pk_bf16_f32 v118, v29, v177
	v_cvt_pk_bf16_f32 v119, v13, v177
	global_store_short v175, v116, s[14:15] offset:0
	global_store_short v175, v117, s[14:15] offset:64
	global_store_short v175, v118, s[14:15] offset:128
	global_store_short v175, v119, s[14:15] offset:192
	s_waitcnt vmcnt(60)
	v_add_u32_e32 v182, 0x1a000, v169
	v_lshlrev_b32_e32 v120, 16, v120
	v_lshlrev_b32_e32 v121, 16, v121
	v_lshlrev_b32_e32 v122, 16, v122
	v_lshlrev_b32_e32 v123, 16, v123
	v_mul_f32_e32 v208, 0xbfb8aa3b, v120
	v_mul_f32_e32 v214, 0xbfb8aa3b, v121
	v_mul_f32_e32 v220, 0xbfb8aa3b, v122
	v_mul_f32_e32 v226, 0xbfb8aa3b, v123
	v_exp_f32_e32 v208, v208
	v_exp_f32_e32 v214, v214
	v_exp_f32_e32 v220, v220
	v_exp_f32_e32 v226, v226
	v_add_f32_e32 v208, 1.0, v208
	v_add_f32_e32 v214, 1.0, v214
	v_add_f32_e32 v220, 1.0, v220
	v_add_f32_e32 v226, 1.0, v226
	v_div_scale_f32 v209, s[12:13], v208, v208, v120
	v_div_scale_f32 v215, s[12:13], v214, v214, v121
	v_div_scale_f32 v221, s[12:13], v220, v220, v122
	v_div_scale_f32 v227, s[12:13], v226, v226, v123
	v_rcp_f32_e32 v210, v209
	v_rcp_f32_e32 v216, v215
	v_rcp_f32_e32 v222, v221
	v_rcp_f32_e32 v228, v227
	v_fma_f32 v211, -v209, v210, 1.0
	v_fma_f32 v217, -v215, v216, 1.0
	v_fma_f32 v223, -v221, v222, 1.0
	v_fma_f32 v229, -v227, v228, 1.0
	v_fmac_f32_e32 v210, v211, v210
	v_fmac_f32_e32 v216, v217, v216
	v_fmac_f32_e32 v222, v223, v222
	v_fmac_f32_e32 v228, v229, v228
	v_div_scale_f32 v211, vcc, v120, v208, v120
	v_mul_f32_e32 v212, v211, v210
	v_fma_f32 v213, -v209, v212, v211
	v_fmac_f32_e32 v212, v213, v210
	v_fma_f32 v209, -v209, v212, v211
	v_div_fmas_f32 v209, v209, v210, v212
	v_div_fixup_f32 v120, v209, v208, v120
	v_div_scale_f32 v217, vcc, v121, v214, v121
	v_mul_f32_e32 v218, v217, v216
	v_fma_f32 v219, -v215, v218, v217
	v_fmac_f32_e32 v218, v219, v216
	v_fma_f32 v215, -v215, v218, v217
	v_div_fmas_f32 v215, v215, v216, v218
	v_div_fixup_f32 v121, v215, v214, v121
	v_div_scale_f32 v223, vcc, v122, v220, v122
	v_mul_f32_e32 v224, v223, v222
	v_fma_f32 v225, -v221, v224, v223
	v_fmac_f32_e32 v224, v225, v222
	v_fma_f32 v221, -v221, v224, v223
	v_div_fmas_f32 v221, v221, v222, v224
	v_div_fixup_f32 v122, v221, v220, v122
	v_div_scale_f32 v229, vcc, v123, v226, v123
	v_mul_f32_e32 v230, v229, v228
	v_fma_f32 v231, -v227, v230, v229
	v_fmac_f32_e32 v230, v231, v228
	v_fma_f32 v227, -v227, v230, v229
	v_div_fmas_f32 v227, v227, v228, v230
	v_div_fixup_f32 v123, v227, v226, v123
	v_mul_f32_e32 v62, v62, v120
	v_mul_f32_e32 v46, v46, v121
	v_mul_f32_e32 v30, v30, v122
	v_mul_f32_e32 v14, v14, v123
	v_mul_f32_e32 v162, v46, v46
	v_fmac_f32_e32 v162, v62, v62
	v_fmac_f32_e32 v162, v30, v30
	v_fmac_f32_e32 v162, v14, v14
	v_cvt_pk_bf16_f32 v120, v62, v177
	v_cvt_pk_bf16_f32 v121, v46, v177
	v_cvt_pk_bf16_f32 v122, v30, v177
	v_cvt_pk_bf16_f32 v123, v14, v177
	global_store_short v182, v120, s[14:15] offset:0
	global_store_short v182, v121, s[14:15] offset:64
	global_store_short v182, v122, s[14:15] offset:128
	global_store_short v182, v123, s[14:15] offset:192
	s_waitcnt vmcnt(60)
	v_add_u32_e32 v175, 0x1b000, v169
	v_lshlrev_b32_e32 v124, 16, v124
	v_lshlrev_b32_e32 v125, 16, v125
	v_lshlrev_b32_e32 v126, 16, v126
	v_lshlrev_b32_e32 v127, 16, v127
	v_mul_f32_e32 v208, 0xbfb8aa3b, v124
	v_mul_f32_e32 v214, 0xbfb8aa3b, v125
	v_mul_f32_e32 v220, 0xbfb8aa3b, v126
	v_mul_f32_e32 v226, 0xbfb8aa3b, v127
	v_exp_f32_e32 v208, v208
	v_exp_f32_e32 v214, v214
	v_exp_f32_e32 v220, v220
	v_exp_f32_e32 v226, v226
	v_add_f32_e32 v208, 1.0, v208
	v_add_f32_e32 v214, 1.0, v214
	v_add_f32_e32 v220, 1.0, v220
	v_add_f32_e32 v226, 1.0, v226
	v_div_scale_f32 v209, s[12:13], v208, v208, v124
	v_div_scale_f32 v215, s[12:13], v214, v214, v125
	v_div_scale_f32 v221, s[12:13], v220, v220, v126
	v_div_scale_f32 v227, s[12:13], v226, v226, v127
	v_rcp_f32_e32 v210, v209
	v_rcp_f32_e32 v216, v215
	v_rcp_f32_e32 v222, v221
	v_rcp_f32_e32 v228, v227
	v_fma_f32 v211, -v209, v210, 1.0
	v_fma_f32 v217, -v215, v216, 1.0
	v_fma_f32 v223, -v221, v222, 1.0
	v_fma_f32 v229, -v227, v228, 1.0
	v_fmac_f32_e32 v210, v211, v210
	v_fmac_f32_e32 v216, v217, v216
	v_fmac_f32_e32 v222, v223, v222
	v_fmac_f32_e32 v228, v229, v228
	v_div_scale_f32 v211, vcc, v124, v208, v124
	v_mul_f32_e32 v212, v211, v210
	v_fma_f32 v213, -v209, v212, v211
	v_fmac_f32_e32 v212, v213, v210
	v_fma_f32 v209, -v209, v212, v211
	v_div_fmas_f32 v209, v209, v210, v212
	v_div_fixup_f32 v124, v209, v208, v124
	v_div_scale_f32 v217, vcc, v125, v214, v125
	v_mul_f32_e32 v218, v217, v216
	v_fma_f32 v219, -v215, v218, v217
	v_fmac_f32_e32 v218, v219, v216
	v_fma_f32 v215, -v215, v218, v217
	v_div_fmas_f32 v215, v215, v216, v218
	v_div_fixup_f32 v125, v215, v214, v125
	v_div_scale_f32 v223, vcc, v126, v220, v126
	v_mul_f32_e32 v224, v223, v222
	v_fma_f32 v225, -v221, v224, v223
	v_fmac_f32_e32 v224, v225, v222
	v_fma_f32 v221, -v221, v224, v223
	v_div_fmas_f32 v221, v221, v222, v224
	v_div_fixup_f32 v126, v221, v220, v126
	v_div_scale_f32 v229, vcc, v127, v226, v127
	v_mul_f32_e32 v230, v229, v228
	v_fma_f32 v231, -v227, v230, v229
	v_fmac_f32_e32 v230, v231, v228
	v_fma_f32 v227, -v227, v230, v229
	v_div_fmas_f32 v227, v227, v228, v230
	v_div_fixup_f32 v127, v227, v226, v127
	v_mul_f32_e32 v63, v63, v124
	v_mul_f32_e32 v47, v47, v125
	v_mul_f32_e32 v31, v31, v126
	v_mul_f32_e32 v15, v15, v127
	v_mul_f32_e32 v163, v47, v47
	v_fmac_f32_e32 v163, v63, v63
	v_fmac_f32_e32 v163, v31, v31
	v_fmac_f32_e32 v163, v15, v15
	v_cvt_pk_bf16_f32 v124, v63, v177
	v_cvt_pk_bf16_f32 v125, v47, v177
	v_cvt_pk_bf16_f32 v126, v31, v177
	v_cvt_pk_bf16_f32 v127, v15, v177
	global_store_short v175, v124, s[14:15] offset:0
	global_store_short v175, v125, s[14:15] offset:64
	global_store_short v175, v126, s[14:15] offset:128
	global_store_short v175, v127, s[14:15] offset:192
	v_add_f32_dpp v148, v148, v148 quad_perm:[1,0,3,2] row_mask:0xf bank_mask:0xf
	v_add_f32_dpp v149, v149, v149 quad_perm:[1,0,3,2] row_mask:0xf bank_mask:0xf
	v_add_f32_dpp v150, v150, v150 quad_perm:[1,0,3,2] row_mask:0xf bank_mask:0xf
	v_add_f32_dpp v151, v151, v151 quad_perm:[1,0,3,2] row_mask:0xf bank_mask:0xf
	v_add_f32_dpp v152, v152, v152 quad_perm:[1,0,3,2] row_mask:0xf bank_mask:0xf
	v_add_f32_dpp v153, v153, v153 quad_perm:[1,0,3,2] row_mask:0xf bank_mask:0xf
	v_add_f32_dpp v154, v154, v154 quad_perm:[1,0,3,2] row_mask:0xf bank_mask:0xf
	v_add_f32_dpp v155, v155, v155 quad_perm:[1,0,3,2] row_mask:0xf bank_mask:0xf
	v_add_f32_dpp v156, v156, v156 quad_perm:[1,0,3,2] row_mask:0xf bank_mask:0xf
	v_add_f32_dpp v157, v157, v157 quad_perm:[1,0,3,2] row_mask:0xf bank_mask:0xf
	v_add_f32_dpp v158, v158, v158 quad_perm:[1,0,3,2] row_mask:0xf bank_mask:0xf
	v_add_f32_dpp v159, v159, v159 quad_perm:[1,0,3,2] row_mask:0xf bank_mask:0xf
	v_add_f32_dpp v160, v160, v160 quad_perm:[1,0,3,2] row_mask:0xf bank_mask:0xf
	v_add_f32_dpp v161, v161, v161 quad_perm:[1,0,3,2] row_mask:0xf bank_mask:0xf
	v_add_f32_dpp v162, v162, v162 quad_perm:[1,0,3,2] row_mask:0xf bank_mask:0xf
	v_add_f32_dpp v163, v163, v163 quad_perm:[1,0,3,2] row_mask:0xf bank_mask:0xf
	v_add_f32_dpp v148, v148, v148 quad_perm:[2,3,0,1] row_mask:0xf bank_mask:0xf
	v_add_f32_dpp v149, v149, v149 quad_perm:[2,3,0,1] row_mask:0xf bank_mask:0xf
	v_add_f32_dpp v150, v150, v150 quad_perm:[2,3,0,1] row_mask:0xf bank_mask:0xf
	v_add_f32_dpp v151, v151, v151 quad_perm:[2,3,0,1] row_mask:0xf bank_mask:0xf
	v_add_f32_dpp v152, v152, v152 quad_perm:[2,3,0,1] row_mask:0xf bank_mask:0xf
	v_add_f32_dpp v153, v153, v153 quad_perm:[2,3,0,1] row_mask:0xf bank_mask:0xf
	v_add_f32_dpp v154, v154, v154 quad_perm:[2,3,0,1] row_mask:0xf bank_mask:0xf
	v_add_f32_dpp v155, v155, v155 quad_perm:[2,3,0,1] row_mask:0xf bank_mask:0xf
	v_add_f32_dpp v156, v156, v156 quad_perm:[2,3,0,1] row_mask:0xf bank_mask:0xf
	v_add_f32_dpp v157, v157, v157 quad_perm:[2,3,0,1] row_mask:0xf bank_mask:0xf
	v_add_f32_dpp v158, v158, v158 quad_perm:[2,3,0,1] row_mask:0xf bank_mask:0xf
	v_add_f32_dpp v159, v159, v159 quad_perm:[2,3,0,1] row_mask:0xf bank_mask:0xf
	v_add_f32_dpp v160, v160, v160 quad_perm:[2,3,0,1] row_mask:0xf bank_mask:0xf
	v_add_f32_dpp v161, v161, v161 quad_perm:[2,3,0,1] row_mask:0xf bank_mask:0xf
	v_add_f32_dpp v162, v162, v162 quad_perm:[2,3,0,1] row_mask:0xf bank_mask:0xf
	v_add_f32_dpp v163, v163, v163 quad_perm:[2,3,0,1] row_mask:0xf bank_mask:0xf
	v_add_f32_dpp v148, v148, v148 row_half_mirror row_mask:0xf bank_mask:0xf
	v_add_f32_dpp v149, v149, v149 row_half_mirror row_mask:0xf bank_mask:0xf
	v_add_f32_dpp v150, v150, v150 row_half_mirror row_mask:0xf bank_mask:0xf
	v_add_f32_dpp v151, v151, v151 row_half_mirror row_mask:0xf bank_mask:0xf
	v_add_f32_dpp v152, v152, v152 row_half_mirror row_mask:0xf bank_mask:0xf
	v_add_f32_dpp v153, v153, v153 row_half_mirror row_mask:0xf bank_mask:0xf
	v_add_f32_dpp v154, v154, v154 row_half_mirror row_mask:0xf bank_mask:0xf
	v_add_f32_dpp v155, v155, v155 row_half_mirror row_mask:0xf bank_mask:0xf
	v_add_f32_dpp v156, v156, v156 row_half_mirror row_mask:0xf bank_mask:0xf
	v_add_f32_dpp v157, v157, v157 row_half_mirror row_mask:0xf bank_mask:0xf
	v_add_f32_dpp v158, v158, v158 row_half_mirror row_mask:0xf bank_mask:0xf
	v_add_f32_dpp v159, v159, v159 row_half_mirror row_mask:0xf bank_mask:0xf
	v_add_f32_dpp v160, v160, v160 row_half_mirror row_mask:0xf bank_mask:0xf
	v_add_f32_dpp v161, v161, v161 row_half_mirror row_mask:0xf bank_mask:0xf
	v_add_f32_dpp v162, v162, v162 row_half_mirror row_mask:0xf bank_mask:0xf
	v_add_f32_dpp v163, v163, v163 row_half_mirror row_mask:0xf bank_mask:0xf
	v_add_f32_dpp v148, v148, v148 row_mirror row_mask:0xf bank_mask:0xf
	v_add_f32_dpp v149, v149, v149 row_mirror row_mask:0xf bank_mask:0xf
	v_add_f32_dpp v150, v150, v150 row_mirror row_mask:0xf bank_mask:0xf
	v_add_f32_dpp v151, v151, v151 row_mirror row_mask:0xf bank_mask:0xf
	v_add_f32_dpp v152, v152, v152 row_mirror row_mask:0xf bank_mask:0xf
	v_add_f32_dpp v153, v153, v153 row_mirror row_mask:0xf bank_mask:0xf
	v_add_f32_dpp v154, v154, v154 row_mirror row_mask:0xf bank_mask:0xf
	v_add_f32_dpp v155, v155, v155 row_mirror row_mask:0xf bank_mask:0xf
	v_add_f32_dpp v156, v156, v156 row_mirror row_mask:0xf bank_mask:0xf
	v_add_f32_dpp v157, v157, v157 row_mirror row_mask:0xf bank_mask:0xf
	v_add_f32_dpp v158, v158, v158 row_mirror row_mask:0xf bank_mask:0xf
	v_add_f32_dpp v159, v159, v159 row_mirror row_mask:0xf bank_mask:0xf
	v_add_f32_dpp v160, v160, v160 row_mirror row_mask:0xf bank_mask:0xf
	v_add_f32_dpp v161, v161, v161 row_mirror row_mask:0xf bank_mask:0xf
	v_add_f32_dpp v162, v162, v162 row_mirror row_mask:0xf bank_mask:0xf
	v_add_f32_dpp v163, v163, v163 row_mirror row_mask:0xf bank_mask:0xf
	ds_bpermute_b32 v208, v207, v148
	ds_bpermute_b32 v209, v207, v149
	ds_bpermute_b32 v210, v207, v150
	ds_bpermute_b32 v211, v207, v151
	ds_bpermute_b32 v212, v207, v152
	ds_bpermute_b32 v213, v207, v153
	ds_bpermute_b32 v214, v207, v154
	ds_bpermute_b32 v215, v207, v155
	ds_bpermute_b32 v216, v207, v156
	ds_bpermute_b32 v217, v207, v157
	ds_bpermute_b32 v218, v207, v158
	ds_bpermute_b32 v219, v207, v159
	ds_bpermute_b32 v220, v207, v160
	ds_bpermute_b32 v221, v207, v161
	ds_bpermute_b32 v222, v207, v162
	ds_bpermute_b32 v223, v207, v163
	v_cmp_eq_u32_e64 s[40:41], 0, v196
	s_waitcnt lgkmcnt(0)
	v_add_f32_e32 v148, v148, v208
	v_add_f32_e32 v149, v149, v209
	v_add_f32_e32 v150, v150, v210
	v_add_f32_e32 v151, v151, v211
	v_add_f32_e32 v152, v152, v212
	v_add_f32_e32 v153, v153, v213
	v_add_f32_e32 v154, v154, v214
	v_add_f32_e32 v155, v155, v215
	v_add_f32_e32 v156, v156, v216
	v_add_f32_e32 v157, v157, v217
	v_add_f32_e32 v158, v158, v218
	v_add_f32_e32 v159, v159, v219
	v_add_f32_e32 v160, v160, v220
	v_add_f32_e32 v161, v161, v221
	v_add_f32_e32 v162, v162, v222
	v_add_f32_e32 v163, v163, v223
	s_and_saveexec_b64 s[44:45], s[40:41]
	v_mov_b32_e32 v171, v170
	global_store_dword v171, v148, s[42:43]
	v_add_u32_e32 v172, 0x20, v170
	global_store_dword v172, v149, s[42:43]
	v_add_u32_e32 v173, 0x40, v170
	global_store_dword v173, v150, s[42:43]
	v_add_u32_e32 v174, 0x60, v170
	global_store_dword v174, v151, s[42:43]
	v_add_u32_e32 v171, 0x100, v170
	global_store_dword v171, v152, s[42:43]
	v_add_u32_e32 v172, 0x120, v170
	global_store_dword v172, v153, s[42:43]
	v_add_u32_e32 v173, 0x140, v170
	global_store_dword v173, v154, s[42:43]
	v_add_u32_e32 v174, 0x160, v170
	global_store_dword v174, v155, s[42:43]
	v_add_u32_e32 v171, 0x200, v170
	global_store_dword v171, v156, s[42:43]
	v_add_u32_e32 v172, 0x220, v170
	global_store_dword v172, v157, s[42:43]
	v_add_u32_e32 v173, 0x240, v170
	global_store_dword v173, v158, s[42:43]
	v_add_u32_e32 v174, 0x260, v170
	global_store_dword v174, v159, s[42:43]
	v_add_u32_e32 v171, 0x300, v170
	global_store_dword v171, v160, s[42:43]
	v_add_u32_e32 v172, 0x320, v170
	global_store_dword v172, v161, s[42:43]
	v_add_u32_e32 v173, 0x340, v170
	global_store_dword v173, v162, s[42:43]
	v_add_u32_e32 v174, 0x360, v170
	global_store_dword v174, v163, s[42:43]
	s_or_b64 exec, exec, s[44:45]
	s_branch .LBB0_416
